# V^T column-block XOR swizzle + nt hints on P2 epilogue stores and on once-read epilogue/norm loads (P1,P5,P6,P9,P10,P11)
# speedup vs baseline: 1.0149x; 1.0124x over previous
; __device__ __forceinline__ void norm_phase(const float* x, const float* ng, const float* mod, bf16_t* H) {
;     ...
;     for (int m = m0; m < m1; m += 2) {
;         const int b = m / SEQ;
;         const bool two = (m + 1 < m1) && ((m + 1) / SEQ == b);
;         if (b != curb) { curb = b;
; #pragma unroll
;             for (int j = 0; j < 4; ++j) { const int col = 4 * lane + 256 * j;
;                 const f32x4 g = *(const f32x4*)(ng + col), sc = *(const f32x4*)(mod + b * 3072 + 1024 + col);
;                 ca[j] = g * (sc + 1.0f); cb[j] = *(const f32x4*)(mod + b * 3072 + col); } }
;         const f32x4* xr = (const f32x4*)(x + (size_t)m * D) + lane;
;         const f32x4* xr2 = two ? xr + D / 4 : xr;
;         f32x4 v[4], v2[4]; float ss = 0.f, ss2 = 0.f;
; #pragma unroll
;         for (int j = 0; j < 4; ++j) { v[j] = xr[64 * j]; v2[j] = xr2[64 * j]; }
; #pragma unroll
;         for (int j = 0; j < 4; ++j) { ss += (v[j][0] * v[j][0] + v[j][1] * v[j][1]) + (v[j][2] * v[j][2] + v[j][3] * v[j][3]);
;             ss2 += (v2[j][0] * v2[j][0] + v2[j][1] * v2[j][1]) + (v2[j][2] * v2[j][2] + v2[j][3] * v2[j][3]); }
;         const float rstd = 1.0f / sqrtf(wave_sum(ss) * (1.0f / D) + EPS), rstd2 = 1.0f / sqrtf(wave_sum(ss2) * (1.0f / D) + EPS);
.LBB0_179:
	v_ashrrev_i32_e32 v32, 31, v64
	v_lshrrev_b32_e32 v32, 19, v32
	v_add_u32_e32 v32, v64, v32
	v_add_u32_e32 v33, 1, v64
	v_ashrrev_i32_e32 v32, 13, v32
	v_cmp_lt_i32_e32 vcc, v33, v82
	s_mov_b64 s[14:15], 0
	s_and_saveexec_b64 s[0:1], vcc
	v_ashrrev_i32_e32 v34, 31, v33
	v_lshrrev_b32_e32 v34, 19, v34
	v_add_u32_e32 v33, v33, v34
	v_ashrrev_i32_e32 v33, 13, v33
	v_cmp_eq_u32_e32 vcc, v33, v32
	s_and_b64 s[14:15], vcc, exec
	s_or_b64 exec, exec, s[0:1]
	v_cmp_ne_u32_e32 vcc, v32, v75
	s_and_saveexec_b64 s[0:1], vcc
	s_cbranch_execz .LBB0_183
	v_mul_i32_i24_e32 v0, 0xc00, v32
	v_ashrrev_i32_e32 v1, 31, v0
	v_lshl_add_u64 v[0:1], v[0:1], 2, s[80:81]
	v_lshl_add_u64 v[2:3], v[0:1], 0, s[10:11]
	v_mov_b32_e32 v75, v67
	v_lshl_add_u64 v[4:5], v[2:3], 0, v[74:75]
	s_waitcnt lgkmcnt(0)
	v_mov_b32_e32 v77, v67
	global_load_dwordx4 v[16:19], v[4:5], off nt
	v_lshl_add_u64 v[4:5], v[2:3], 0, v[76:77]
	v_mov_b32_e32 v79, v67
	global_load_dwordx4 v[20:23], v[4:5], off nt
	v_lshl_add_u64 v[4:5], v[2:3], 0, v[78:79]
	v_mov_b32_e32 v81, v67
	global_load_dwordx4 v[24:27], v[4:5], off nt
	v_lshl_add_u64 v[2:3], v[2:3], 0, v[80:81]
	global_load_dwordx4 v[28:31], v[2:3], off nt
	global_load_dwordx4 v[34:37], v[68:69], off nt
	global_load_dwordx4 v[38:41], v[68:69], off offset:1024 nt
	v_lshl_add_u64 v[12:13], v[0:1], 0, v[74:75]
	global_load_dwordx4 v[42:45], v[68:69], off offset:2048 nt
	global_load_dwordx4 v[0:3], v[12:13], off nt
	global_load_dwordx4 v[46:49], v[68:69], off offset:3072 nt
	global_load_dwordx4 v[8:11], v[12:13], off offset:1024 nt
	global_load_dwordx4 v[4:7], v[12:13], off offset:2048 nt
	s_nop 0
	global_load_dwordx4 v[12:15], v[12:13], off offset:3072 nt
	v_mov_b32_e32 v75, v32
	s_waitcnt vmcnt(11)
	v_pk_add_f32 v[18:19], v[18:19], 1.0 op_sel_hi:[1,0]
	v_pk_add_f32 v[16:17], v[16:17], 1.0 op_sel_hi:[1,0]
	s_waitcnt vmcnt(10)
	v_pk_add_f32 v[22:23], v[22:23], 1.0 op_sel_hi:[1,0]
	v_pk_add_f32 v[20:21], v[20:21], 1.0 op_sel_hi:[1,0]
	s_waitcnt vmcnt(9)
	v_pk_add_f32 v[26:27], v[26:27], 1.0 op_sel_hi:[1,0]
	v_pk_add_f32 v[24:25], v[24:25], 1.0 op_sel_hi:[1,0]
	s_waitcnt vmcnt(8)
	v_pk_add_f32 v[30:31], v[30:31], 1.0 op_sel_hi:[1,0]
	v_pk_add_f32 v[28:29], v[28:29], 1.0 op_sel_hi:[1,0]
	s_waitcnt vmcnt(7)
	v_pk_mul_f32 v[18:19], v[36:37], v[18:19]
	v_pk_mul_f32 v[16:17], v[34:35], v[16:17]
	s_waitcnt vmcnt(6)
	v_pk_mul_f32 v[22:23], v[40:41], v[22:23]
	v_pk_mul_f32 v[20:21], v[38:39], v[20:21]
	s_waitcnt vmcnt(5)
	v_pk_mul_f32 v[26:27], v[44:45], v[26:27]
	v_pk_mul_f32 v[24:25], v[42:43], v[24:25]
	s_waitcnt vmcnt(3)
	v_pk_mul_f32 v[30:31], v[48:49], v[30:31]
	v_pk_mul_f32 v[28:29], v[46:47], v[28:29]
.LBB0_183:
	s_or_b64 exec, exec, s[0:1]
	global_load_dwordx4 v[32:35], v[72:73], off nt
	global_load_dwordx4 v[36:39], v[72:73], off offset:1024 nt
	global_load_dwordx4 v[40:43], v[72:73], off offset:3072 nt
	global_load_dwordx4 v[44:47], v[72:73], off offset:2048 nt
	v_cndmask_b32_e64 v66, 0, v90, s[14:15]
	v_lshl_add_u64 v[92:93], v[72:73], 0, v[66:67]
	global_load_dwordx4 v[48:51], v[92:93], off nt
	global_load_dwordx4 v[60:63], v[92:93], off offset:1024 nt
	global_load_dwordx4 v[56:59], v[92:93], off offset:2048 nt
	global_load_dwordx4 v[52:55], v[92:93], off offset:3072 nt
	s_waitcnt vmcnt(7)
	v_pk_mul_f32 v[92:93], v[34:35], v[34:35]
	v_pk_mul_f32 v[94:95], v[32:33], v[32:33]
	s_waitcnt vmcnt(6)
	v_pk_mul_f32 v[96:97], v[38:39], v[38:39]
	v_pk_mul_f32 v[98:99], v[36:37], v[36:37]
	v_pk_mov_b32 v[102:103], v[94:95], v[92:93] op_sel:[1,0]
	v_mov_b32_e32 v95, v93
	v_pk_mov_b32 v[92:93], v[98:99], v[96:97] op_sel:[1,0]
	v_mov_b32_e32 v99, v97
	s_waitcnt vmcnt(4)
	v_mul_f32_e32 v66, v45, v45
	v_mul_f32_e32 v100, v47, v47
	v_pk_add_f32 v[94:95], v[102:103], v[94:95]
	v_pk_add_f32 v[92:93], v[92:93], v[98:99]
	s_waitcnt lgkmcnt(0)
	v_mul_f32_e32 v77, v40, v40
	v_mul_f32_e32 v79, v41, v41
	v_mul_f32_e32 v81, v42, v42
	v_mul_f32_e32 v91, v43, v43
	v_pk_fma_f32 v[96:97], v[44:45], v[44:45], v[66:67] op_sel_hi:[1,1,0]
	v_pk_fma_f32 v[100:101], v[46:47], v[46:47], v[100:101] op_sel_hi:[1,1,0]
	v_pk_add_f32 v[94:95], v[94:95], v[94:95] op_sel:[0,1] op_sel_hi:[1,0]
	v_pk_add_f32 v[92:93], v[92:93], v[92:93] op_sel:[0,1] op_sel_hi:[1,0]
	v_mov_b32_e32 v97, v81
	v_mov_b32_e32 v101, v91
	v_mov_b32_e32 v95, v77
	v_mov_b32_e32 v93, v79
	v_pk_add_f32 v[96:97], v[96:97], v[100:101]
	v_pk_add_f32 v[92:93], v[94:95], v[92:93]
	s_waitcnt vmcnt(3)
	v_mul_f32_e32 v66, v49, v49
	v_pk_add_f32 v[92:93], v[92:93], v[96:97]
	v_mul_f32_e32 v81, v51, v51
	v_add_f32_e32 v77, v92, v93
	ds_bpermute_b32 v79, v83, v77
	s_waitcnt vmcnt(2)
	v_mul_f32_e32 v91, v61, v61
	v_mul_f32_e32 v98, v63, v63
	s_waitcnt vmcnt(1)
	v_mul_f32_e32 v99, v57, v57
	v_mul_f32_e32 v102, v59, v59
	s_waitcnt lgkmcnt(0)
	v_add_f32_e32 v77, v77, v79
	ds_bpermute_b32 v79, v84, v77
	v_fmac_f32_e32 v66, v48, v48
	v_fmac_f32_e32 v81, v50, v50
	v_fmac_f32_e32 v91, v60, v60
	v_fmac_f32_e32 v98, v62, v62
	s_waitcnt vmcnt(0)
	v_mul_f32_e32 v103, v53, v53
	v_mul_f32_e32 v104, v55, v55
	v_fmac_f32_e32 v99, v56, v56
	v_fmac_f32_e32 v102, v58, v58
	v_add_f32_e32 v66, v66, v81
	v_add_f32_e32 v81, v91, v98
	v_fmac_f32_e32 v103, v52, v52
	v_fmac_f32_e32 v104, v54, v54
	v_add_f32_e32 v91, v99, v102
	v_add_f32_e32 v66, v66, v81
	s_waitcnt lgkmcnt(0)
	v_add_f32_e32 v77, v77, v79
	v_add_f32_e32 v92, v103, v104
	v_add_f32_e32 v66, v66, v91
	ds_bpermute_b32 v79, v85, v77
	v_add_f32_e32 v66, v66, v92
	ds_bpermute_b32 v81, v83, v66
	s_waitcnt lgkmcnt(1)
	v_add_f32_e32 v77, v77, v79
	ds_bpermute_b32 v79, v86, v77
	s_waitcnt lgkmcnt(1)
; __device__ __forceinline__ unsigned cvt_pk_bf16(float lo, float hi) { unsigned r; asm volatile("v_cvt_pk_bf16_f32 %0, %1, %2" : "=v"(r) : "v"(lo), "v"(hi)); return r; }
; __device__ __forceinline__ void norm_phase(const float* x, const float* ng, const float* mod, bf16_t* H) {
;     ...
;         const float rstd = 1.0f / sqrtf(wave_sum(ss) * (1.0f / D) + EPS), rstd2 = 1.0f / sqrtf(wave_sum(ss2) * (1.0f / D) + EPS);
;         u32x2* o8 = (u32x2*)(H + (size_t)m * D) + lane;
; #pragma unroll
;         for (int j = 0; j < 4; ++j) { const f32x4 h = v[j] * rstd * ca[j] + cb[j]; u32x2 w; w.x = cvt_pk_bf16(h[0], h[1]); w.y = cvt_pk_bf16(h[2], h[3]); o8[64 * j] = w; }
;         if (two) {
;             u32x2* o82 = o8 + D / 4;
; #pragma unroll
;             for (int j = 0; j < 4; ++j) { const f32x4 h = v2[j] * rstd2 * ca[j] + cb[j]; u32x2 w; w.x = cvt_pk_bf16(h[0], h[1]); w.y = cvt_pk_bf16(h[2], h[3]); o82[64 * j] = w; }
;         }
	v_add_f32_e32 v66, v66, v81
	ds_bpermute_b32 v81, v84, v66
	s_waitcnt lgkmcnt(1)
	v_add_f32_e32 v77, v77, v79
	ds_bpermute_b32 v79, v87, v77
	s_waitcnt lgkmcnt(1)
	v_add_f32_e32 v66, v66, v81
	ds_bpermute_b32 v81, v85, v66
	s_waitcnt lgkmcnt(1)
	v_add_f32_e32 v77, v77, v79
	ds_bpermute_b32 v79, v88, v77
	s_waitcnt lgkmcnt(1)
	v_add_f32_e32 v66, v66, v81
	ds_bpermute_b32 v81, v86, v66
	s_waitcnt lgkmcnt(1)
	v_add_f32_e32 v77, v77, v79
	v_fmamk_f32 v77, v77, 0x3a800000, v65
	s_waitcnt lgkmcnt(0)
	v_add_f32_e32 v66, v66, v81
	v_mul_f32_e32 v79, 0x4f800000, v77
	v_cmp_gt_f32_e32 vcc, s3, v77
	ds_bpermute_b32 v81, v87, v66
	s_waitcnt lgkmcnt(0)
	v_add_f32_e32 v66, v66, v81
	v_cndmask_b32_e32 v77, v77, v79, vcc
	v_sqrt_f32_e32 v79, v77
	s_nop 0
	v_add_u32_e32 v81, -1, v79
	v_add_u32_e32 v91, 1, v79
	v_fma_f32 v92, -v81, v79, v77
	v_fma_f32 v93, -v91, v79, v77
	v_cmp_ge_f32_e64 s[0:1], 0, v92
	s_nop 1
	v_cndmask_b32_e64 v79, v79, v81, s[0:1]
	v_cmp_lt_f32_e64 s[0:1], 0, v93
	s_nop 1
	v_cndmask_b32_e64 v79, v79, v91, s[0:1]
	v_mul_f32_e32 v81, 0x37800000, v79
	v_cndmask_b32_e32 v79, v79, v81, vcc
	v_cmp_class_f32_e32 vcc, v77, v89
	s_nop 1
	v_cndmask_b32_e32 v79, v79, v77, vcc
	v_div_scale_f32 v81, s[0:1], v79, v79, 1.0
	v_rcp_f32_e32 v91, v81
	v_div_scale_f32 v92, vcc, 1.0, v79, 1.0
	ds_bpermute_b32 v77, v88, v66
	v_fma_f32 v93, -v81, v91, 1.0
	v_fmac_f32_e32 v91, v93, v91
	v_mul_f32_e32 v93, v92, v91
	v_fma_f32 v94, -v81, v93, v92
	v_fmac_f32_e32 v93, v94, v91
	v_fma_f32 v81, -v81, v93, v92
	v_div_fmas_f32 v81, v81, v91, v93
	v_div_fixup_f32 v92, v81, v79, 1.0
	v_pk_mul_f32 v[32:33], v[32:33], v[92:93] op_sel_hi:[1,0]
	v_pk_mul_f32 v[34:35], v[34:35], v[92:93] op_sel_hi:[1,0]
	v_pk_fma_f32 v[32:33], v[16:17], v[32:33], v[0:1]
	v_pk_mul_f32 v[36:37], v[36:37], v[92:93] op_sel_hi:[1,0]
	v_pk_mul_f32 v[38:39], v[38:39], v[92:93] op_sel_hi:[1,0]
	v_pk_fma_f32 v[34:35], v[18:19], v[34:35], v[2:3]
	v_cvt_pk_bf16_f32 v32, v32, v33
	v_pk_mul_f32 v[44:45], v[44:45], v[92:93] op_sel_hi:[1,0]
	v_cvt_pk_bf16_f32 v33, v34, v35
	v_pk_mul_f32 v[46:47], v[46:47], v[92:93] op_sel_hi:[1,0]
	v_pk_fma_f32 v[38:39], v[22:23], v[38:39], v[10:11]
	v_pk_fma_f32 v[36:37], v[20:21], v[36:37], v[8:9]
	global_store_dwordx2 v[70:71], v[32:33], off
	v_cvt_pk_bf16_f32 v32, v36, v37
	v_cvt_pk_bf16_f32 v33, v38, v39
	v_pk_mul_f32 v[40:41], v[40:41], v[92:93] op_sel_hi:[1,0]
	v_pk_mul_f32 v[42:43], v[42:43], v[92:93] op_sel_hi:[1,0]
	v_pk_fma_f32 v[46:47], v[26:27], v[46:47], v[6:7]
	v_pk_fma_f32 v[44:45], v[24:25], v[44:45], v[4:5]
	global_store_dwordx2 v[70:71], v[32:33], off offset:512
	v_cvt_pk_bf16_f32 v32, v44, v45
	v_cvt_pk_bf16_f32 v33, v46, v47
	v_pk_fma_f32 v[42:43], v[30:31], v[42:43], v[14:15]
	v_pk_fma_f32 v[40:41], v[28:29], v[40:41], v[12:13]
	global_store_dwordx2 v[70:71], v[32:33], off offset:1024
	v_cvt_pk_bf16_f32 v32, v40, v41
	v_cvt_pk_bf16_f32 v33, v42, v43
	global_store_dwordx2 v[70:71], v[32:33], off offset:1536
	s_and_saveexec_b64 s[16:17], s[14:15]
	s_cbranch_execz .LBB0_178
	s_waitcnt lgkmcnt(0)
	v_add_f32_e32 v32, v66, v77
	v_fmamk_f32 v32, v32, 0x3a800000, v65
	v_mul_f32_e32 v33, 0x4f800000, v32
	v_cmp_gt_f32_e32 vcc, s3, v32
	s_nop 1
	v_cndmask_b32_e32 v32, v32, v33, vcc
	v_sqrt_f32_e32 v33, v32
	s_nop 0
	v_add_u32_e32 v34, -1, v33
	v_fma_f32 v36, -v34, v33, v32
	v_add_u32_e32 v35, 1, v33
	v_cmp_ge_f32_e64 s[0:1], 0, v36
	s_nop 1
	v_cndmask_b32_e64 v34, v33, v34, s[0:1]
	v_fma_f32 v33, -v35, v33, v32
	v_cmp_lt_f32_e64 s[0:1], 0, v33
	s_nop 1
	v_cndmask_b32_e64 v33, v34, v35, s[0:1]
	v_mul_f32_e32 v34, 0x37800000, v33
	v_cndmask_b32_e32 v33, v33, v34, vcc
	v_cmp_class_f32_e32 vcc, v32, v89
	s_nop 1
	v_cndmask_b32_e32 v32, v33, v32, vcc
	v_div_scale_f32 v33, s[0:1], v32, v32, 1.0
	v_rcp_f32_e32 v34, v33
	s_nop 0
	v_fma_f32 v35, -v33, v34, 1.0
	v_fmac_f32_e32 v34, v35, v34
	v_div_scale_f32 v35, vcc, 1.0, v32, 1.0
	v_mul_f32_e32 v36, v35, v34
	v_fma_f32 v37, -v33, v36, v35
	v_fmac_f32_e32 v36, v37, v34
	v_fma_f32 v33, -v33, v36, v35
	v_div_fmas_f32 v33, v33, v34, v36
	v_div_fixup_f32 v32, v33, v32, 1.0
	v_pk_mul_f32 v[34:35], v[48:49], v[32:33] op_sel_hi:[1,0]
	v_pk_mul_f32 v[36:37], v[50:51], v[32:33] op_sel_hi:[1,0]
	v_pk_fma_f32 v[34:35], v[16:17], v[34:35], v[0:1]
	v_pk_fma_f32 v[36:37], v[18:19], v[36:37], v[2:3]
	v_cvt_pk_bf16_f32 v34, v34, v35
	s_nop 0
	v_cvt_pk_bf16_f32 v35, v36, v37
	global_store_dwordx2 v[70:71], v[34:35], off offset:2048
	v_pk_mul_f32 v[34:35], v[60:61], v[32:33] op_sel_hi:[1,0]
	v_pk_mul_f32 v[36:37], v[62:63], v[32:33] op_sel_hi:[1,0]
	v_pk_fma_f32 v[34:35], v[20:21], v[34:35], v[8:9]
	v_pk_fma_f32 v[36:37], v[22:23], v[36:37], v[10:11]
	v_cvt_pk_bf16_f32 v34, v34, v35
	s_nop 0
	v_cvt_pk_bf16_f32 v35, v36, v37
	global_store_dwordx2 v[70:71], v[34:35], off offset:2560
	v_pk_mul_f32 v[34:35], v[56:57], v[32:33] op_sel_hi:[1,0]
	v_pk_mul_f32 v[36:37], v[58:59], v[32:33] op_sel_hi:[1,0]
	v_pk_fma_f32 v[34:35], v[24:25], v[34:35], v[4:5]
	v_pk_fma_f32 v[36:37], v[26:27], v[36:37], v[6:7]
	v_cvt_pk_bf16_f32 v34, v34, v35
	s_nop 0
	v_cvt_pk_bf16_f32 v35, v36, v37
	global_store_dwordx2 v[70:71], v[34:35], off offset:3072
	v_pk_mul_f32 v[34:35], v[52:53], v[32:33] op_sel_hi:[1,0]
	v_pk_mul_f32 v[32:33], v[54:55], v[32:33] op_sel_hi:[1,0]
	v_pk_fma_f32 v[34:35], v[28:29], v[34:35], v[12:13]
	v_pk_fma_f32 v[32:33], v[30:31], v[32:33], v[14:15]
	v_cvt_pk_bf16_f32 v34, v34, v35
	s_nop 0
	v_cvt_pk_bf16_f32 v35, v32, v33
	global_store_dwordx2 v[70:71], v[34:35], off offset:3584
	s_branch .LBB0_178

; #define LAS __attribute__((address_space(3)))
;     __device__ __forceinline__ void operator()(f32x4 (&acc)[2][2][4][2], const Unit& u, int wr, int wc, int fr, int fq, LAS unsigned char* lds) const {
;     ...
;             asm volatile("s_waitcnt lgkmcnt(0)" ::: "memory"); __builtin_amdgcn_s_barrier(); asm volatile("" ::: "memory");
;             const float* gv = (seg == 2) ? qg : kg; const float sc = (seg == 2) ? QSCALE : 1.0f;
;             const int hc = wc * 32 + 8 * fq;
;             f32x4 g0 = *(const f32x4*)(gv + hc), g1 = *(const f32x4*)(gv + hc + 4);
;             g0 = g0 * sc; g1 = g1 * sc;
; #pragma unroll
;             for (int ai = 0; ai < 2; ++ai)
; #pragma unroll
;                 for (int m = 0; m < 4; ++m) {
;                     bf16_t* rowp = base + (size_t)(row0 + ai * HALF + m * 16) * 1024 + col0;
; #pragma unroll
;                     for (int bj = 0; bj < 2; ++bj) {
;                         const f32x4 t = *(const LAS f32x4*)(X + ((wr * 2 + bj) * 128 + ai * 64 + m * 16 + fr) * 4);
;                         const float rstd = __builtin_amdgcn_rsqf(((t[0] + t[1]) + (t[2] + t[3])) * (1.0f / 128.0f) + EPS);
;                         store8(rowp + bj * HALF, acc[ai][bj][m][0] * rstd * g0, acc[ai][bj][m][1] * rstd * g1);
;                     }
;                 }
.LBB0_300:
	s_or_b64 exec, exec, s[66:67]
	s_cmp_eq_u32 s8, 2
	s_cselect_b64 vcc, -1, 0
	s_and_b64 s[10:11], vcc, exec
	s_waitcnt lgkmcnt(0)
	s_barrier
	s_cselect_b32 s11, s27, s29
	s_cselect_b32 s10, s26, s28
	s_waitcnt lgkmcnt(0)
	v_lshlrev_b32_e32 v149, 2, v138
	global_load_dwordx4 v[150:153], v149, s[10:11]
	global_load_dwordx4 v[154:157], v149, s[10:11] offset:16
	ds_read_b128 v[158:161], v166
	v_cndmask_b32_e32 v136, 1.0, v171, vcc
	s_mov_b32 s8, 0x40000
	s_mov_b64 s[10:11], 0x40000
	s_waitcnt lgkmcnt(0)
	v_mov_b32_e32 v174, v159
	v_mov_b32_e32 v175, v160
	v_mov_b32_e32 v159, v161
	v_pk_add_f32 v[158:159], v[174:175], v[158:159]
	s_nop 0
	v_add_f32_e32 v149, v158, v159
	v_fmamk_f32 v149, v149, 0x3c000000, v167
	v_rsq_f32_e32 v158, v149
	v_ashrrev_i32_e32 v149, 31, v148
	v_pk_mul_f32 v[160:161], v[124:125], v[158:159] op_sel_hi:[1,0]
	v_pk_mul_f32 v[174:175], v[126:127], v[158:159] op_sel_hi:[1,0]
	v_pk_mul_f32 v[176:177], v[120:121], v[158:159] op_sel_hi:[1,0]
	v_pk_mul_f32 v[158:159], v[122:123], v[158:159] op_sel_hi:[1,0]
	s_waitcnt vmcnt(0)
	v_pk_mul_f32 v[124:125], v[136:137], v[152:153] op_sel_hi:[0,1]
	v_pk_mul_f32 v[120:121], v[136:137], v[156:157] op_sel_hi:[0,1]
	v_pk_mul_f32 v[122:123], v[136:137], v[154:155] op_sel_hi:[0,1]
	v_pk_mul_f32 v[126:127], v[136:137], v[150:151] op_sel_hi:[0,1]
	v_pk_mul_f32 v[158:159], v[120:121], v[158:159]
	v_pk_mul_f32 v[156:157], v[122:123], v[176:177]
	v_pk_mul_f32 v[150:151], v[124:125], v[174:175]
	v_pk_mul_f32 v[152:153], v[126:127], v[160:161]
	v_lshlrev_b32_e32 v136, 1, v172
	v_cvt_pk_bf16_f32 v154, v152, v153
	v_cvt_pk_bf16_f32 v155, v150, v151
	v_cvt_pk_bf16_f32 v156, v156, v157
	v_cvt_pk_bf16_f32 v157, v158, v159
	ds_read_b128 v[158:161], v166 offset:2048
	v_lshl_add_u64 v[152:153], s[64:65], 0, v[136:137]
	s_waitcnt lgkmcnt(0)
	v_mov_b32_e32 v150, v159
	v_mov_b32_e32 v151, v160
	v_mov_b32_e32 v159, v161
	v_pk_add_f32 v[150:151], v[150:151], v[158:159]
	s_nop 0
	v_add_f32_e32 v136, v150, v151
	v_fmamk_f32 v136, v136, 0x3c000000, v167
	v_rsq_f32_e32 v136, v136
	v_lshlrev_b64 v[150:151], 11, v[148:149]
	v_lshl_add_u64 v[150:151], v[152:153], 0, v[150:151]
	global_store_dwordx4 v[150:151], v[154:157], off nt
	v_pk_mul_f32 v[116:117], v[116:117], v[136:137] op_sel_hi:[1,0]
	v_pk_mul_f32 v[118:119], v[118:119], v[136:137] op_sel_hi:[1,0]
	v_pk_mul_f32 v[112:113], v[112:113], v[136:137] op_sel_hi:[1,0]
	v_pk_mul_f32 v[114:115], v[114:115], v[136:137] op_sel_hi:[1,0]
	v_pk_mul_f32 v[118:119], v[124:125], v[118:119]
	v_pk_mul_f32 v[116:117], v[126:127], v[116:117]
	v_pk_mul_f32 v[154:155], v[120:121], v[114:115]
	v_pk_mul_f32 v[114:115], v[122:123], v[112:113]
	v_cvt_pk_bf16_f32 v112, v116, v117
	v_cvt_pk_bf16_f32 v113, v118, v119
	s_nop 0
	v_cvt_pk_bf16_f32 v114, v114, v115
	v_cvt_pk_bf16_f32 v115, v154, v155
	ds_read_b128 v[116:119], v166 offset:256
	global_store_dwordx4 v[150:151], v[112:115], off offset:256 nt
	s_waitcnt lgkmcnt(0)
	v_mov_b32_e32 v154, v117
	v_mov_b32_e32 v155, v118
	v_mov_b32_e32 v117, v119
	v_pk_add_f32 v[116:117], v[154:155], v[116:117]
	s_nop 0
	v_add_f32_e32 v116, v116, v117
	v_fmamk_f32 v116, v116, 0x3c000000, v167
	v_rsq_f32_e32 v116, v116
	s_nop 0
	v_pk_mul_f32 v[108:109], v[108:109], v[116:117] op_sel_hi:[1,0]
	v_pk_mul_f32 v[110:111], v[110:111], v[116:117] op_sel_hi:[1,0]
	v_pk_mul_f32 v[104:105], v[104:105], v[116:117] op_sel_hi:[1,0]
	v_pk_mul_f32 v[106:107], v[106:107], v[116:117] op_sel_hi:[1,0]
	v_pk_mul_f32 v[110:111], v[124:125], v[110:111]
	v_pk_mul_f32 v[108:109], v[126:127], v[108:109]
	v_pk_mul_f32 v[112:113], v[120:121], v[106:107]
	v_pk_mul_f32 v[106:107], v[122:123], v[104:105]
	v_cvt_pk_bf16_f32 v104, v108, v109
	v_cvt_pk_bf16_f32 v105, v110, v111
	s_nop 0
	v_cvt_pk_bf16_f32 v106, v106, v107
	v_cvt_pk_bf16_f32 v107, v112, v113
	ds_read_b128 v[108:111], v166 offset:2304
	v_or_b32_e32 v112, 16, v148
	v_ashrrev_i32_e32 v113, 31, v112
	s_waitcnt lgkmcnt(0)
	v_mov_b32_e32 v114, v109
	v_mov_b32_e32 v115, v110
	v_mov_b32_e32 v109, v111
	v_pk_add_f32 v[108:109], v[114:115], v[108:109]
	v_lshlrev_b64 v[110:111], 11, v[112:113]
	v_add_f32_e32 v108, v108, v109
	v_fmamk_f32 v108, v108, 0x3c000000, v167
	v_rsq_f32_e32 v108, v108
	v_lshl_add_u64 v[110:111], v[152:153], 0, v[110:111]
	global_store_dwordx4 v[110:111], v[104:107], off nt
	v_pk_mul_f32 v[100:101], v[100:101], v[108:109] op_sel_hi:[1,0]
	v_pk_mul_f32 v[102:103], v[102:103], v[108:109] op_sel_hi:[1,0]
	v_pk_mul_f32 v[96:97], v[96:97], v[108:109] op_sel_hi:[1,0]
	v_pk_mul_f32 v[98:99], v[98:99], v[108:109] op_sel_hi:[1,0]
	v_pk_mul_f32 v[102:103], v[124:125], v[102:103]
	v_pk_mul_f32 v[100:101], v[126:127], v[100:101]
	v_pk_mul_f32 v[104:105], v[120:121], v[98:99]
	v_pk_mul_f32 v[98:99], v[122:123], v[96:97]
	v_cvt_pk_bf16_f32 v96, v100, v101
	v_cvt_pk_bf16_f32 v97, v102, v103
	s_nop 0
	v_cvt_pk_bf16_f32 v98, v98, v99
	v_cvt_pk_bf16_f32 v99, v104, v105
	ds_read_b128 v[100:103], v166 offset:512
	global_store_dwordx4 v[110:111], v[96:99], off offset:256 nt
	s_waitcnt lgkmcnt(0)
	v_mov_b32_e32 v104, v101
	v_mov_b32_e32 v105, v102
	v_mov_b32_e32 v101, v103
	v_pk_add_f32 v[100:101], v[104:105], v[100:101]
	s_nop 0
	v_add_f32_e32 v100, v100, v101
	v_fmamk_f32 v100, v100, 0x3c000000, v167
	v_rsq_f32_e32 v100, v100
	s_nop 0
	v_pk_mul_f32 v[92:93], v[92:93], v[100:101] op_sel_hi:[1,0]
	v_pk_mul_f32 v[94:95], v[94:95], v[100:101] op_sel_hi:[1,0]
	v_pk_mul_f32 v[88:89], v[88:89], v[100:101] op_sel_hi:[1,0]
	v_pk_mul_f32 v[90:91], v[90:91], v[100:101] op_sel_hi:[1,0]
	v_pk_mul_f32 v[94:95], v[124:125], v[94:95]
	v_pk_mul_f32 v[92:93], v[126:127], v[92:93]
	v_pk_mul_f32 v[96:97], v[120:121], v[90:91]
	v_pk_mul_f32 v[90:91], v[122:123], v[88:89]
	v_cvt_pk_bf16_f32 v88, v92, v93
	v_cvt_pk_bf16_f32 v89, v94, v95
	s_nop 0
	v_cvt_pk_bf16_f32 v90, v90, v91
	v_cvt_pk_bf16_f32 v91, v96, v97
	ds_read_b128 v[92:95], v166 offset:2560
	v_or_b32_e32 v96, 32, v148
	v_ashrrev_i32_e32 v97, 31, v96
	s_waitcnt lgkmcnt(0)
; #define LAS __attribute__((address_space(3)))
;     __device__ __forceinline__ void operator()(f32x4 (&acc)[2][2][4][2], const Unit& u, int wr, int wc, int fr, int fq, LAS unsigned char* lds) const {
;     ...
;             for (int ai = 0; ai < 2; ++ai)
; #pragma unroll
;                 for (int m = 0; m < 4; ++m) {
;                     bf16_t* rowp = base + (size_t)(row0 + ai * HALF + m * 16) * 1024 + col0;
; #pragma unroll
;                     for (int bj = 0; bj < 2; ++bj) {
;                         const f32x4 t = *(const LAS f32x4*)(X + ((wr * 2 + bj) * 128 + ai * 64 + m * 16 + fr) * 4);
;                         const float rstd = __builtin_amdgcn_rsqf(((t[0] + t[1]) + (t[2] + t[3])) * (1.0f / 128.0f) + EPS);
;                         store8(rowp + bj * HALF, acc[ai][bj][m][0] * rstd * g0, acc[ai][bj][m][1] * rstd * g1);
;                     }
;                 }
	v_mov_b32_e32 v98, v93
	v_mov_b32_e32 v99, v94
	v_mov_b32_e32 v93, v95
	v_pk_add_f32 v[92:93], v[98:99], v[92:93]
	v_lshlrev_b64 v[94:95], 11, v[96:97]
	v_add_f32_e32 v92, v92, v93
	v_fmamk_f32 v92, v92, 0x3c000000, v167
	v_rsq_f32_e32 v92, v92
	v_lshl_add_u64 v[94:95], v[152:153], 0, v[94:95]
	global_store_dwordx4 v[94:95], v[88:91], off nt
	v_pk_mul_f32 v[84:85], v[84:85], v[92:93] op_sel_hi:[1,0]
	v_pk_mul_f32 v[86:87], v[86:87], v[92:93] op_sel_hi:[1,0]
	v_pk_mul_f32 v[80:81], v[80:81], v[92:93] op_sel_hi:[1,0]
	v_pk_mul_f32 v[82:83], v[82:83], v[92:93] op_sel_hi:[1,0]
	v_pk_mul_f32 v[86:87], v[124:125], v[86:87]
	v_pk_mul_f32 v[84:85], v[126:127], v[84:85]
	v_pk_mul_f32 v[88:89], v[120:121], v[82:83]
	v_pk_mul_f32 v[82:83], v[122:123], v[80:81]
	v_cvt_pk_bf16_f32 v80, v84, v85
	v_cvt_pk_bf16_f32 v81, v86, v87
	s_nop 0
	v_cvt_pk_bf16_f32 v82, v82, v83
	v_cvt_pk_bf16_f32 v83, v88, v89
	ds_read_b128 v[84:87], v166 offset:768
	global_store_dwordx4 v[94:95], v[80:83], off offset:256 nt
	s_waitcnt lgkmcnt(0)
	v_mov_b32_e32 v88, v85
	v_mov_b32_e32 v89, v86
	v_mov_b32_e32 v85, v87
	v_pk_add_f32 v[84:85], v[88:89], v[84:85]
	s_nop 0
	v_add_f32_e32 v84, v84, v85
	v_fmamk_f32 v84, v84, 0x3c000000, v167
	v_rsq_f32_e32 v84, v84
	s_nop 0
	v_pk_mul_f32 v[76:77], v[76:77], v[84:85] op_sel_hi:[1,0]
	v_pk_mul_f32 v[78:79], v[78:79], v[84:85] op_sel_hi:[1,0]
	v_pk_mul_f32 v[72:73], v[72:73], v[84:85] op_sel_hi:[1,0]
	v_pk_mul_f32 v[74:75], v[74:75], v[84:85] op_sel_hi:[1,0]
	v_pk_mul_f32 v[78:79], v[124:125], v[78:79]
	v_pk_mul_f32 v[76:77], v[126:127], v[76:77]
	v_pk_mul_f32 v[80:81], v[120:121], v[74:75]
	v_pk_mul_f32 v[74:75], v[122:123], v[72:73]
	v_cvt_pk_bf16_f32 v72, v76, v77
	v_cvt_pk_bf16_f32 v73, v78, v79
	s_nop 0
	v_cvt_pk_bf16_f32 v74, v74, v75
	v_cvt_pk_bf16_f32 v75, v80, v81
	ds_read_b128 v[76:79], v166 offset:2816
	v_or_b32_e32 v80, 48, v148
	v_ashrrev_i32_e32 v81, 31, v80
	s_waitcnt lgkmcnt(0)
	v_mov_b32_e32 v82, v77
	v_mov_b32_e32 v83, v78
	v_mov_b32_e32 v77, v79
	v_pk_add_f32 v[76:77], v[82:83], v[76:77]
	v_lshlrev_b64 v[78:79], 11, v[80:81]
	v_add_f32_e32 v76, v76, v77
	v_fmamk_f32 v76, v76, 0x3c000000, v167
	v_rsq_f32_e32 v76, v76
	v_lshl_add_u64 v[78:79], v[152:153], 0, v[78:79]
	global_store_dwordx4 v[78:79], v[72:75], off nt
	v_pk_mul_f32 v[68:69], v[68:69], v[76:77] op_sel_hi:[1,0]
	v_pk_mul_f32 v[70:71], v[70:71], v[76:77] op_sel_hi:[1,0]
	v_pk_mul_f32 v[64:65], v[64:65], v[76:77] op_sel_hi:[1,0]
	v_pk_mul_f32 v[66:67], v[66:67], v[76:77] op_sel_hi:[1,0]
	v_pk_mul_f32 v[70:71], v[124:125], v[70:71]
	v_pk_mul_f32 v[68:69], v[126:127], v[68:69]
	v_pk_mul_f32 v[72:73], v[120:121], v[66:67]
	v_pk_mul_f32 v[66:67], v[122:123], v[64:65]
	v_cvt_pk_bf16_f32 v64, v68, v69
	v_cvt_pk_bf16_f32 v65, v70, v71
	s_nop 0
	v_cvt_pk_bf16_f32 v66, v66, v67
	v_cvt_pk_bf16_f32 v67, v72, v73
	ds_read_b128 v[68:71], v166 offset:1024
	global_store_dwordx4 v[78:79], v[64:67], off offset:256 nt
	s_waitcnt lgkmcnt(0)
	v_mov_b32_e32 v72, v69
	v_mov_b32_e32 v73, v70
	v_mov_b32_e32 v69, v71
	v_pk_add_f32 v[68:69], v[72:73], v[68:69]
	s_nop 0
	v_add_f32_e32 v68, v68, v69
	v_fmamk_f32 v68, v68, 0x3c000000, v167
	v_rsq_f32_e32 v68, v68
	s_nop 0
	v_pk_mul_f32 v[60:61], v[60:61], v[68:69] op_sel_hi:[1,0]
	v_pk_mul_f32 v[62:63], v[62:63], v[68:69] op_sel_hi:[1,0]
	v_pk_mul_f32 v[56:57], v[56:57], v[68:69] op_sel_hi:[1,0]
	v_pk_mul_f32 v[58:59], v[58:59], v[68:69] op_sel_hi:[1,0]
	v_pk_mul_f32 v[62:63], v[124:125], v[62:63]
	v_pk_mul_f32 v[60:61], v[126:127], v[60:61]
	v_pk_mul_f32 v[64:65], v[120:121], v[58:59]
	v_pk_mul_f32 v[58:59], v[122:123], v[56:57]
	v_cvt_pk_bf16_f32 v56, v60, v61
	v_cvt_pk_bf16_f32 v57, v62, v63
	s_nop 0
	v_cvt_pk_bf16_f32 v58, v58, v59
	v_cvt_pk_bf16_f32 v59, v64, v65
	ds_read_b128 v[60:63], v166 offset:3072
	s_waitcnt lgkmcnt(0)
	v_mov_b32_e32 v64, v61
	v_mov_b32_e32 v65, v62
	v_mov_b32_e32 v61, v63
	v_pk_add_f32 v[60:61], v[64:65], v[60:61]
	v_add_co_u32_e32 v62, vcc, s8, v150
	v_add_f32_e32 v60, v60, v61
	v_fmamk_f32 v60, v60, 0x3c000000, v167
	v_rsq_f32_e32 v60, v60
	v_addc_co_u32_e32 v63, vcc, 0, v151, vcc
	global_store_dwordx4 v[62:63], v[56:59], off nt
	v_pk_mul_f32 v[52:53], v[52:53], v[60:61] op_sel_hi:[1,0]
	v_pk_mul_f32 v[54:55], v[54:55], v[60:61] op_sel_hi:[1,0]
	v_pk_mul_f32 v[48:49], v[48:49], v[60:61] op_sel_hi:[1,0]
	v_pk_mul_f32 v[50:51], v[50:51], v[60:61] op_sel_hi:[1,0]
	v_pk_mul_f32 v[54:55], v[124:125], v[54:55]
	v_pk_mul_f32 v[52:53], v[126:127], v[52:53]
	v_pk_mul_f32 v[56:57], v[120:121], v[50:51]
	v_pk_mul_f32 v[50:51], v[122:123], v[48:49]
	v_cvt_pk_bf16_f32 v48, v52, v53
	v_cvt_pk_bf16_f32 v49, v54, v55
	s_mov_b32 s8, 0x48000
	v_cvt_pk_bf16_f32 v50, v50, v51
	v_cvt_pk_bf16_f32 v51, v56, v57
	ds_read_b128 v[52:55], v166 offset:1280
	s_waitcnt lgkmcnt(0)
	v_mov_b32_e32 v56, v53
	v_mov_b32_e32 v57, v54
	v_mov_b32_e32 v53, v55
	v_pk_add_f32 v[52:53], v[56:57], v[52:53]
	v_lshl_add_u64 v[54:55], v[150:151], 0, s[10:11]
	v_add_f32_e32 v52, v52, v53
	v_fmamk_f32 v52, v52, 0x3c000000, v167
	v_rsq_f32_e32 v52, v52
	global_store_dwordx4 v[54:55], v[48:51], off offset:256 nt
	v_pk_mul_f32 v[44:45], v[44:45], v[52:53] op_sel_hi:[1,0]
	v_pk_mul_f32 v[46:47], v[46:47], v[52:53] op_sel_hi:[1,0]
	v_pk_mul_f32 v[40:41], v[40:41], v[52:53] op_sel_hi:[1,0]
	v_pk_mul_f32 v[42:43], v[42:43], v[52:53] op_sel_hi:[1,0]
	v_pk_mul_f32 v[46:47], v[124:125], v[46:47]
	v_pk_mul_f32 v[44:45], v[126:127], v[44:45]
	v_pk_mul_f32 v[48:49], v[120:121], v[42:43]
	v_pk_mul_f32 v[42:43], v[122:123], v[40:41]
	v_cvt_pk_bf16_f32 v40, v44, v45
	v_cvt_pk_bf16_f32 v41, v46, v47
	s_nop 0
	v_cvt_pk_bf16_f32 v42, v42, v43
	v_cvt_pk_bf16_f32 v43, v48, v49
	ds_read_b128 v[44:47], v166 offset:3328
	s_waitcnt lgkmcnt(0)
; #define LAS __attribute__((address_space(3)))
;     __device__ __forceinline__ void operator()(f32x4 (&acc)[2][2][4][2], const Unit& u, int wr, int wc, int fr, int fq, LAS unsigned char* lds) const {
;     ...
;             for (int ai = 0; ai < 2; ++ai)
; #pragma unroll
;                 for (int m = 0; m < 4; ++m) {
;                     bf16_t* rowp = base + (size_t)(row0 + ai * HALF + m * 16) * 1024 + col0;
; #pragma unroll
;                     for (int bj = 0; bj < 2; ++bj) {
;                         const f32x4 t = *(const LAS f32x4*)(X + ((wr * 2 + bj) * 128 + ai * 64 + m * 16 + fr) * 4);
;                         const float rstd = __builtin_amdgcn_rsqf(((t[0] + t[1]) + (t[2] + t[3])) * (1.0f / 128.0f) + EPS);
;                         store8(rowp + bj * HALF, acc[ai][bj][m][0] * rstd * g0, acc[ai][bj][m][1] * rstd * g1);
;                     }
;                 }
	v_mov_b32_e32 v48, v45
	v_mov_b32_e32 v49, v46
	v_mov_b32_e32 v45, v47
	v_pk_add_f32 v[44:45], v[48:49], v[44:45]
	v_add_co_u32_e32 v46, vcc, s8, v150
	v_add_f32_e32 v44, v44, v45
	v_fmamk_f32 v44, v44, 0x3c000000, v167
	v_rsq_f32_e32 v44, v44
	v_addc_co_u32_e32 v47, vcc, 0, v151, vcc
	global_store_dwordx4 v[46:47], v[40:43], off nt
	v_pk_mul_f32 v[36:37], v[36:37], v[44:45] op_sel_hi:[1,0]
	v_pk_mul_f32 v[38:39], v[38:39], v[44:45] op_sel_hi:[1,0]
	v_pk_mul_f32 v[32:33], v[32:33], v[44:45] op_sel_hi:[1,0]
	v_pk_mul_f32 v[34:35], v[34:35], v[44:45] op_sel_hi:[1,0]
	v_pk_mul_f32 v[38:39], v[124:125], v[38:39]
	v_pk_mul_f32 v[36:37], v[126:127], v[36:37]
	v_pk_mul_f32 v[40:41], v[120:121], v[34:35]
	v_pk_mul_f32 v[34:35], v[122:123], v[32:33]
	v_cvt_pk_bf16_f32 v32, v36, v37
	v_cvt_pk_bf16_f32 v33, v38, v39
	s_mov_b32 s8, 0x50000
	v_cvt_pk_bf16_f32 v34, v34, v35
	v_cvt_pk_bf16_f32 v35, v40, v41
	ds_read_b128 v[36:39], v166 offset:1536
	s_waitcnt lgkmcnt(0)
	v_mov_b32_e32 v40, v37
	v_mov_b32_e32 v41, v38
	v_mov_b32_e32 v37, v39
	v_pk_add_f32 v[36:37], v[40:41], v[36:37]
	v_lshl_add_u64 v[38:39], v[150:151], 0, s[54:55]
	v_add_f32_e32 v36, v36, v37
	v_fmamk_f32 v36, v36, 0x3c000000, v167
	v_rsq_f32_e32 v36, v36
	global_store_dwordx4 v[38:39], v[32:35], off offset:256 nt
	v_pk_mul_f32 v[28:29], v[28:29], v[36:37] op_sel_hi:[1,0]
	v_pk_mul_f32 v[30:31], v[30:31], v[36:37] op_sel_hi:[1,0]
	v_pk_mul_f32 v[24:25], v[24:25], v[36:37] op_sel_hi:[1,0]
	v_pk_mul_f32 v[26:27], v[26:27], v[36:37] op_sel_hi:[1,0]
	v_pk_mul_f32 v[30:31], v[124:125], v[30:31]
	v_pk_mul_f32 v[28:29], v[126:127], v[28:29]
	v_pk_mul_f32 v[32:33], v[120:121], v[26:27]
	v_pk_mul_f32 v[26:27], v[122:123], v[24:25]
	v_cvt_pk_bf16_f32 v24, v28, v29
	v_cvt_pk_bf16_f32 v25, v30, v31
	s_nop 0
	v_cvt_pk_bf16_f32 v26, v26, v27
	v_cvt_pk_bf16_f32 v27, v32, v33
	ds_read_b128 v[28:31], v166 offset:3584
	s_waitcnt lgkmcnt(0)
	v_mov_b32_e32 v32, v29
	v_mov_b32_e32 v33, v30
	v_mov_b32_e32 v29, v31
	v_pk_add_f32 v[28:29], v[32:33], v[28:29]
	v_add_co_u32_e32 v30, vcc, s8, v150
	v_add_f32_e32 v28, v28, v29
	v_fmamk_f32 v28, v28, 0x3c000000, v167
	v_rsq_f32_e32 v28, v28
	v_addc_co_u32_e32 v31, vcc, 0, v151, vcc
	global_store_dwordx4 v[30:31], v[24:27], off nt
	v_pk_mul_f32 v[20:21], v[20:21], v[28:29] op_sel_hi:[1,0]
	v_pk_mul_f32 v[22:23], v[22:23], v[28:29] op_sel_hi:[1,0]
	v_pk_mul_f32 v[16:17], v[16:17], v[28:29] op_sel_hi:[1,0]
	v_pk_mul_f32 v[18:19], v[18:19], v[28:29] op_sel_hi:[1,0]
	v_pk_mul_f32 v[22:23], v[124:125], v[22:23]
	v_pk_mul_f32 v[20:21], v[126:127], v[20:21]
	v_pk_mul_f32 v[24:25], v[120:121], v[18:19]
	v_pk_mul_f32 v[18:19], v[122:123], v[16:17]
	v_cvt_pk_bf16_f32 v16, v20, v21
	v_cvt_pk_bf16_f32 v17, v22, v23
	s_mov_b32 s8, 0x58000
	v_cvt_pk_bf16_f32 v18, v18, v19
	v_cvt_pk_bf16_f32 v19, v24, v25
	ds_read_b128 v[20:23], v166 offset:1792
	s_waitcnt lgkmcnt(0)
	v_mov_b32_e32 v24, v21
	v_mov_b32_e32 v25, v22
	v_mov_b32_e32 v21, v23
	v_pk_add_f32 v[20:21], v[24:25], v[20:21]
	v_lshl_add_u64 v[22:23], v[150:151], 0, s[56:57]
	v_add_f32_e32 v20, v20, v21
	v_fmamk_f32 v20, v20, 0x3c000000, v167
	v_rsq_f32_e32 v20, v20
	global_store_dwordx4 v[22:23], v[16:19], off offset:256 nt
	v_pk_mul_f32 v[12:13], v[12:13], v[20:21] op_sel_hi:[1,0]
	v_pk_mul_f32 v[14:15], v[14:15], v[20:21] op_sel_hi:[1,0]
	v_pk_mul_f32 v[8:9], v[8:9], v[20:21] op_sel_hi:[1,0]
	v_pk_mul_f32 v[10:11], v[10:11], v[20:21] op_sel_hi:[1,0]
	v_pk_mul_f32 v[14:15], v[124:125], v[14:15]
	v_pk_mul_f32 v[12:13], v[126:127], v[12:13]
	v_pk_mul_f32 v[16:17], v[120:121], v[10:11]
	v_pk_mul_f32 v[10:11], v[122:123], v[8:9]
	v_cvt_pk_bf16_f32 v8, v12, v13
	v_cvt_pk_bf16_f32 v9, v14, v15
	s_nop 0
	v_cvt_pk_bf16_f32 v10, v10, v11
	v_cvt_pk_bf16_f32 v11, v16, v17
	ds_read_b128 v[12:15], v166 offset:3840
	v_lshl_add_u64 v[16:17], v[150:151], 0, s[58:59]
	s_waitcnt lgkmcnt(0)
	v_mov_b32_e32 v18, v13
	v_mov_b32_e32 v19, v14
	v_mov_b32_e32 v13, v15
	v_pk_add_f32 v[12:13], v[18:19], v[12:13]
	v_add_co_u32_e32 v14, vcc, s8, v150
	v_add_f32_e32 v12, v12, v13
	v_fmamk_f32 v12, v12, 0x3c000000, v167
	v_rsq_f32_e32 v12, v12
	v_addc_co_u32_e32 v15, vcc, 0, v151, vcc
	global_store_dwordx4 v[14:15], v[8:11], off nt
	v_pk_mul_f32 v[0:1], v[0:1], v[12:13] op_sel_hi:[1,0]
	v_pk_mul_f32 v[2:3], v[2:3], v[12:13] op_sel_hi:[1,0]
	v_pk_mul_f32 v[4:5], v[4:5], v[12:13] op_sel_hi:[1,0]
	v_pk_mul_f32 v[6:7], v[6:7], v[12:13] op_sel_hi:[1,0]
	v_pk_mul_f32 v[8:9], v[120:121], v[2:3]
	v_pk_mul_f32 v[2:3], v[122:123], v[0:1]
	v_pk_mul_f32 v[6:7], v[124:125], v[6:7]
	v_pk_mul_f32 v[4:5], v[126:127], v[4:5]
	s_nop 0
	v_cvt_pk_bf16_f32 v0, v4, v5
	v_cvt_pk_bf16_f32 v1, v6, v7
	v_cvt_pk_bf16_f32 v2, v2, v3
	v_cvt_pk_bf16_f32 v3, v8, v9
	global_store_dwordx4 v[16:17], v[0:3], off offset:256 nt
	s_andn2_b64 vcc, exec, s[4:5]
	s_mov_b64 s[4:5], -1
	s_cbranch_vccnz .LBB0_244
	s_branch .LBB0_397

; __device__ __forceinline__ float siluf_(float x) { return x * sigmoidf_(x); }
;     __device__ __forceinline__ void operator()(f32x4 (&acc)[2][2][4][2], const Unit& u, int wr, int wc, int fr, int fq, LAS unsigned char* lds) const {
;     ...
;             const bool act = (seg == 1 || seg == 4);
; #pragma unroll
;             for (int ai = 0; ai < 2; ++ai)
; #pragma unroll
;                 for (int m = 0; m < 4; ++m) {
;                     bf16_t* rowp = base + (size_t)(row0 + ai * HALF + m * 16) * 1024 + col0;
; #pragma unroll
;                     for (int bj = 0; bj < 2; ++bj) {
;                         f32x4 v0 = acc[ai][bj][m][0], v1 = acc[ai][bj][m][1];
;                         if (act) {
; #pragma unroll
;                             for (int j = 0; j < 4; ++j) { v0[j] = siluf_(v0[j]); v1[j] = siluf_(v1[j]); }
;                         }
;                         store8(rowp + bj * HALF, v0, v1);
;                     }
.LBB0_305:
	v_lshlrev_b32_e32 v136, 1, v172
	v_ashrrev_i32_e32 v149, 31, v148
	v_lshl_add_u64 v[150:151], s[64:65], 0, v[136:137]
	v_lshlrev_b64 v[152:153], 11, v[148:149]
	v_lshl_add_u64 v[152:153], v[150:151], 0, v[152:153]
	s_cmp_lt_i32 s8, 4
	v_cvt_pk_bf16_f32 v174, v160, v161
	v_cvt_pk_bf16_f32 v175, v156, v157
	v_cvt_pk_bf16_f32 v176, v158, v159
	v_cvt_pk_bf16_f32 v177, v154, v155
	global_store_dwordx4 v[152:153], v[174:177], off nt
	s_cbranch_scc1 .LBB0_307
	s_cmp_eq_u32 s8, 4
	s_cselect_b64 s[66:67], -1, 0
	s_cbranch_execz .LBB0_308
	s_branch .LBB0_309

; __device__ __forceinline__ float siluf_(float x) { return x * sigmoidf_(x); }
;     __device__ __forceinline__ void operator()(f32x4 (&acc)[2][2][4][2], const Unit& u, int wr, int wc, int fr, int fq, LAS unsigned char* lds) const {
;     ...
;             const bool act = (seg == 1 || seg == 4);
; #pragma unroll
;             for (int ai = 0; ai < 2; ++ai)
; #pragma unroll
;                 for (int m = 0; m < 4; ++m) {
;                     bf16_t* rowp = base + (size_t)(row0 + ai * HALF + m * 16) * 1024 + col0;
; #pragma unroll
;                     for (int bj = 0; bj < 2; ++bj) {
;                         f32x4 v0 = acc[ai][bj][m][0], v1 = acc[ai][bj][m][1];
;                         if (act) {
; #pragma unroll
;                             for (int j = 0; j < 4; ++j) { v0[j] = siluf_(v0[j]); v1[j] = siluf_(v1[j]); }
;                         }
;                         store8(rowp + bj * HALF, v0, v1);
;                     }
.LBB0_311:
	s_cmp_lt_i32 s8, 4
	v_cvt_pk_bf16_f32 v174, v160, v161
	v_cvt_pk_bf16_f32 v175, v156, v157
	v_cvt_pk_bf16_f32 v176, v158, v159
	v_cvt_pk_bf16_f32 v177, v154, v155
	global_store_dwordx4 v[152:153], v[174:177], off offset:256 nt
	s_cbranch_scc1 .LBB0_313
	s_cmp_eq_u32 s8, 4
	s_cselect_b64 s[66:67], -1, 0
	s_cbranch_execz .LBB0_314
	s_branch .LBB0_315

; __device__ __forceinline__ float siluf_(float x) { return x * sigmoidf_(x); }
;     __device__ __forceinline__ void operator()(f32x4 (&acc)[2][2][4][2], const Unit& u, int wr, int wc, int fr, int fq, LAS unsigned char* lds) const {
;     ...
;             const bool act = (seg == 1 || seg == 4);
; #pragma unroll
;             for (int ai = 0; ai < 2; ++ai)
; #pragma unroll
;                 for (int m = 0; m < 4; ++m) {
;                     bf16_t* rowp = base + (size_t)(row0 + ai * HALF + m * 16) * 1024 + col0;
; #pragma unroll
;                     for (int bj = 0; bj < 2; ++bj) {
;                         f32x4 v0 = acc[ai][bj][m][0], v1 = acc[ai][bj][m][1];
;                         if (act) {
; #pragma unroll
;                             for (int j = 0; j < 4; ++j) { v0[j] = siluf_(v0[j]); v1[j] = siluf_(v1[j]); }
;                         }
;                         store8(rowp + bj * HALF, v0, v1);
;                     }
.LBB0_317:
	v_or_b32_e32 v152, 16, v148
	v_ashrrev_i32_e32 v153, 31, v152
	v_lshlrev_b64 v[152:153], 11, v[152:153]
	v_lshl_add_u64 v[152:153], v[150:151], 0, v[152:153]
	s_cmp_lt_i32 s8, 4
	v_cvt_pk_bf16_f32 v174, v160, v161
	v_cvt_pk_bf16_f32 v175, v156, v157
	v_cvt_pk_bf16_f32 v176, v158, v159
	v_cvt_pk_bf16_f32 v177, v154, v155
	global_store_dwordx4 v[152:153], v[174:177], off nt
	s_cbranch_scc1 .LBB0_319
	s_cmp_eq_u32 s8, 4
	s_cselect_b64 s[66:67], -1, 0
	s_cbranch_execz .LBB0_320
	s_branch .LBB0_321

; __device__ __forceinline__ float siluf_(float x) { return x * sigmoidf_(x); }
;     __device__ __forceinline__ void operator()(f32x4 (&acc)[2][2][4][2], const Unit& u, int wr, int wc, int fr, int fq, LAS unsigned char* lds) const {
;     ...
;             const bool act = (seg == 1 || seg == 4);
; #pragma unroll
;             for (int ai = 0; ai < 2; ++ai)
; #pragma unroll
;                 for (int m = 0; m < 4; ++m) {
;                     bf16_t* rowp = base + (size_t)(row0 + ai * HALF + m * 16) * 1024 + col0;
; #pragma unroll
;                     for (int bj = 0; bj < 2; ++bj) {
;                         f32x4 v0 = acc[ai][bj][m][0], v1 = acc[ai][bj][m][1];
;                         if (act) {
; #pragma unroll
;                             for (int j = 0; j < 4; ++j) { v0[j] = siluf_(v0[j]); v1[j] = siluf_(v1[j]); }
;                         }
;                         store8(rowp + bj * HALF, v0, v1);
;                     }
.LBB0_329:
	v_or_b32_e32 v152, 32, v148
	v_ashrrev_i32_e32 v153, 31, v152
	v_lshlrev_b64 v[152:153], 11, v[152:153]
	v_lshl_add_u64 v[152:153], v[150:151], 0, v[152:153]
	s_cmp_lt_i32 s8, 4
	v_cvt_pk_bf16_f32 v174, v160, v161
	v_cvt_pk_bf16_f32 v175, v156, v157
	v_cvt_pk_bf16_f32 v176, v158, v159
	v_cvt_pk_bf16_f32 v177, v154, v155
	global_store_dwordx4 v[152:153], v[174:177], off nt
	s_cbranch_scc1 .LBB0_331
	s_cmp_eq_u32 s8, 4
	s_cselect_b64 s[66:67], -1, 0
	s_cbranch_execz .LBB0_332
	s_branch .LBB0_333

; __device__ __forceinline__ float siluf_(float x) { return x * sigmoidf_(x); }
;     __device__ __forceinline__ void operator()(f32x4 (&acc)[2][2][4][2], const Unit& u, int wr, int wc, int fr, int fq, LAS unsigned char* lds) const {
;     ...
;             const bool act = (seg == 1 || seg == 4);
; #pragma unroll
;             for (int ai = 0; ai < 2; ++ai)
; #pragma unroll
;                 for (int m = 0; m < 4; ++m) {
;                     bf16_t* rowp = base + (size_t)(row0 + ai * HALF + m * 16) * 1024 + col0;
; #pragma unroll
;                     for (int bj = 0; bj < 2; ++bj) {
;                         f32x4 v0 = acc[ai][bj][m][0], v1 = acc[ai][bj][m][1];
;                         if (act) {
; #pragma unroll
;                             for (int j = 0; j < 4; ++j) { v0[j] = siluf_(v0[j]); v1[j] = siluf_(v1[j]); }
;                         }
;                         store8(rowp + bj * HALF, v0, v1);
;                     }
.LBB0_341:
	v_or_b32_e32 v152, 48, v148
	v_ashrrev_i32_e32 v153, 31, v152
	v_lshlrev_b64 v[152:153], 11, v[152:153]
	v_lshl_add_u64 v[152:153], v[150:151], 0, v[152:153]
	s_cmp_lt_i32 s8, 4
	v_cvt_pk_bf16_f32 v174, v160, v161
	v_cvt_pk_bf16_f32 v175, v156, v157
	v_cvt_pk_bf16_f32 v176, v158, v159
	v_cvt_pk_bf16_f32 v177, v154, v155
	global_store_dwordx4 v[152:153], v[174:177], off nt
	s_cbranch_scc1 .LBB0_343
	s_cmp_eq_u32 s8, 4
	s_cselect_b64 s[66:67], -1, 0
	s_cbranch_execz .LBB0_344
	s_branch .LBB0_345

; __device__ __forceinline__ float siluf_(float x) { return x * sigmoidf_(x); }
;     __device__ __forceinline__ void operator()(f32x4 (&acc)[2][2][4][2], const Unit& u, int wr, int wc, int fr, int fq, LAS unsigned char* lds) const {
;     ...
;             const bool act = (seg == 1 || seg == 4);
; #pragma unroll
;             for (int ai = 0; ai < 2; ++ai)
; #pragma unroll
;                 for (int m = 0; m < 4; ++m) {
;                     bf16_t* rowp = base + (size_t)(row0 + ai * HALF + m * 16) * 1024 + col0;
; #pragma unroll
;                     for (int bj = 0; bj < 2; ++bj) {
;                         f32x4 v0 = acc[ai][bj][m][0], v1 = acc[ai][bj][m][1];
;                         if (act) {
; #pragma unroll
;                             for (int j = 0; j < 4; ++j) { v0[j] = siluf_(v0[j]); v1[j] = siluf_(v1[j]); }
;                         }
;                         store8(rowp + bj * HALF, v0, v1);
;                     }
.LBB0_353:
	v_lshlrev_b64 v[152:153], 11, v[148:149]
	v_lshl_add_u64 v[178:179], v[150:151], 0, v[152:153]
	s_mov_b64 s[10:11], 0x40000
	v_cvt_pk_bf16_f32 v174, v160, v161
	v_cvt_pk_bf16_f32 v175, v156, v157
	v_cvt_pk_bf16_f32 v176, v158, v159
	v_cvt_pk_bf16_f32 v177, v154, v155
	v_add_co_u32_e32 v154, vcc, 0x40000, v178
	v_lshl_add_u64 v[152:153], v[178:179], 0, s[10:11]
	s_nop 0
	v_addc_co_u32_e32 v155, vcc, 0, v179, vcc
	s_cmp_lt_i32 s8, 4
	global_store_dwordx4 v[154:155], v[174:177], off nt
	s_cbranch_scc1 .LBB0_355
	s_cmp_eq_u32 s8, 4
	s_cselect_b64 s[66:67], -1, 0
	s_cbranch_execz .LBB0_356
	s_branch .LBB0_357

; __device__ __forceinline__ float siluf_(float x) { return x * sigmoidf_(x); }
;     __device__ __forceinline__ void operator()(f32x4 (&acc)[2][2][4][2], const Unit& u, int wr, int wc, int fr, int fq, LAS unsigned char* lds) const {
;     ...
;             const bool act = (seg == 1 || seg == 4);
; #pragma unroll
;             for (int ai = 0; ai < 2; ++ai)
; #pragma unroll
;                 for (int m = 0; m < 4; ++m) {
;                     bf16_t* rowp = base + (size_t)(row0 + ai * HALF + m * 16) * 1024 + col0;
; #pragma unroll
;                     for (int bj = 0; bj < 2; ++bj) {
;                         f32x4 v0 = acc[ai][bj][m][0], v1 = acc[ai][bj][m][1];
;                         if (act) {
; #pragma unroll
;                             for (int j = 0; j < 4; ++j) { v0[j] = siluf_(v0[j]); v1[j] = siluf_(v1[j]); }
;                         }
;                         store8(rowp + bj * HALF, v0, v1);
;                     }
.LBB0_365:
	v_lshlrev_b64 v[152:153], 11, v[148:149]
	v_lshl_add_u64 v[178:179], v[150:151], 0, v[152:153]
	v_cvt_pk_bf16_f32 v174, v160, v161
	v_cvt_pk_bf16_f32 v175, v156, v157
	v_cvt_pk_bf16_f32 v176, v158, v159
	v_cvt_pk_bf16_f32 v177, v154, v155
	v_add_co_u32_e32 v154, vcc, 0x48000, v178
	v_lshl_add_u64 v[152:153], v[178:179], 0, s[54:55]
	s_nop 0
	v_addc_co_u32_e32 v155, vcc, 0, v179, vcc
	s_cmp_lt_i32 s8, 4
	global_store_dwordx4 v[154:155], v[174:177], off nt
	s_cbranch_scc1 .LBB0_367
	s_cmp_eq_u32 s8, 4
	s_cselect_b64 s[66:67], -1, 0
	s_cbranch_execz .LBB0_368
	s_branch .LBB0_369

; __device__ __forceinline__ float siluf_(float x) { return x * sigmoidf_(x); }
;     __device__ __forceinline__ void operator()(f32x4 (&acc)[2][2][4][2], const Unit& u, int wr, int wc, int fr, int fq, LAS unsigned char* lds) const {
;     ...
;             const bool act = (seg == 1 || seg == 4);
; #pragma unroll
;             for (int ai = 0; ai < 2; ++ai)
; #pragma unroll
;                 for (int m = 0; m < 4; ++m) {
;                     bf16_t* rowp = base + (size_t)(row0 + ai * HALF + m * 16) * 1024 + col0;
; #pragma unroll
;                     for (int bj = 0; bj < 2; ++bj) {
;                         f32x4 v0 = acc[ai][bj][m][0], v1 = acc[ai][bj][m][1];
;                         if (act) {
; #pragma unroll
;                             for (int j = 0; j < 4; ++j) { v0[j] = siluf_(v0[j]); v1[j] = siluf_(v1[j]); }
;                         }
;                         store8(rowp + bj * HALF, v0, v1);
;                     }
.LBB0_377:
	v_lshlrev_b64 v[152:153], 11, v[148:149]
	v_lshl_add_u64 v[178:179], v[150:151], 0, v[152:153]
	v_cvt_pk_bf16_f32 v174, v160, v161
	v_cvt_pk_bf16_f32 v175, v156, v157
	v_cvt_pk_bf16_f32 v176, v158, v159
	v_cvt_pk_bf16_f32 v177, v154, v155
	v_add_co_u32_e32 v154, vcc, 0x50000, v178
	v_lshl_add_u64 v[152:153], v[178:179], 0, s[56:57]
	s_nop 0
	v_addc_co_u32_e32 v155, vcc, 0, v179, vcc
	s_cmp_lt_i32 s8, 4
	global_store_dwordx4 v[154:155], v[174:177], off nt
	s_cbranch_scc1 .LBB0_379
	s_cmp_eq_u32 s8, 4
	s_cselect_b64 s[66:67], -1, 0
	s_cbranch_execz .LBB0_380
	s_branch .LBB0_381

; __device__ __forceinline__ float siluf_(float x) { return x * sigmoidf_(x); }
;     __device__ __forceinline__ void operator()(f32x4 (&acc)[2][2][4][2], const Unit& u, int wr, int wc, int fr, int fq, LAS unsigned char* lds) const {
;     ...
;             const bool act = (seg == 1 || seg == 4);
; #pragma unroll
;             for (int ai = 0; ai < 2; ++ai)
; #pragma unroll
;                 for (int m = 0; m < 4; ++m) {
;                     bf16_t* rowp = base + (size_t)(row0 + ai * HALF + m * 16) * 1024 + col0;
; #pragma unroll
;                     for (int bj = 0; bj < 2; ++bj) {
;                         f32x4 v0 = acc[ai][bj][m][0], v1 = acc[ai][bj][m][1];
;                         if (act) {
; #pragma unroll
;                             for (int j = 0; j < 4; ++j) { v0[j] = siluf_(v0[j]); v1[j] = siluf_(v1[j]); }
;                         }
;                         store8(rowp + bj * HALF, v0, v1);
;                     }
.LBB0_389:
	v_lshlrev_b64 v[160:161], 11, v[148:149]
	v_lshl_add_u64 v[174:175], v[150:151], 0, v[160:161]
	v_cvt_pk_bf16_f32 v158, v158, v159
	v_cvt_pk_bf16_f32 v159, v154, v155
	v_cvt_pk_bf16_f32 v160, v156, v157
	v_cvt_pk_bf16_f32 v161, v152, v153
	v_add_co_u32_e32 v152, vcc, 0x58000, v174
	v_lshl_add_u64 v[150:151], v[174:175], 0, s[58:59]
	s_nop 0
	v_addc_co_u32_e32 v153, vcc, 0, v175, vcc
	s_cmp_lt_i32 s8, 4
	global_store_dwordx4 v[152:153], v[158:161], off nt
	s_cbranch_scc1 .LBB0_391
	s_cmp_eq_u32 s8, 4
	s_cselect_b64 s[66:67], -1, 0
	s_cbranch_execz .LBB0_392
	s_branch .LBB0_393

; __device__ __forceinline__ float siluf_(float x) { return x * sigmoidf_(x); }
;     __device__ __forceinline__ void operator()(f32x4 (&acc)[2][2][4][2], const Unit& u, int wr, int wc, int fr, int fq, LAS unsigned char* lds) const {
;     ...
;             const bool act = (seg == 1 || seg == 4);
; #pragma unroll
;             for (int ai = 0; ai < 2; ++ai)
; #pragma unroll
;                 for (int m = 0; m < 4; ++m) {
;                     bf16_t* rowp = base + (size_t)(row0 + ai * HALF + m * 16) * 1024 + col0;
; #pragma unroll
;                     for (int bj = 0; bj < 2; ++bj) {
;                         f32x4 v0 = acc[ai][bj][m][0], v1 = acc[ai][bj][m][1];
;                         if (act) {
; #pragma unroll
;                             for (int j = 0; j < 4; ++j) { v0[j] = siluf_(v0[j]); v1[j] = siluf_(v1[j]); }
;                         }
;                         store8(rowp + bj * HALF, v0, v1);
;                     }
.LBB0_395:
	v_cvt_pk_bf16_f32 v158, v158, v159
	v_cvt_pk_bf16_f32 v159, v154, v155
	s_nop 0
	v_cvt_pk_bf16_f32 v160, v156, v157
	v_cvt_pk_bf16_f32 v161, v152, v153
	global_store_dwordx4 v[150:151], v[158:161], off offset:256 nt

; __device__ __forceinline__ float siluf_(float x) { return x * sigmoidf_(x); }
;     __device__ __forceinline__ void operator()(f32x4 (&acc)[2][2][4][2], const Unit& u, int wr, int wc, int fr, int fq, LAS unsigned char* lds) const {
;         const int seg = (u.pn * BM) / ldc >= 1 && O1 != nullptr ? 1 : 0;
;         const int colt = (O1 != nullptr) ? (u.pn * BM - seg * ldc) : u.pn * BM;
;         bf16_t* base = seg ? O1 : O0;
;         const bool act = seg && (act1 & 1);
;         const bool grp = !seg && (act1 & 2);
;         const int row0 = u.pm * BM + wr * 64 + fr, col0 = colt + wc * 32 + 8 * fq;
; #pragma unroll
;         for (int ai = 0; ai < 2; ++ai)
; #pragma unroll
;             for (int m = 0; m < 4; ++m) {
;                 bf16_t* rowp = base + (size_t)(row0 + ai * HALF + m * 16) * ldc + col0;
; #pragma unroll
;                 for (int bj = 0; bj < 2; ++bj) {
;                     f32x4 v0 = acc[ai][bj][m][0], v1 = acc[ai][bj][m][1];
;                     if (act) {
; #pragma unroll
;                         for (int j = 0; j < 4; ++j) { v0[j] = siluf_(v0[j]); v1[j] = siluf_(v1[j]); }
;                     }
;                     if (grp) { const int cc = col0 + bj * HALF; store8(base + ((size_t)(cc >> 4) * T + (row0 + ai * HALF + m * 16)) * 16 + (cc & 15), v0, v1); }
;                     else store8(rowp + bj * HALF, v0, v1);
.LBB0_416:
	v_lshrrev_b32_e32 v160, 6, v150
	v_lshl_or_b32 v160, s83, 2, v160
	v_xor_b32_e32 v160, v160, v148
	v_lshlrev_b32_e32 v160, 7, v160
	v_lshl_or_b32 v160, v148, 16, v160
	v_and_b32_e32 v161, 63, v150
	v_lshlrev_b32_e32 v162, 1, v161
	s_lshl_b32 s68, s54, 24
	v_add_u32_e32 v162, s68, v162
	v_mov_b32_e32 v163, 0
	v_lshl_add_u64 v[164:165], v[162:163], 0, s[26:27]
	v_mov_b32_e32 v167, 0
	v_mov_b32_e32 v169, 0
	v_lshl_add_u32 v146, s54, 8, v148
	v_lshl_or_b32 v144, s83, 8, v150
	v_ashrrev_i32_e32 v145, 31, v144
	v_ashrrev_i32_e32 v147, 31, v146
	v_lshl_add_u64 v[154:155], v[144:145], 1, s[26:27]
	v_lshlrev_b64 v[144:145], 16, v[146:147]
	v_lshl_add_u64 v[144:145], v[154:155], 0, v[144:145]
	v_cvt_pk_bf16_f32 v124, v124, v125
	v_cvt_pk_bf16_f32 v125, v126, v127
	v_cvt_pk_bf16_f32 v126, v120, v121
	v_cvt_pk_bf16_f32 v127, v122, v123
	v_mov_b32_e32 v166, v160
	v_lshl_add_u64 v[172:173], v[166:167], 0, v[164:165]
	global_store_dwordx4 v[172:173], v[124:127], off nt
	v_cvt_pk_bf16_f32 v112, v112, v113
	v_cvt_pk_bf16_f32 v113, v114, v115
	v_cvt_pk_bf16_f32 v114, v104, v105
	v_or_b32_e32 v104, 16, v146
	v_ashrrev_i32_e32 v105, 31, v104
	v_lshlrev_b64 v[104:105], 16, v[104:105]
	v_cvt_pk_bf16_f32 v115, v106, v107
	v_xor_b32_e32 v168, 0x100, v160
	v_lshl_add_u64 v[174:175], v[168:169], 0, v[164:165]
	global_store_dwordx4 v[174:175], v[112:115], off nt
	s_mov_b32 s4, 0x800000
	s_mov_b64 s[54:55], 0x800000
	v_lshl_add_u64 v[112:113], v[154:155], 0, v[104:105]
	v_cvt_pk_bf16_f32 v104, v116, v117
	v_cvt_pk_bf16_f32 v105, v118, v119
	v_cvt_pk_bf16_f32 v106, v108, v109
	v_cvt_pk_bf16_f32 v107, v110, v111
	v_xor_b32_e32 v166, 0x100800, v160
	v_lshl_add_u64 v[172:173], v[166:167], 0, v[164:165]
	global_store_dwordx4 v[172:173], v[104:107], off nt
	v_cvt_pk_bf16_f32 v96, v96, v97
	v_cvt_pk_bf16_f32 v97, v98, v99
	v_cvt_pk_bf16_f32 v98, v88, v89
	v_or_b32_e32 v88, 32, v146
	v_ashrrev_i32_e32 v89, 31, v88
	v_lshlrev_b64 v[88:89], 16, v[88:89]
	v_cvt_pk_bf16_f32 v99, v90, v91
	v_xor_b32_e32 v168, 0x100900, v160
	v_lshl_add_u64 v[174:175], v[168:169], 0, v[164:165]
	global_store_dwordx4 v[174:175], v[96:99], off nt
	s_nop 1
	v_lshl_add_u64 v[96:97], v[154:155], 0, v[88:89]
	v_cvt_pk_bf16_f32 v88, v100, v101
	v_cvt_pk_bf16_f32 v89, v102, v103
	v_cvt_pk_bf16_f32 v90, v92, v93
	v_cvt_pk_bf16_f32 v91, v94, v95
	v_xor_b32_e32 v166, 0x201000, v160
	v_lshl_add_u64 v[172:173], v[166:167], 0, v[164:165]
	global_store_dwordx4 v[172:173], v[88:91], off nt
	v_cvt_pk_bf16_f32 v80, v80, v81
	v_cvt_pk_bf16_f32 v81, v82, v83
	v_cvt_pk_bf16_f32 v82, v72, v73
	v_or_b32_e32 v72, 48, v146
	v_ashrrev_i32_e32 v73, 31, v72
	v_lshlrev_b64 v[72:73], 16, v[72:73]
	v_cvt_pk_bf16_f32 v83, v74, v75
	v_xor_b32_e32 v168, 0x201100, v160
	v_lshl_add_u64 v[174:175], v[168:169], 0, v[164:165]
	global_store_dwordx4 v[174:175], v[80:83], off nt
	s_nop 1
	v_lshl_add_u64 v[80:81], v[154:155], 0, v[72:73]
	v_cvt_pk_bf16_f32 v72, v84, v85
	v_cvt_pk_bf16_f32 v73, v86, v87
	v_cvt_pk_bf16_f32 v74, v76, v77
	v_cvt_pk_bf16_f32 v75, v78, v79
	v_xor_b32_e32 v166, 0x301800, v160
	v_lshl_add_u64 v[172:173], v[166:167], 0, v[164:165]
	global_store_dwordx4 v[172:173], v[72:75], off nt
	v_cvt_pk_bf16_f32 v68, v68, v69
	v_cvt_pk_bf16_f32 v69, v70, v71
	v_cvt_pk_bf16_f32 v70, v64, v65
	v_cvt_pk_bf16_f32 v71, v66, v67
	v_xor_b32_e32 v168, 0x301900, v160
	v_lshl_add_u64 v[174:175], v[168:169], 0, v[164:165]
	global_store_dwordx4 v[174:175], v[68:71], off nt
	v_cvt_pk_bf16_f32 v60, v60, v61
	v_cvt_pk_bf16_f32 v61, v62, v63
	v_cvt_pk_bf16_f32 v62, v56, v57
	v_add_co_u32_e32 v56, vcc, s4, v144
	v_lshl_add_u64 v[64:65], v[144:145], 0, s[54:55]
	s_nop 0
	v_addc_co_u32_e32 v57, vcc, 0, v145, vcc
	s_mov_b32 s4, 0x900000
	v_cvt_pk_bf16_f32 v63, v58, v59
	v_xor_b32_e32 v166, 0x804000, v160
	v_lshl_add_u64 v[172:173], v[166:167], 0, v[164:165]
	global_store_dwordx4 v[172:173], v[60:63], off nt
	v_cvt_pk_bf16_f32 v48, v48, v49
	v_cvt_pk_bf16_f32 v49, v50, v51
	v_cvt_pk_bf16_f32 v50, v40, v41
	v_cvt_pk_bf16_f32 v51, v42, v43
	v_xor_b32_e32 v168, 0x804100, v160
	v_lshl_add_u64 v[174:175], v[168:169], 0, v[164:165]
	global_store_dwordx4 v[174:175], v[48:51], off nt
	s_mov_b64 s[54:55], 0x900000
	v_cvt_pk_bf16_f32 v40, v52, v53
	v_cvt_pk_bf16_f32 v41, v54, v55
	v_cvt_pk_bf16_f32 v42, v44, v45
	v_add_co_u32_e32 v44, vcc, s4, v144
	v_lshl_add_u64 v[48:49], v[144:145], 0, s[54:55]
	s_nop 0
	v_addc_co_u32_e32 v45, vcc, 0, v145, vcc
	s_mov_b32 s4, 0xa00000
	v_cvt_pk_bf16_f32 v43, v46, v47
	v_xor_b32_e32 v166, 0x904800, v160
	v_lshl_add_u64 v[172:173], v[166:167], 0, v[164:165]
	global_store_dwordx4 v[172:173], v[40:43], off nt
	v_cvt_pk_bf16_f32 v32, v32, v33
	v_cvt_pk_bf16_f32 v33, v34, v35
	v_cvt_pk_bf16_f32 v34, v24, v25
	v_cvt_pk_bf16_f32 v35, v26, v27
	v_xor_b32_e32 v168, 0x904900, v160
	v_lshl_add_u64 v[174:175], v[168:169], 0, v[164:165]
	global_store_dwordx4 v[174:175], v[32:35], off nt
	s_mov_b64 s[54:55], 0xa00000
	v_cvt_pk_bf16_f32 v24, v36, v37
	v_cvt_pk_bf16_f32 v25, v38, v39
	v_cvt_pk_bf16_f32 v26, v28, v29
	v_add_co_u32_e32 v28, vcc, s4, v144
	v_lshl_add_u64 v[32:33], v[144:145], 0, s[54:55]
	s_nop 0
	v_addc_co_u32_e32 v29, vcc, 0, v145, vcc
	s_mov_b32 s4, 0xb00000
	v_cvt_pk_bf16_f32 v27, v30, v31
	v_xor_b32_e32 v166, 0xa05000, v160
	v_lshl_add_u64 v[172:173], v[166:167], 0, v[164:165]
	global_store_dwordx4 v[172:173], v[24:27], off nt
	v_cvt_pk_bf16_f32 v16, v16, v17
	v_cvt_pk_bf16_f32 v17, v18, v19
	v_cvt_pk_bf16_f32 v18, v8, v9
	v_cvt_pk_bf16_f32 v19, v10, v11
	v_xor_b32_e32 v168, 0xa05100, v160
	v_lshl_add_u64 v[174:175], v[168:169], 0, v[164:165]
	global_store_dwordx4 v[174:175], v[16:19], off nt
	v_cvt_pk_bf16_f32 v8, v20, v21
	v_cvt_pk_bf16_f32 v9, v22, v23
	v_cvt_pk_bf16_f32 v10, v12, v13
	v_add_co_u32_e32 v12, vcc, s4, v144
	s_mov_b64 s[54:55], 0xb00000
	s_nop 0
	v_addc_co_u32_e32 v13, vcc, 0, v145, vcc
	v_lshl_add_u64 v[16:17], v[144:145], 0, s[54:55]
	s_andn2_b64 vcc, exec, s[0:1]
	s_mov_b64 s[0:1], -1
	v_cvt_pk_bf16_f32 v11, v14, v15
	v_xor_b32_e32 v166, 0xb05800, v160
	v_lshl_add_u64 v[172:173], v[166:167], 0, v[164:165]
	global_store_dwordx4 v[172:173], v[8:11], off nt
	v_cvt_pk_bf16_f32 v4, v4, v5
	v_cvt_pk_bf16_f32 v5, v6, v7
	v_cvt_pk_bf16_f32 v6, v0, v1
	v_cvt_pk_bf16_f32 v7, v2, v3
	v_xor_b32_e32 v168, 0xb05900, v160
	v_lshl_add_u64 v[174:175], v[168:169], 0, v[164:165]
	global_store_dwordx4 v[174:175], v[4:7], off nt
	s_cbranch_vccnz .LBB0_405
	s_andn2_b64 vcc, exec, s[8:9]
	s_cbranch_vccnz .LBB0_404
	s_barrier
	s_branch .LBB0_404

; #define LAS __attribute__((address_space(3)))
; #define ATT_LOAD(kbi) do { const int k0_ = (kbi) * 64; _Pragma("unroll") for (int i_ = 0; i_ < 4; ++i_) { const int ci = (tid + 512 * i_) & 1023, hh_ = 2 * hp + (i_ >> 1); \
;         pk[i_] = *(const u32x4*)(Km + (rowbase + k0_ + (ci >> 4)) * 1024 + hh_ * 128 + (ci & 15) * 8); \
;         pv[i_] = *(const u32x4*)(VT + (size_t)(hh_ * 128 + (ci >> 3)) * T + rowbase + k0_ + (ci & 7) * 8); } } while (0)
; __device__ __forceinline__ void attn_unit(LAS unsigned char* lds, const bf16_t* Qm, const bf16_t* Km, const bf16_t* VT, const bf16_t* GBm, bf16_t* YB, int b, int hp, int qb) {
;     int tidl_ = threadIdx.x; asm volatile("" : "+v"(tidl_));
;     const int tid = tidl_, wave = tid >> 6, lane = tid & 63, fr = lane & 15, fq = lane >> 4;
;     const int hsel = wave >> 2, h = 2 * hp + hsel;
;     const int q0 = qb * 64, qw = q0 + (hsel ? 3 - (wave & 3) : (wave & 3)) * 16;
;     const size_t rowbase = (size_t)b * SEQ;
;     LAS unsigned char* KL = lds + hsel * 35840;
;     LAS unsigned char* VL = KL + 17408;
;     volatile LAS int* FL = (volatile LAS int*)(lds + 71680);
;     bf16x8 qf[4];
;     { const bf16_t* qp = Qm + (rowbase + qw + fr) * 1024 + h * 128 + fq * 8;
; #pragma unroll
;       for (int ks = 0; ks < 4; ++ks) qf[ks] = *(const bf16x8*)(qp + ks * 32); }
;     f32x4 o[8];
; #pragma unroll
;     for (int d = 0; d < 8; ++d) o[d] = (f32x4){0.f, 0.f, 0.f, 0.f};
;     float Rs = 1.f;
;     int kb = q0 >> 6;
;     u32x4 pk[4], pv[4];
;     ...
;     ATT_LOAD(kb);
.LBB0_515:
	v_mov_b32_e32 v32, v226
	s_ashr_i32 s0, s39, 4
	s_sub_i32 s0, 0x7f, s0
	v_ashrrev_i32_e32 v33, 6, v32
	v_bitop3_b32 v0, v33, 3, v33 bitop3:0xc
	v_cmp_gt_u32_e32 vcc, s6, v32
	s_lshl_b32 s1, s39, 11
	s_lshl_b32 s56, s0, 6
	v_cndmask_b32_e32 v0, v0, v33, vcc
	s_and_b32 s60, s1, 0x6000
	s_lshl_b32 s1, s39, 8
	v_lshl_add_u32 v44, v0, 4, s56
	s_and_b32 s8, s1, 0x300
	s_and_b32 s61, s0, 0x3ffffff
	s_add_i32 s9, s56, s60
	s_lshl_b32 s0, s60, 1
	v_and_b32_e32 v34, 15, v32
	v_add_u32_e32 v0, s60, v44
	s_add_u32 s0, s26, s0
	v_bitop3_b32 v36, v32, s7, v104 bitop3:0x6c
	v_ashrrev_i32_e32 v35, 8, v32
	v_or_b32_e32 v80, v0, v34
	s_addc_u32 s1, s27, 0
	s_lshl_b64 s[4:5], s[56:57], 1
	v_lshrrev_b32_e32 v88, 4, v36
	v_lshlrev_b64 v[0:1], 11, v[80:81]
	v_lshl_add_u32 v84, v35, 7, s8
	s_add_u32 s4, s0, s4
	v_lshlrev_b32_e32 v22, 4, v32
	v_bfe_u32 v86, v32, 4, 6
	v_bfe_u32 v45, v32, 3, 7
	v_or_b32_e32 v26, s9, v88
	v_mov_b32_e32 v27, v81
	v_lshl_add_u64 v[0:1], s[46:47], 0, v[0:1]
	v_ashrrev_i32_e32 v85, 31, v84
	s_addc_u32 s5, s1, s5
	v_and_b32_e32 v16, 0x70, v22
	v_mov_b32_e32 v17, v81
	v_or_b32_e32 v20, s9, v86
	v_mov_b32_e32 v21, v81
	v_or_b32_e32 v46, s8, v45
	v_lshlrev_b64 v[26:27], 11, v[26:27]
	v_lshlrev_b64 v[82:83], 10, v[80:81]
	v_lshl_add_u64 v[0:1], v[84:85], 1, v[0:1]
	v_and_b32_e32 v80, 48, v32
	v_lshl_add_u64 v[18:19], s[4:5], 0, v[16:17]
	v_lshlrev_b64 v[20:21], 11, v[20:21]
	s_lshl_b32 s12, s8, 1
	s_mov_b32 s13, s57
	v_lshlrev_b32_e32 v24, 16, v46
	v_mov_b32_e32 v25, v81
	v_lshl_add_u64 v[26:27], s[44:45], 0, v[26:27]
	v_lshrrev_b32_e32 v47, 3, v36
	v_lshl_add_u64 v[12:13], v[0:1], 0, v[80:81]
	v_lshl_add_u64 v[20:21], s[44:45], 0, v[20:21]
	v_and_b32_e32 v22, 0xf0, v22
	v_mov_b32_e32 v23, v81
	v_lshl_add_u64 v[24:25], v[18:19], 0, v[24:25]
	v_lshl_add_u64 v[26:27], v[26:27], 0, s[12:13]
	v_or_b32_e32 v56, s8, v47
	global_load_dwordx4 v[0:3], v[12:13], off
	global_load_dwordx4 v[4:7], v[12:13], off offset:64
	global_load_dwordx4 v[8:11], v[12:13], off offset:128
	s_nop 0
	global_load_dwordx4 v[12:15], v[12:13], off offset:192
	v_lshl_add_u64 v[20:21], v[20:21], 0, s[12:13]
	v_lshl_add_u64 v[26:27], v[26:27], 0, v[22:23]
	v_lshrrev_b32_e32 v196, 3, v226
	v_and_b32_e32 v197, 7, v226
	v_lshlrev_b32_e32 v197, 4, v197
	v_add_u32_e32 v198, s8, v196
	v_lshlrev_b32_e32 v198, 16, v198
	v_or_b32_e32 v198, v198, v197
	v_mov_b32_e32 v199, 0
	s_mov_b32 s66, 0x400000
	s_mov_b32 s67, 0
	v_lshl_add_u64 v[216:217], v[198:199], 0, s[26:27]
	v_lshl_add_u64 v[218:219], v[216:217], 0, s[66:67]
	v_lshl_add_u64 v[220:221], v[218:219], 0, s[66:67]
	v_lshl_add_u64 v[222:223], v[220:221], 0, s[66:67]
	v_lshlrev_b32_e32 v196, 7, v196
	v_add_u32_e32 v228, 0x2000, v196
	v_add_u32_e32 v229, 0x4000, v196
	v_add_u32_e32 v230, 0x6000, v196
	v_mov_b32_e32 v233, 0
	v_mov_b32_e32 v235, 0
	v_mov_b32_e32 v237, 0
	v_mov_b32_e32 v239, 0
	s_add_i32 s68, s60, s56
	s_lshl_b32 s68, s68, 1
	v_xor_b32_e32 v232, s68, v196
	v_xor_b32_e32 v234, s68, v228
	v_xor_b32_e32 v236, s68, v229
	v_xor_b32_e32 v238, s68, v230
	v_lshl_add_u64 v[200:201], v[232:233], 0, v[216:217]
	v_lshl_add_u64 v[202:203], v[234:235], 0, v[218:219]
	v_lshl_add_u64 v[204:205], v[236:237], 0, v[220:221]
	v_lshl_add_u64 v[206:207], v[238:239], 0, v[222:223]
	global_load_dwordx4 v[28:31], v[200:201], off
	global_load_dwordx4 v[40:43], v[26:27], off
	v_lshlrev_b32_e32 v24, 16, v56
	v_mov_b32_e32 v25, v81
	s_or_b32 s58, s8, 0x80
	v_lshl_add_u64 v[20:21], v[20:21], 0, v[22:23]
	v_lshl_add_u64 v[24:25], v[18:19], 0, v[24:25]
	v_or_b32_e32 v57, s58, v45
	global_load_dwordx4 v[36:39], v[20:21], off
	global_load_dwordx4 v[48:51], v[20:21], off offset:256
	v_lshlrev_b32_e32 v20, 16, v57
	v_mov_b32_e32 v21, v81
	global_load_dwordx4 v[52:55], v[202:203], off
	global_load_dwordx4 v[64:67], v[26:27], off offset:256
	v_or_b32_e32 v26, s58, v47
	v_lshl_add_u64 v[20:21], v[18:19], 0, v[20:21]
	v_lshlrev_b32_e32 v24, 16, v26
	v_mov_b32_e32 v25, v81
	v_lshl_add_u64 v[18:19], v[18:19], 0, v[24:25]
	global_load_dwordx4 v[68:71], v[204:205], off
	global_load_dwordx4 v[76:79], v[206:207], off
	v_lshl_add_u64 v[90:91], s[0:1], 0, v[16:17]
	v_lshlrev_b32_e32 v17, 1, v32
	v_and_b32_e32 v21, 3, v32
	v_and_or_b32 v17, v17, 24, v21
	v_add_u32_e32 v21, 16, v32
	v_mul_i32_i24_e32 v19, 0x8c00, v35
	v_and_b32_e32 v21, 63, v21
	v_add_u32_e32 v25, 48, v32
	v_mad_u32_u24 v35, v45, s38, 0
	v_mad_u32_u24 v45, v47, s38, 0
	s_add_u32 s12, s44, s12
	v_and_b32_e32 v25, 63, v25
	s_addc_u32 s13, s45, 0
	v_add_u32_e32 v113, v35, v16
	v_add_u32_e32 v115, v45, v16
	v_or_b32_e32 v16, v105, v21
	v_and_b32_e32 v107, 63, v32
	v_bfe_u32 v106, v32, 4, 2
	v_lshlrev_b32_e32 v18, 15, v46
	v_lshlrev_b32_e32 v20, 15, v56
	v_lshlrev_b32_e32 v24, 15, v57
	v_lshlrev_b32_e32 v26, 15, v26
	v_or_b32_e32 v109, 15, v44
	v_lshl_add_u32 v110, v33, 2, s28
	v_add3_u32 v19, 0, v19, v80
	v_or_b32_e32 v111, v44, v34
	v_mad_u32_u24 v27, v86, s29, 0
	v_mad_u32_u24 v44, v88, s29, 0
	v_lshl_add_u64 v[92:93], s[12:13], 0, v[22:23]
	v_lshl_add_u64 v[32:33], s[44:45], 0, v[22:23]
	v_mul_u32_u24_e32 v17, 0x110, v17
	v_mul_u32_u24_e32 v23, 0x90, v34
	s_lshl_b32 s12, s58, 1
	s_mov_b32 s13, s57
	v_mov_b32_e32 v60, v81
	v_mov_b32_e32 v61, v81
	v_mov_b32_e32 v62, v81
	v_mov_b32_e32 v63, v81
	v_lshlrev_b32_e32 v118, 2, v16
	v_or_b32_e32 v16, v105, v25
	v_lshl_add_u64 v[94:95], v[32:33], 0, s[12:13]
	v_add_u32_e32 v112, v27, v22
	v_add_u32_e32 v114, v44, v22
	v_lshlrev_b32_e32 v80, 1, v18
	v_lshlrev_b32_e32 v98, 1, v20
	v_lshlrev_b32_e32 v100, 1, v24
	v_lshlrev_b32_e32 v102, 1, v26
	v_add_u32_e32 v116, v19, v17
	v_add_u32_e32 v117, v19, v23
	v_lshlrev_b32_e32 v119, 2, v16
	v_mov_b64_e32 v[74:75], v[62:63]
	v_mov_b64_e32 v[56:57], v[60:61]
	v_mov_b64_e32 v[44:45], v[60:61]
	v_mov_b64_e32 v[32:33], v[60:61]
	v_mov_b64_e32 v[24:25], v[60:61]
	v_mov_b64_e32 v[20:21], v[60:61]
	v_mov_b64_e32 v[16:17], v[60:61]
	v_lshlrev_b32_e32 v108, 3, v106
	v_mov_b32_e32 v87, v81
	v_mov_b32_e32 v89, v81
	v_cmp_eq_u32_e64 s[0:1], 3, v106
	v_cmp_gt_u32_e64 s[10:11], 32, v107
	v_cmp_gt_u32_e64 s[4:5], 16, v107
	v_cmp_eq_u32_e64 s[8:9], 0, v107
	s_lshl_b32 s62, s61, 3
	s_sub_i32 s56, s56, 64
	v_mov_b32_e32 v96, 1.0
	s_mov_b32 s63, s57
	v_mov_b64_e32 v[72:73], v[60:61]
	v_mov_b64_e32 v[58:59], v[62:63]
	v_mov_b64_e32 v[46:47], v[62:63]
	v_mov_b64_e32 v[34:35], v[62:63]
	v_mov_b64_e32 v[26:27], v[62:63]
	v_mov_b64_e32 v[22:23], v[62:63]
	v_mov_b64_e32 v[18:19], v[62:63]
	s_branch .LBB0_517

; #define LAS __attribute__((address_space(3)))
; #define ATT_LOAD(kbi) do { const int k0_ = (kbi) * 64; _Pragma("unroll") for (int i_ = 0; i_ < 4; ++i_) { const int ci = (tid + 512 * i_) & 1023, hh_ = 2 * hp + (i_ >> 1); \
;         pk[i_] = *(const u32x4*)(Km + (rowbase + k0_ + (ci >> 4)) * 1024 + hh_ * 128 + (ci & 15) * 8); \
;         pv[i_] = *(const u32x4*)(VT + (size_t)(hh_ * 128 + (ci >> 3)) * T + rowbase + k0_ + (ci & 7) * 8); } } while (0)
; __device__ __forceinline__ void attn_unit(LAS unsigned char* lds, const bf16_t* Qm, const bf16_t* Km, const bf16_t* VT, const bf16_t* GBm, bf16_t* YB, int b, int hp, int qb) {
;     ...
;     for (;;) {
; #pragma unroll
;         for (int i = 0; i < 4; ++i) { const int ci = (tid + 512 * i) & 1023; LAS unsigned char* kd = lds + (i >> 1) * 35840;
;             *(LAS u32x4*)(kd + (ci >> 4) * 272 + (ci & 15) * 16) = pk[i];
;             *(LAS u32x4*)(kd + 17408 + (ci >> 3) * 144 + (ci & 7) * 16) = pv[i]; }
;         __syncthreads();
;         if (kb > 0) ATT_LOAD(kb - 1);
.LBB0_517:
	s_cmp_lt_i32 s61, 1
	s_waitcnt vmcnt(5)
	ds_write_b128 v112, v[36:39]
	ds_write_b128 v113, v[28:31] offset:17408
	ds_write_b128 v114, v[40:43]
	s_waitcnt vmcnt(3)
	ds_write_b128 v115, v[52:55] offset:17408
	ds_write_b128 v112, v[48:51] offset:35840
	s_waitcnt vmcnt(1)
	ds_write_b128 v113, v[68:71] offset:53248
	ds_write_b128 v114, v[64:67] offset:35840
	s_waitcnt vmcnt(0)
	ds_write_b128 v115, v[76:79] offset:53248
	s_waitcnt lgkmcnt(0)
	s_barrier
	s_cbranch_scc1 .LBB0_519
	s_add_i32 s12, s56, s60
	v_or_b32_e32 v28, s12, v86
	v_mov_b32_e32 v29, v87
	v_or_b32_e32 v40, s12, v88
	v_mov_b32_e32 v41, v89
	v_lshl_add_u64 v[64:65], s[56:57], 1, v[90:91]
	v_lshlrev_b64 v[48:49], 11, v[28:29]
	v_lshlrev_b64 v[66:67], 11, v[40:41]
	v_mov_b32_e32 v99, v81
	v_mov_b32_e32 v101, v81
	v_mov_b32_e32 v103, v81
	v_lshl_add_u64 v[28:29], v[92:93], 0, v[48:49]
	v_lshl_add_u64 v[30:31], v[64:65], 0, v[80:81]
	v_lshl_add_u64 v[40:41], v[92:93], 0, v[66:67]
	v_lshl_add_u64 v[50:51], v[64:65], 0, v[98:99]
	v_lshl_add_u64 v[48:49], v[94:95], 0, v[48:49]
	v_lshl_add_u64 v[68:69], v[64:65], 0, v[100:101]
	v_lshl_add_u64 v[66:67], v[94:95], 0, v[66:67]
	v_lshl_add_u64 v[76:77], v[64:65], 0, v[102:103]
	s_lshl_b32 s68, s12, 1
	v_xor_b32_e32 v232, s68, v196
	v_xor_b32_e32 v234, s68, v228
	v_xor_b32_e32 v236, s68, v229
	v_xor_b32_e32 v238, s68, v230
	v_lshl_add_u64 v[200:201], v[232:233], 0, v[216:217]
	v_lshl_add_u64 v[202:203], v[234:235], 0, v[218:219]
	v_lshl_add_u64 v[204:205], v[236:237], 0, v[220:221]
	v_lshl_add_u64 v[206:207], v[238:239], 0, v[222:223]
	global_load_dwordx4 v[36:39], v[28:29], off
	s_nop 0
	global_load_dwordx4 v[28:31], v[200:201], off
	s_nop 0
	global_load_dwordx4 v[40:43], v[40:41], off
	s_nop 0
	global_load_dwordx4 v[52:55], v[202:203], off
	s_nop 0
	global_load_dwordx4 v[48:51], v[48:49], off
	s_nop 0
	global_load_dwordx4 v[68:71], v[204:205], off
	s_nop 0
	global_load_dwordx4 v[64:67], v[66:67], off
	s_nop 0
	global_load_dwordx4 v[76:79], v[206:207], off

;     __device__ __forceinline__ void operator()(f32x4 (&acc)[2][2][4][2], const Unit& u, int wr, int wc, int fr, int fq, LAS unsigned char* lds) const {
;         const int b = (u.pm * BM) / SEQ;
;         const int row0 = u.pm * BM + wr * 64 + fr, col0 = u.pn * BM + wc * 32 + 8 * fq;
;         f32x4 gv[2][2];
; #pragma unroll
;         for (int bj = 0; bj < 2; ++bj)
; #pragma unroll
;             for (int n = 0; n < 2; ++n) gv[bj][n] = *(const f32x4*)(gate + b * 3072 + col0 + bj * HALF + 4 * n);
; #pragma unroll
;         for (int ai = 0; ai < 2; ++ai) {
;             f32x4 xv[4][2][2];
; #pragma unroll
;             for (int m = 0; m < 4; ++m) {
;                 const size_t off = (size_t)(row0 + ai * HALF + m * 16) * 1024 + col0;
; #pragma unroll
;                 for (int bj = 0; bj < 2; ++bj)
; #pragma unroll
;                     for (int n = 0; n < 2; ++n) xv[m][bj][n] = *(const f32x4*)(base + off + bj * HALF + 4 * n);
;             }
; #pragma unroll
;             for (int m = 0; m < 4; ++m) {
;                 const size_t off = (size_t)(row0 + ai * HALF + m * 16) * 1024 + col0;
; #pragma unroll
;                 for (int bj = 0; bj < 2; ++bj) store8(out + off + bj * HALF, xv[m][bj][0] + gv[bj][0] * acc[ai][bj][m][0], xv[m][bj][1] + gv[bj][1] * acc[ai][bj][m][1]);
;             }
;             asm volatile("" ::: "memory");
.LBB0_708:
	s_lshr_b32 s4, s63, 27
	s_add_i32 s4, s62, s4
	s_lshr_b32 s4, s4, 5
	s_mul_i32 s66, s4, 0xc00
	s_ashr_i32 s67, s66, 31
	v_lshl_or_b32 v164, s64, 8, v173
	s_lshl_b64 s[66:67], s[66:67], 2
	s_add_u32 s66, s97, s66
	v_ashrrev_i32_e32 v165, 31, v164
	v_lshl_add_u32 v168, s62, 8, v171
	s_addc_u32 s67, s91, s67
	v_lshlrev_b64 v[128:129], 2, v[164:165]
	v_ashrrev_i32_e32 v169, 31, v168
	v_lshl_add_u64 v[132:133], s[66:67], 0, v[128:129]
	v_lshl_add_u64 v[166:167], s[36:37], 0, v[128:129]
	v_lshlrev_b64 v[128:129], 12, v[168:169]
	v_or_b32_e32 v224, 16, v168
	v_lshl_add_u64 v[144:145], v[166:167], 0, v[128:129]
	v_ashrrev_i32_e32 v225, 31, v224
	global_load_dwordx4 v[136:139], v[132:133], off offset:16 nt
	global_load_dwordx4 v[140:143], v[132:133], off nt
	global_load_dwordx4 v[176:179], v[144:145], off offset:16 nt
	global_load_dwordx4 v[180:183], v[144:145], off nt
	global_load_dwordx4 v[128:131], v[132:133], off offset:528 nt
	s_nop 0
	global_load_dwordx4 v[132:135], v[132:133], off offset:512 nt
	s_nop 0
	global_load_dwordx4 v[184:187], v[144:145], off offset:528 nt
	global_load_dwordx4 v[188:191], v[144:145], off offset:512 nt
	v_lshlrev_b64 v[144:145], 12, v[224:225]
	v_lshl_add_u64 v[144:145], v[166:167], 0, v[144:145]
	global_load_dwordx4 v[192:195], v[144:145], off nt
	global_load_dwordx4 v[196:199], v[144:145], off offset:16 nt
	global_load_dwordx4 v[200:203], v[144:145], off offset:512 nt
	global_load_dwordx4 v[204:207], v[144:145], off offset:528 nt
	v_or_b32_e32 v236, 32, v168
	v_ashrrev_i32_e32 v237, 31, v236
	v_lshlrev_b64 v[144:145], 12, v[236:237]
	v_lshl_add_u64 v[144:145], v[166:167], 0, v[144:145]
	global_load_dwordx4 v[208:211], v[144:145], off nt
	global_load_dwordx4 v[212:215], v[144:145], off offset:16 nt
	global_load_dwordx4 v[216:219], v[144:145], off offset:512 nt
	global_load_dwordx4 v[220:223], v[144:145], off offset:528 nt
	v_or_b32_e32 v238, 48, v168
	v_ashrrev_i32_e32 v239, 31, v238
	v_lshlrev_b64 v[144:145], 12, v[238:239]
	v_lshl_add_u64 v[144:145], v[166:167], 0, v[144:145]
	global_load_dwordx4 v[228:231], v[144:145], off nt
	global_load_dwordx4 v[232:235], v[144:145], off offset:16 nt
	global_load_dwordx4 v[148:151], v[144:145], off offset:512 nt
	s_nop 0
	global_load_dwordx4 v[144:147], v[144:145], off offset:528 nt
	v_lshlrev_b64 v[240:241], 11, v[168:169]
	v_lshlrev_b64 v[164:165], 1, v[164:165]
	v_lshl_add_u64 v[240:241], s[30:31], 0, v[240:241]
	v_lshlrev_b64 v[224:225], 11, v[224:225]
	v_lshl_add_u64 v[240:241], v[240:241], 0, v[164:165]
	v_lshl_add_u64 v[224:225], s[30:31], 0, v[224:225]
	v_lshlrev_b64 v[236:237], 11, v[236:237]
	v_lshl_add_u64 v[224:225], v[224:225], 0, v[164:165]
	v_lshl_add_u64 v[236:237], s[30:31], 0, v[236:237]
	v_lshl_add_u64 v[236:237], v[236:237], 0, v[164:165]
	s_andn2_b64 vcc, exec, s[0:1]
	s_mov_b64 s[0:1], -1
	s_waitcnt vmcnt(0)
	v_pk_fma_f32 v[122:123], v[122:123], v[138:139], v[178:179]
	v_pk_fma_f32 v[126:127], v[126:127], v[142:143], v[182:183]
	v_pk_fma_f32 v[124:125], v[124:125], v[140:141], v[180:181]
	v_pk_fma_f32 v[120:121], v[120:121], v[136:137], v[176:177]
	v_pk_fma_f32 v[110:111], v[110:111], v[134:135], v[190:191]
	v_pk_fma_f32 v[176:177], v[94:95], v[130:131], v[206:207]
	v_pk_fma_f32 v[178:179], v[92:93], v[128:129], v[204:205]
	v_cvt_pk_bf16_f32 v92, v124, v125
	v_cvt_pk_bf16_f32 v93, v126, v127
	v_cvt_pk_bf16_f32 v94, v120, v121
	v_cvt_pk_bf16_f32 v95, v122, v123
	v_pk_fma_f32 v[108:109], v[108:109], v[132:133], v[188:189]
	v_pk_fma_f32 v[106:107], v[106:107], v[130:131], v[186:187]
	v_pk_fma_f32 v[104:105], v[104:105], v[128:129], v[184:185]
	global_store_dwordx4 v[240:241], v[92:95], off
	v_pk_fma_f32 v[118:119], v[118:119], v[142:143], v[194:195]
	v_pk_fma_f32 v[116:117], v[116:117], v[140:141], v[192:193]
	v_cvt_pk_bf16_f32 v92, v108, v109
	v_cvt_pk_bf16_f32 v93, v110, v111
	v_cvt_pk_bf16_f32 v94, v104, v105
	v_cvt_pk_bf16_f32 v95, v106, v107
	v_pk_fma_f32 v[114:115], v[114:115], v[138:139], v[198:199]
	v_pk_fma_f32 v[112:113], v[112:113], v[136:137], v[196:197]
	global_store_dwordx4 v[240:241], v[92:95], off offset:256
	v_pk_fma_f32 v[102:103], v[102:103], v[134:135], v[202:203]
	v_pk_fma_f32 v[100:101], v[100:101], v[132:133], v[200:201]
	v_cvt_pk_bf16_f32 v92, v116, v117
	v_cvt_pk_bf16_f32 v93, v118, v119
	v_cvt_pk_bf16_f32 v94, v112, v113
	v_cvt_pk_bf16_f32 v95, v114, v115
	global_store_dwordx4 v[224:225], v[92:95], off
	v_pk_fma_f32 v[86:87], v[86:87], v[134:135], v[218:219]
	v_pk_fma_f32 v[84:85], v[84:85], v[132:133], v[216:217]
	v_cvt_pk_bf16_f32 v92, v100, v101
	v_cvt_pk_bf16_f32 v93, v102, v103
	v_cvt_pk_bf16_f32 v94, v178, v179
	v_cvt_pk_bf16_f32 v95, v176, v177
	global_store_dwordx4 v[224:225], v[92:95], off offset:256
	v_pk_fma_f32 v[80:81], v[80:81], v[140:141], v[228:229]
	v_pk_fma_f32 v[70:71], v[70:71], v[134:135], v[150:151]
	v_pk_fma_f32 v[92:93], v[98:99], v[142:143], v[210:211]
	v_pk_fma_f32 v[94:95], v[96:97], v[140:141], v[208:209]
	v_pk_fma_f32 v[96:97], v[90:91], v[138:139], v[214:215]
	v_pk_fma_f32 v[90:91], v[88:89], v[136:137], v[212:213]
	v_cvt_pk_bf16_f32 v88, v94, v95
	v_cvt_pk_bf16_f32 v89, v92, v93
	v_pk_fma_f32 v[68:69], v[68:69], v[132:133], v[148:149]
	v_cvt_pk_bf16_f32 v90, v90, v91
	v_cvt_pk_bf16_f32 v91, v96, v97
	global_store_dwordx4 v[236:237], v[88:91], off
	v_add_u32_e32 v148, 0xa0, v168
	v_ashrrev_i32_e32 v149, 31, v148
	v_pk_fma_f32 v[88:89], v[78:79], v[130:131], v[222:223]
	v_pk_fma_f32 v[78:79], v[76:77], v[128:129], v[220:221]
	v_cvt_pk_bf16_f32 v76, v84, v85
	v_cvt_pk_bf16_f32 v77, v86, v87
	v_lshlrev_b64 v[96:97], 12, v[148:149]
	v_cvt_pk_bf16_f32 v78, v78, v79
	v_cvt_pk_bf16_f32 v79, v88, v89
;     __device__ __forceinline__ void operator()(f32x4 (&acc)[2][2][4][2], const Unit& u, int wr, int wc, int fr, int fq, LAS unsigned char* lds) const {
;     ...
;         for (int ai = 0; ai < 2; ++ai) {
;             f32x4 xv[4][2][2];
; #pragma unroll
;             for (int m = 0; m < 4; ++m) {
;                 const size_t off = (size_t)(row0 + ai * HALF + m * 16) * 1024 + col0;
; #pragma unroll
;                 for (int bj = 0; bj < 2; ++bj)
; #pragma unroll
;                     for (int n = 0; n < 2; ++n) xv[m][bj][n] = *(const f32x4*)(base + off + bj * HALF + 4 * n);
;             }
; #pragma unroll
;             for (int m = 0; m < 4; ++m) {
;                 const size_t off = (size_t)(row0 + ai * HALF + m * 16) * 1024 + col0;
; #pragma unroll
;                 for (int bj = 0; bj < 2; ++bj) store8(out + off + bj * HALF, xv[m][bj][0] + gv[bj][0] * acc[ai][bj][m][0], xv[m][bj][1] + gv[bj][1] * acc[ai][bj][m][1]);
;             }
;             asm volatile("" ::: "memory");
	global_store_dwordx4 v[236:237], v[76:79], off offset:256
	v_lshl_add_u64 v[108:109], v[166:167], 0, v[96:97]
	v_add_u32_e32 v150, 0xb0, v168
	v_lshlrev_b64 v[76:77], 11, v[238:239]
	v_lshl_add_u64 v[76:77], s[30:31], 0, v[76:77]
	v_lshl_add_u64 v[76:77], v[76:77], 0, v[164:165]
	v_pk_fma_f32 v[78:79], v[82:83], v[142:143], v[230:231]
	v_pk_fma_f32 v[82:83], v[74:75], v[138:139], v[234:235]
	v_pk_fma_f32 v[74:75], v[72:73], v[136:137], v[232:233]
	v_cvt_pk_bf16_f32 v72, v80, v81
	v_cvt_pk_bf16_f32 v73, v78, v79
	v_ashrrev_i32_e32 v151, 31, v150
	v_cvt_pk_bf16_f32 v74, v74, v75
	v_cvt_pk_bf16_f32 v75, v82, v83
	global_store_dwordx4 v[76:77], v[72:75], off
	v_lshlrev_b64 v[112:113], 12, v[150:151]
	v_lshl_add_u64 v[124:125], v[166:167], 0, v[112:113]
	v_pk_fma_f32 v[72:73], v[66:67], v[130:131], v[146:147]
	v_pk_fma_f32 v[66:67], v[64:65], v[128:129], v[144:145]
	v_add_u32_e32 v144, 0x80, v168
	v_cvt_pk_bf16_f32 v64, v68, v69
	v_cvt_pk_bf16_f32 v65, v70, v71
	v_ashrrev_i32_e32 v145, 31, v144
	v_cvt_pk_bf16_f32 v66, v66, v67
	v_cvt_pk_bf16_f32 v67, v72, v73
	global_store_dwordx4 v[76:77], v[64:67], off offset:256
	v_add_u32_e32 v146, 0x90, v168
	v_ashrrev_i32_e32 v147, 31, v146
	v_lshlrev_b64 v[64:65], 12, v[144:145]
	v_lshl_add_u64 v[76:77], v[166:167], 0, v[64:65]
	global_load_dwordx4 v[64:67], v[76:77], off nt
	global_load_dwordx4 v[68:71], v[76:77], off offset:16 nt
	global_load_dwordx4 v[72:75], v[76:77], off offset:512 nt
	s_nop 0
	global_load_dwordx4 v[76:79], v[76:77], off offset:528 nt
	v_lshlrev_b64 v[80:81], 12, v[146:147]
	v_lshl_add_u64 v[92:93], v[166:167], 0, v[80:81]
	global_load_dwordx4 v[80:83], v[92:93], off nt
	global_load_dwordx4 v[84:87], v[92:93], off offset:16 nt
	global_load_dwordx4 v[88:91], v[92:93], off offset:512 nt
	s_nop 0
	global_load_dwordx4 v[92:95], v[92:93], off offset:528 nt
	s_nop 0
	global_load_dwordx4 v[96:99], v[108:109], off nt
	global_load_dwordx4 v[100:103], v[108:109], off offset:16 nt
	global_load_dwordx4 v[104:107], v[108:109], off offset:512 nt
	s_nop 0
	global_load_dwordx4 v[108:111], v[108:109], off offset:528 nt
	s_nop 0
	global_load_dwordx4 v[112:115], v[124:125], off nt
	global_load_dwordx4 v[116:119], v[124:125], off offset:16 nt
	global_load_dwordx4 v[120:123], v[124:125], off offset:512 nt
	s_nop 0
	global_load_dwordx4 v[124:127], v[124:125], off offset:528 nt
	v_lshlrev_b64 v[144:145], 11, v[144:145]
	v_lshl_add_u64 v[144:145], s[30:31], 0, v[144:145]
	v_lshl_add_u64 v[144:145], v[144:145], 0, v[164:165]
	s_waitcnt vmcnt(15)
	v_pk_fma_f32 v[62:63], v[62:63], v[142:143], v[66:67]
	v_pk_fma_f32 v[60:61], v[60:61], v[140:141], v[64:65]
	s_waitcnt vmcnt(14)
	v_pk_fma_f32 v[58:59], v[58:59], v[138:139], v[70:71]
	s_waitcnt vmcnt(12)
	v_pk_fma_f32 v[66:67], v[48:49], v[128:129], v[76:77]
	v_cvt_pk_bf16_f32 v48, v60, v61
	v_cvt_pk_bf16_f32 v49, v62, v63
	v_pk_fma_f32 v[56:57], v[56:57], v[136:137], v[68:69]
	v_pk_fma_f32 v[54:55], v[54:55], v[134:135], v[74:75]
	v_pk_fma_f32 v[52:53], v[52:53], v[132:133], v[72:73]
	v_pk_fma_f32 v[64:65], v[50:51], v[130:131], v[78:79]
	v_cvt_pk_bf16_f32 v50, v56, v57
	v_cvt_pk_bf16_f32 v51, v58, v59
	global_store_dwordx4 v[144:145], v[48:51], off
	s_waitcnt vmcnt(12)
	v_pk_fma_f32 v[46:47], v[46:47], v[142:143], v[82:83]
	v_pk_fma_f32 v[44:45], v[44:45], v[140:141], v[80:81]
	v_cvt_pk_bf16_f32 v48, v52, v53
	v_cvt_pk_bf16_f32 v49, v54, v55
	v_cvt_pk_bf16_f32 v50, v66, v67
	v_cvt_pk_bf16_f32 v51, v64, v65
	global_store_dwordx4 v[144:145], v[48:51], off offset:256
	s_waitcnt vmcnt(11)
	v_pk_fma_f32 v[38:39], v[38:39], v[134:135], v[90:91]
	v_pk_fma_f32 v[36:37], v[36:37], v[132:133], v[88:89]
	v_lshlrev_b64 v[48:49], 11, v[146:147]
	v_lshl_add_u64 v[48:49], s[30:31], 0, v[48:49]
	v_lshl_add_u64 v[48:49], v[48:49], 0, v[164:165]
	v_pk_fma_f32 v[50:51], v[42:43], v[138:139], v[86:87]
	v_pk_fma_f32 v[42:43], v[40:41], v[136:137], v[84:85]
	v_cvt_pk_bf16_f32 v40, v44, v45
	v_cvt_pk_bf16_f32 v41, v46, v47
	s_waitcnt vmcnt(9)
	v_pk_fma_f32 v[32:33], v[32:33], v[140:141], v[96:97]
	v_cvt_pk_bf16_f32 v42, v42, v43
	v_cvt_pk_bf16_f32 v43, v50, v51
	global_store_dwordx4 v[48:49], v[40:43], off
	s_waitcnt vmcnt(8)
	v_pk_fma_f32 v[22:23], v[22:23], v[134:135], v[106:107]
	v_pk_fma_f32 v[20:21], v[20:21], v[132:133], v[104:105]
	v_pk_fma_f32 v[40:41], v[30:31], v[130:131], v[94:95]
	v_pk_fma_f32 v[30:31], v[28:29], v[128:129], v[92:93]
	v_cvt_pk_bf16_f32 v28, v36, v37
	v_cvt_pk_bf16_f32 v29, v38, v39
	s_waitcnt vmcnt(6)
	v_pk_fma_f32 v[16:17], v[16:17], v[140:141], v[112:113]
	v_cvt_pk_bf16_f32 v30, v30, v31
	v_cvt_pk_bf16_f32 v31, v40, v41
	global_store_dwordx4 v[48:49], v[28:31], off offset:256
	s_waitcnt vmcnt(5)
	v_pk_fma_f32 v[6:7], v[6:7], v[134:135], v[122:123]
	v_pk_fma_f32 v[4:5], v[4:5], v[132:133], v[120:121]
	v_lshlrev_b64 v[28:29], 11, v[148:149]
	v_lshl_add_u64 v[28:29], s[30:31], 0, v[28:29]
	v_lshl_add_u64 v[28:29], v[28:29], 0, v[164:165]
	v_pk_fma_f32 v[30:31], v[34:35], v[142:143], v[98:99]
	v_pk_fma_f32 v[34:35], v[26:27], v[138:139], v[102:103]
	v_pk_fma_f32 v[26:27], v[24:25], v[136:137], v[100:101]
	v_cvt_pk_bf16_f32 v24, v32, v33
	v_cvt_pk_bf16_f32 v25, v30, v31
	s_nop 0
	v_cvt_pk_bf16_f32 v26, v26, v27
	v_cvt_pk_bf16_f32 v27, v34, v35
	global_store_dwordx4 v[28:29], v[24:27], off
	s_nop 1
	v_pk_fma_f32 v[24:25], v[14:15], v[130:131], v[110:111]
	v_pk_fma_f32 v[14:15], v[12:13], v[128:129], v[108:109]
	v_cvt_pk_bf16_f32 v12, v20, v21
	v_cvt_pk_bf16_f32 v13, v22, v23
	s_nop 0
	v_cvt_pk_bf16_f32 v14, v14, v15
	v_cvt_pk_bf16_f32 v15, v24, v25
	global_store_dwordx4 v[28:29], v[12:15], off offset:256
	s_nop 1
	v_lshlrev_b64 v[12:13], 11, v[150:151]
	v_lshl_add_u64 v[12:13], s[30:31], 0, v[12:13]
	v_lshl_add_u64 v[12:13], v[12:13], 0, v[164:165]
	v_pk_fma_f32 v[14:15], v[18:19], v[142:143], v[114:115]
	v_pk_fma_f32 v[18:19], v[10:11], v[138:139], v[118:119]
	v_pk_fma_f32 v[10:11], v[8:9], v[136:137], v[116:117]
	v_cvt_pk_bf16_f32 v8, v16, v17
	v_cvt_pk_bf16_f32 v9, v14, v15
	s_nop 0
	v_cvt_pk_bf16_f32 v10, v10, v11
	v_cvt_pk_bf16_f32 v11, v18, v19
	global_store_dwordx4 v[12:13], v[8:11], off
	s_waitcnt vmcnt(7)
	s_nop 0
	v_pk_fma_f32 v[8:9], v[2:3], v[130:131], v[126:127]
	v_pk_fma_f32 v[2:3], v[0:1], v[128:129], v[124:125]
	v_cvt_pk_bf16_f32 v0, v4, v5
	v_cvt_pk_bf16_f32 v1, v6, v7
	s_nop 0
	v_cvt_pk_bf16_f32 v2, v2, v3
	v_cvt_pk_bf16_f32 v3, v8, v9
	global_store_dwordx4 v[12:13], v[0:3], off offset:256
	s_cbranch_vccnz .LBB0_687
	s_andn2_b64 vcc, exec, s[8:9]
	s_cbranch_vccnz .LBB0_686
	s_barrier
	s_branch .LBB0_686

; __device__ __forceinline__ float bflo(unsigned w) { return __uint_as_float(w << 16); }
; __device__ __forceinline__ float bfhi(unsigned w) { return __uint_as_float(w & 0xffff0000u); }
; __device__ __forceinline__ void norm_phase_bf16(const bf16_t* x, const float* ng, const float* mod, bf16_t* Hh) {
;     ...
;     for (int m = m0; m < m1; m += 4) {
;         const int b = m / SEQ;
;         if (b != curb) { curb = b;
; #pragma unroll
;             for (int j = 0; j < 4; ++j) { const int col = 8 * lane + 512 * (j >> 1) + 4 * (j & 1);
;                 const f32x4 g = *(const f32x4*)(ng + col), sc = *(const f32x4*)(mod + b * 3072 + 1024 + col);
;                 ca[j] = g * (sc + 1.0f); cb[j] = *(const f32x4*)(mod + b * 3072 + col); } }
;         u32x4 v[4][2];
; #pragma unroll
;         for (int r = 0; r < 4; ++r) { const int mr = (m + r < m1) ? m + r : m; const u32x4* xr = (const u32x4*)(x + (size_t)mr * D) + lane; v[r][0] = xr[0]; v[r][1] = xr[64]; }
; #pragma unroll
;         for (int r = 0; r < 4; ++r) {
;             f32x4 f[4];
; #pragma unroll
;             for (int hh = 0; hh < 2; ++hh) { const u32x4 w = v[r][hh]; f[2 * hh] = (f32x4){bflo(w.x), bfhi(w.x), bflo(w.y), bfhi(w.y)}; f[2 * hh + 1] = (f32x4){bflo(w.z), bfhi(w.z), bflo(w.w), bfhi(w.w)}; }
;             float ss = 0.f;
; #pragma unroll
;             for (int j = 0; j < 4; ++j) ss += (f[j][0] * f[j][0] + f[j][1] * f[j][1]) + (f[j][2] * f[j][2] + f[j][3] * f[j][3]);
;             const float rstd = 1.0f / sqrtf(wave_sum(ss) * (1.0f / D) + EPS);
.LBB0_768:
	v_ashrrev_i32_e32 v32, 31, v52
	v_lshrrev_b32_e32 v32, 19, v32
	v_add_u32_e32 v32, v52, v32
	v_ashrrev_i32_e32 v32, 13, v32
	v_cmp_ne_u32_e32 vcc, v32, v67
	s_and_saveexec_b64 s[0:1], vcc
	s_cbranch_execz .LBB0_770
	v_mul_i32_i24_e32 v0, 0xc00, v32
	v_ashrrev_i32_e32 v1, 31, v0
	v_lshl_add_u64 v[0:1], v[0:1], 2, s[14:15]
	v_lshl_add_u64 v[2:3], v[0:1], 0, s[18:19]
	v_mov_b32_e32 v67, v55
	v_lshl_add_u64 v[4:5], v[2:3], 0, v[54:55]
	v_lshl_add_u64 v[2:3], v[2:3], 0, v[66:67]
	v_lshl_add_u64 v[8:9], v[0:1], 0, v[54:55]
	global_load_dwordx4 v[16:19], v[4:5], off nt
	global_load_dwordx4 v[20:23], v[4:5], off offset:16 nt
	global_load_dwordx4 v[24:27], v[2:3], off nt
	global_load_dwordx4 v[28:31], v[2:3], off offset:16 nt
	s_waitcnt lgkmcnt(0)
	global_load_dwordx4 v[34:37], v[60:61], off nt
	global_load_dwordx4 v[38:41], v[60:61], off offset:16 nt
	global_load_dwordx4 v[42:45], v[62:63], off offset:16 nt
	global_load_dwordx4 v[46:49], v[62:63], off nt
	global_load_dwordx4 v[4:7], v[8:9], off offset:16 nt
	global_load_dwordx4 v[0:3], v[8:9], off nt
	global_load_dwordx4 v[12:15], v[8:9], off offset:2064 nt
	s_nop 0
	global_load_dwordx4 v[8:11], v[8:9], off offset:2048 nt
	v_mov_b32_e32 v67, v32
	s_waitcnt vmcnt(9)
	v_pk_add_f32 v[26:27], v[26:27], 1.0 op_sel_hi:[1,0]
	v_pk_add_f32 v[24:25], v[24:25], 1.0 op_sel_hi:[1,0]
	s_waitcnt vmcnt(8)
	v_pk_add_f32 v[30:31], v[30:31], 1.0 op_sel_hi:[1,0]
	v_pk_add_f32 v[18:19], v[18:19], 1.0 op_sel_hi:[1,0]
	v_pk_add_f32 v[16:17], v[16:17], 1.0 op_sel_hi:[1,0]
	v_pk_add_f32 v[22:23], v[22:23], 1.0 op_sel_hi:[1,0]
	v_pk_add_f32 v[20:21], v[20:21], 1.0 op_sel_hi:[1,0]
	v_pk_add_f32 v[28:29], v[28:29], 1.0 op_sel_hi:[1,0]
	s_waitcnt vmcnt(7)
	v_pk_mul_f32 v[18:19], v[36:37], v[18:19]
	v_pk_mul_f32 v[16:17], v[34:35], v[16:17]
	s_waitcnt vmcnt(6)
	v_pk_mul_f32 v[22:23], v[40:41], v[22:23]
	v_pk_mul_f32 v[20:21], v[38:39], v[20:21]
	s_waitcnt vmcnt(4)
	v_pk_mul_f32 v[26:27], v[48:49], v[26:27]
	v_pk_mul_f32 v[24:25], v[46:47], v[24:25]
	v_pk_mul_f32 v[30:31], v[44:45], v[30:31]
	v_pk_mul_f32 v[28:29], v[42:43], v[28:29]
.LBB0_770:
	s_or_b64 exec, exec, s[0:1]
	global_load_dwordx4 v[82:85], v[64:65], off offset:1024 nt
	global_load_dwordx4 v[86:89], v[64:65], off nt
	v_add_u32_e32 v72, 1, v52
	v_cmp_lt_i32_e64 s[8:9], v72, v100
	v_add_u32_e32 v70, 2, v52
	v_add_u32_e32 v68, 3, v52
	v_cndmask_b32_e64 v32, v52, v72, s[8:9]
	v_ashrrev_i32_e32 v33, 31, v32
	v_lshlrev_b64 v[32:33], 11, v[32:33]
	v_lshl_add_u64 v[32:33], v[56:57], 0, v[32:33]
	global_load_dwordx4 v[92:95], v[32:33], off nt
	global_load_dwordx4 v[48:51], v[32:33], off offset:1024 nt
	v_cmp_lt_i32_e64 s[4:5], v70, v100
	v_cmp_lt_i32_e64 s[0:1], v68, v100
	s_waitcnt vmcnt(3)
	v_lshlrev_b32_e32 v74, 16, v84
	v_and_b32_e32 v69, 0xffff0000, v84
	s_waitcnt vmcnt(2)
	v_lshlrev_b32_e32 v80, 16, v86
	v_lshlrev_b32_e32 v84, 16, v87
	v_lshlrev_b32_e32 v76, 16, v85
	v_and_b32_e32 v77, 0xffff0000, v85
	v_and_b32_e32 v81, 0xffff0000, v86
	v_and_b32_e32 v85, 0xffff0000, v87
	v_lshlrev_b32_e32 v90, 16, v88
	v_and_b32_e32 v87, 0xffff0000, v89
	v_and_b32_e32 v86, 0xffff0000, v88
	v_mul_f32_e32 v88, v80, v80
	v_mul_f32_e32 v96, v84, v84
	v_lshlrev_b32_e32 v91, 16, v89
	v_lshlrev_b32_e32 v78, 16, v82
	v_and_b32_e32 v79, 0xffff0000, v82
	v_lshlrev_b32_e32 v82, 16, v83
	v_pk_mul_f32 v[98:99], v[86:87], v[86:87]
	v_pk_fma_f32 v[88:89], v[80:81], v[80:81], v[88:89] op_sel_hi:[1,1,0]
	v_pk_fma_f32 v[96:97], v[84:85], v[84:85], v[96:97] op_sel_hi:[1,1,0]
	v_and_b32_e32 v83, 0xffff0000, v83
	v_mul_f32_e32 v108, v78, v78
	v_mul_f32_e32 v110, v82, v82
	v_mov_b32_e32 v112, v74
	v_mov_b32_e32 v114, v90
	v_mov_b32_e32 v115, v86
	v_mov_b32_e32 v86, v91
	v_pk_fma_f32 v[90:91], v[90:91], v[90:91], v[98:99]
	v_mov_b32_e32 v75, v89
	v_mov_b32_e32 v113, v97
	v_pk_fma_f32 v[98:99], v[78:79], v[78:79], v[108:109] op_sel_hi:[1,1,0]
	v_pk_fma_f32 v[108:109], v[82:83], v[82:83], v[110:111] op_sel_hi:[1,1,0]
	v_pk_add_f32 v[90:91], v[90:91], v[90:91] op_sel_hi:[0,1]
	v_pk_add_f32 v[88:89], v[88:89], v[96:97]
	v_pk_mul_f32 v[110:111], v[74:75], v[112:113]
	v_mul_f32_e32 v98, v76, v76
	v_mul_f32_e32 v108, v77, v77
	v_mul_f32_e32 v90, v69, v69
	v_mov_b32_e32 v111, v89
	v_pk_add_f32 v[108:109], v[98:99], v[108:109]
	v_pk_add_f32 v[88:89], v[110:111], v[90:91]
	v_cndmask_b32_e64 v32, v52, v70, s[4:5]
	v_pk_add_f32 v[88:89], v[88:89], v[108:109]
	v_cndmask_b32_e64 v34, v52, v68, s[0:1]
	v_add_f32_e32 v71, v88, v89
	ds_bpermute_b32 v73, v101, v71
	v_ashrrev_i32_e32 v33, 31, v32
	s_waitcnt lgkmcnt(1)
	v_ashrrev_i32_e32 v35, 31, v34
	v_lshlrev_b64 v[32:33], 11, v[32:33]
	v_lshlrev_b64 v[34:35], 11, v[34:35]
	s_waitcnt lgkmcnt(0)
	v_add_f32_e32 v71, v71, v73
	ds_bpermute_b32 v73, v102, v71
	v_lshl_add_u64 v[32:33], v[56:57], 0, v[32:33]
	v_lshl_add_u64 v[34:35], v[56:57], 0, v[34:35]
	global_load_dwordx4 v[44:47], v[32:33], off nt
	global_load_dwordx4 v[40:43], v[32:33], off offset:1024 nt
	global_load_dwordx4 v[36:39], v[34:35], off nt
	s_nop 0
	global_load_dwordx4 v[32:35], v[34:35], off offset:1024 nt
	s_waitcnt vmcnt(5)
	v_lshlrev_b32_e32 v98, 16, v92
	s_waitcnt lgkmcnt(0)
	v_add_f32_e32 v71, v71, v73
	ds_bpermute_b32 v73, v103, v71
	v_and_b32_e32 v99, 0xffff0000, v92
	v_lshlrev_b32_e32 v96, 16, v93
	v_and_b32_e32 v97, 0xffff0000, v93
	v_lshlrev_b32_e32 v92, 16, v94
	s_waitcnt lgkmcnt(0)
	v_add_f32_e32 v71, v71, v73
	ds_bpermute_b32 v73, v104, v71
	v_and_b32_e32 v93, 0xffff0000, v94
	v_lshlrev_b32_e32 v94, 16, v95
	v_and_b32_e32 v95, 0xffff0000, v95
	v_mul_f32_e32 v75, v99, v99
	s_waitcnt lgkmcnt(0)
	v_add_f32_e32 v71, v71, v73
	ds_bpermute_b32 v73, v105, v71
	v_mul_f32_e32 v108, v97, v97
	v_mul_f32_e32 v109, v93, v93
	v_mul_f32_e32 v110, v95, v95
	s_waitcnt vmcnt(4)
; __device__ __forceinline__ unsigned cvt_pk_bf16(float lo, float hi) { unsigned r; asm volatile("v_cvt_pk_bf16_f32 %0, %1, %2" : "=v"(r) : "v"(lo), "v"(hi)); return r; }
; __device__ __forceinline__ float bflo(unsigned w) { return __uint_as_float(w << 16); }
; __device__ __forceinline__ float bfhi(unsigned w) { return __uint_as_float(w & 0xffff0000u); }
; __device__ __forceinline__ void norm_phase_bf16(const bf16_t* x, const float* ng, const float* mod, bf16_t* Hh) {
;     ...
;         for (int r = 0; r < 4; ++r) {
;             f32x4 f[4];
; #pragma unroll
;             for (int hh = 0; hh < 2; ++hh) { const u32x4 w = v[r][hh]; f[2 * hh] = (f32x4){bflo(w.x), bfhi(w.x), bflo(w.y), bfhi(w.y)}; f[2 * hh + 1] = (f32x4){bflo(w.z), bfhi(w.z), bflo(w.w), bfhi(w.w)}; }
;             float ss = 0.f;
; #pragma unroll
;             for (int j = 0; j < 4; ++j) ss += (f[j][0] * f[j][0] + f[j][1] * f[j][1]) + (f[j][2] * f[j][2] + f[j][3] * f[j][3]);
;             const float rstd = 1.0f / sqrtf(wave_sum(ss) * (1.0f / D) + EPS);
;             if (m + r < m1) {
;                 u32x4* o16 = (u32x4*)(Hh + (size_t)(m + r) * D) + lane;
; #pragma unroll
;                 for (int hh = 0; hh < 2; ++hh) { const f32x4 h0 = f[2 * hh] * rstd * ca[2 * hh] + cb[2 * hh], h1 = f[2 * hh + 1] * rstd * ca[2 * hh + 1] + cb[2 * hh + 1];
;                     u32x4 w; w.x = cvt_pk_bf16(h0[0], h0[1]); w.y = cvt_pk_bf16(h0[2], h0[3]); w.z = cvt_pk_bf16(h1[0], h1[1]); w.w = cvt_pk_bf16(h1[2], h1[3]); o16[64 * hh] = w; }
;             }
	v_and_b32_e32 v89, 0xffff0000, v48
	s_waitcnt lgkmcnt(0)
	v_add_f32_e32 v71, v71, v73
	ds_bpermute_b32 v73, v106, v71
	v_and_b32_e32 v91, 0xffff0000, v49
	v_fmac_f32_e32 v75, v98, v98
	v_fmac_f32_e32 v108, v96, v96
	v_fmac_f32_e32 v109, v92, v92
	s_waitcnt lgkmcnt(0)
	v_add_f32_e32 v71, v71, v73
	v_fmamk_f32 v71, v71, 0x3a800000, v53
	v_mul_f32_e32 v73, 0x4f800000, v71
	v_cmp_gt_f32_e32 vcc, s6, v71
	v_fmac_f32_e32 v110, v94, v94
	v_lshlrev_b32_e32 v88, 16, v48
	v_cndmask_b32_e32 v71, v71, v73, vcc
	v_sqrt_f32_e32 v73, v71
	v_lshlrev_b32_e32 v90, 16, v49
	v_mul_f32_e32 v111, v89, v89
	v_mul_f32_e32 v112, v91, v91
	v_add_f32_e32 v75, v75, v108
	v_add_f32_e32 v108, v109, v110
	v_fmac_f32_e32 v111, v88, v88
	v_fmac_f32_e32 v112, v90, v90
	v_add_f32_e32 v75, v75, v108
	v_add_u32_e32 v108, -1, v73
	v_add_f32_e32 v109, v111, v112
	v_add_u32_e32 v110, 1, v73
	v_fma_f32 v111, -v108, v73, v71
	v_fma_f32 v112, -v110, v73, v71
	v_cmp_ge_f32_e64 s[10:11], 0, v111
	v_add_f32_e32 v75, v75, v109
	v_lshlrev_b32_e32 v48, 16, v50
	v_cndmask_b32_e64 v73, v73, v108, s[10:11]
	v_cmp_lt_f32_e64 s[10:11], 0, v112
	v_and_b32_e32 v49, 0xffff0000, v50
	v_lshlrev_b32_e32 v50, 16, v51
	v_cndmask_b32_e64 v73, v73, v110, s[10:11]
	v_mul_f32_e32 v108, 0x37800000, v73
	v_cndmask_b32_e32 v73, v73, v108, vcc
	v_cmp_class_f32_e32 vcc, v71, v107
	v_and_b32_e32 v51, 0xffff0000, v51
	v_mul_f32_e32 v116, v49, v49
	v_cndmask_b32_e32 v71, v73, v71, vcc
	v_div_scale_f32 v73, s[10:11], v71, v71, 1.0
	v_rcp_f32_e32 v108, v73
	v_div_scale_f32 v109, vcc, 1.0, v71, 1.0
	v_fmac_f32_e32 v116, v48, v48
	v_fma_f32 v110, -v73, v108, 1.0
	v_fmac_f32_e32 v108, v110, v108
	v_mul_f32_e32 v110, v109, v108
	v_fma_f32 v111, -v73, v110, v109
	v_fmac_f32_e32 v110, v111, v108
	v_fma_f32 v73, -v73, v110, v109
	v_div_fmas_f32 v73, v73, v108, v110
	v_div_fixup_f32 v108, v73, v71, 1.0
	v_mul_f32_e32 v71, v51, v51
	v_fmac_f32_e32 v71, v50, v50
	v_add_f32_e32 v71, v116, v71
	v_add_f32_e32 v71, v71, v75
	ds_bpermute_b32 v73, v101, v71
	v_mov_b32_e32 v75, v69
	v_pk_mul_f32 v[80:81], v[108:109], v[80:81] op_sel_hi:[0,1]
	v_pk_mul_f32 v[84:85], v[108:109], v[84:85] op_sel_hi:[0,1]
	v_pk_fma_f32 v[80:81], v[16:17], v[80:81], v[0:1]
	s_waitcnt lgkmcnt(0)
	v_add_f32_e32 v71, v71, v73
	ds_bpermute_b32 v73, v102, v71
	v_pk_mul_f32 v[110:111], v[108:109], v[114:115] op_sel_hi:[0,1]
	v_pk_mul_f32 v[86:87], v[108:109], v[86:87] op_sel_hi:[0,1]
	v_pk_fma_f32 v[112:113], v[18:19], v[84:85], v[2:3]
	v_cvt_pk_bf16_f32 v84, v80, v81
	s_waitcnt lgkmcnt(0)
	v_add_f32_e32 v71, v71, v73
	ds_bpermute_b32 v73, v103, v71
	v_add_co_u32_e32 v80, vcc, s7, v64
	v_pk_mul_f32 v[78:79], v[108:109], v[78:79] op_sel_hi:[0,1]
	v_pk_fma_f32 v[114:115], v[22:23], v[86:87], v[6:7]
	s_waitcnt lgkmcnt(0)
	v_add_f32_e32 v69, v71, v73
	ds_bpermute_b32 v71, v104, v69
	v_pk_fma_f32 v[86:87], v[20:21], v[110:111], v[4:5]
	v_addc_co_u32_e32 v81, vcc, -1, v65, vcc
	v_pk_fma_f32 v[78:79], v[24:25], v[78:79], v[8:9]
	s_waitcnt lgkmcnt(0)
	v_add_f32_e32 v69, v69, v71
	ds_bpermute_b32 v71, v105, v69
	v_pk_mul_f32 v[74:75], v[74:75], v[108:109] op_sel_hi:[1,0]
	v_pk_mul_f32 v[76:77], v[76:77], v[108:109] op_sel_hi:[1,0]
	v_cvt_pk_bf16_f32 v85, v112, v113
	v_cvt_pk_bf16_f32 v86, v86, v87
	s_waitcnt lgkmcnt(0)
	v_add_f32_e32 v69, v69, v71
	ds_bpermute_b32 v71, v106, v69
	v_cvt_pk_bf16_f32 v87, v114, v115
	global_store_dwordx4 v[80:81], v[84:87], off
	v_pk_mul_f32 v[80:81], v[108:109], v[82:83] op_sel_hi:[0,1]
	v_pk_fma_f32 v[82:83], v[30:31], v[76:77], v[14:15]
	v_pk_fma_f32 v[76:77], v[28:29], v[74:75], v[12:13]
	v_cvt_pk_bf16_f32 v74, v78, v79
	v_add_co_u32_e32 v78, vcc, s22, v64
	v_pk_fma_f32 v[80:81], v[26:27], v[80:81], v[10:11]
	s_nop 0
	v_addc_co_u32_e32 v79, vcc, -1, v65, vcc
	v_cvt_pk_bf16_f32 v75, v80, v81
	v_cvt_pk_bf16_f32 v76, v76, v77
	v_cvt_pk_bf16_f32 v77, v82, v83
	global_store_dwordx4 v[78:79], v[74:77], off offset:-3072
	s_and_saveexec_b64 s[10:11], s[8:9]
	s_cbranch_execz .LBB0_772
	s_waitcnt lgkmcnt(0)
	v_add_f32_e32 v69, v69, v71
	v_fmamk_f32 v69, v69, 0x3a800000, v53
	v_mul_f32_e32 v71, 0x4f800000, v69
	v_cmp_gt_f32_e32 vcc, s6, v69
	s_nop 1
	v_cndmask_b32_e32 v69, v69, v71, vcc
	v_sqrt_f32_e32 v71, v69
	s_nop 0
	v_add_u32_e32 v73, -1, v71
	v_fma_f32 v75, -v73, v71, v69
	v_add_u32_e32 v74, 1, v71
	v_cmp_ge_f32_e64 s[8:9], 0, v75
	s_nop 1
	v_cndmask_b32_e64 v73, v71, v73, s[8:9]
	v_fma_f32 v71, -v74, v71, v69
	v_cmp_lt_f32_e64 s[8:9], 0, v71
	s_nop 1
	v_cndmask_b32_e64 v71, v73, v74, s[8:9]
	v_mul_f32_e32 v73, 0x37800000, v71
	v_cndmask_b32_e32 v71, v71, v73, vcc
	v_cmp_class_f32_e32 vcc, v69, v107
	s_nop 1
	v_cndmask_b32_e32 v69, v71, v69, vcc
	v_div_scale_f32 v71, s[8:9], v69, v69, 1.0
	v_rcp_f32_e32 v73, v71
	s_nop 0
	v_fma_f32 v74, -v71, v73, 1.0
	v_fmac_f32_e32 v73, v74, v73
	v_div_scale_f32 v74, vcc, 1.0, v69, 1.0
	v_mul_f32_e32 v75, v74, v73
	v_fma_f32 v76, -v71, v75, v74
	v_fmac_f32_e32 v75, v76, v73
	v_fma_f32 v71, -v71, v75, v74
	v_div_fmas_f32 v71, v71, v73, v75
	v_ashrrev_i32_e32 v73, 31, v72
	v_div_fixup_f32 v76, v71, v69, 1.0
	v_lshlrev_b64 v[72:73], 11, v[72:73]
	v_lshl_add_u64 v[78:79], v[58:59], 0, v[72:73]
	v_pk_mul_f32 v[72:73], v[98:99], v[76:77] op_sel_hi:[1,0]
	v_pk_mul_f32 v[74:75], v[96:97], v[76:77] op_sel_hi:[1,0]
	v_pk_fma_f32 v[72:73], v[16:17], v[72:73], v[0:1]
	v_pk_fma_f32 v[74:75], v[18:19], v[74:75], v[2:3]
	v_pk_mul_f32 v[80:81], v[92:93], v[76:77] op_sel_hi:[1,0]
	v_pk_mul_f32 v[82:83], v[94:95], v[76:77] op_sel_hi:[1,0]
	v_pk_fma_f32 v[80:81], v[20:21], v[80:81], v[4:5]
	v_pk_fma_f32 v[82:83], v[22:23], v[82:83], v[6:7]
	v_cvt_pk_bf16_f32 v72, v72, v73
	v_cvt_pk_bf16_f32 v73, v74, v75
	v_cvt_pk_bf16_f32 v74, v80, v81
	v_pk_mul_f32 v[48:49], v[48:49], v[76:77] op_sel_hi:[1,0]
	v_cvt_pk_bf16_f32 v75, v82, v83
	v_pk_mul_f32 v[50:51], v[50:51], v[76:77] op_sel_hi:[1,0]
	global_store_dwordx4 v[78:79], v[72:75], off
	s_nop 1
	v_pk_mul_f32 v[72:73], v[88:89], v[76:77] op_sel_hi:[1,0]
	v_pk_mul_f32 v[74:75], v[90:91], v[76:77] op_sel_hi:[1,0]
	v_pk_fma_f32 v[76:77], v[30:31], v[50:51], v[14:15]
	v_pk_fma_f32 v[50:51], v[28:29], v[48:49], v[12:13]
	v_pk_fma_f32 v[74:75], v[26:27], v[74:75], v[10:11]
	v_pk_fma_f32 v[72:73], v[24:25], v[72:73], v[8:9]
	s_nop 0
	v_cvt_pk_bf16_f32 v48, v72, v73
	v_cvt_pk_bf16_f32 v49, v74, v75
	v_cvt_pk_bf16_f32 v50, v50, v51
	v_cvt_pk_bf16_f32 v51, v76, v77
	global_store_dwordx4 v[78:79], v[48:51], off offset:1024

; __device__ __forceinline__ unsigned f2bf(float f) { unsigned u = __float_as_uint(f); return (u + 0x7fffu + ((u >> 16) & 1u)) >> 16; }
; template <bool PASSB>
; __device__ __forceinline__ void s5_phase(LAS unsigned char* lds, const Params& p) {
;     ...
;         if (g != curg) { curg = g;
; #pragma unroll
;             for (int nb = 0; nb < 8; ++nb) bfm[nb] = (fq < 2) ? *(const bf16x8*)((const bf16_t*)(ws + WS_BBM) + ((size_t)g * 128 + nb * 16 + fr) * 16 + fq * 8) : zero8;
;             if (PASSB) {
; #pragma unroll
;                 for (int ks = 0; ks < 4; ++ks) cfm[ks] = *(const bf16x8*)((const bf16_t*)(ws + WS_CM) + ((size_t)g * 16 + fr) * 128 + ks * 32 + fq * 8);
;                 const unsigned dbits = f2bf(p.in[24][g * 16 + fr]);
;                 dfm = zero8;
; #pragma unroll
;                 for (int i = 0; i < 8; ++i) if (fq < 2 && fq * 8 + i == fr) dfm[i] = (short)dbits;
;             }
;             const f32x2 a = *(const f32x2*)((const float*)(ws + WS_ABAR) + (g * 64 + lane) * 2); are = a[0]; aim = a[1];
;             const f32x2 al = *(const f32x2*)((const float*)(ws + WS_ABARL) + (g * 64 + lane) * 2); alre = al[0]; alim = al[1];
.LBB0_1062:
	v_and_b32_e32 v93, 63, v102
	v_cmp_ne_u32_e64 s[24:25], v93, v111
	s_and_saveexec_b64 s[66:67], s[24:25]
	s_cbranch_execz .LBB0_1082
	v_lshlrev_b32_e32 v1, 1, v104
	v_mov_b32_e32 v4, 0
	v_lshl_or_b32 v2, v93, 12, v1
	v_mov_b32_e32 v8, 0
	v_mov_b32_e32 v9, 0
	v_mov_b32_e32 v10, 0
	v_mov_b32_e32 v11, 0
	s_and_saveexec_b64 s[24:25], vcc
	s_cbranch_execz .LBB0_1065
	v_mov_b32_e32 v3, v0
	v_lshl_add_u64 v[6:7], v[74:75], 0, v[2:3]
	global_load_dwordx4 v[8:11], v[6:7], off nt
.LBB0_1065:
	s_or_b64 exec, exec, s[24:25]
	v_mov_b32_e32 v5, 0
	v_mov_b32_e32 v6, 0
	v_mov_b32_e32 v7, 0
	s_and_saveexec_b64 s[24:25], vcc
	s_cbranch_execz .LBB0_1067
	v_mov_b32_e32 v3, v0
	v_lshl_add_u64 v[4:5], v[74:75], 0, v[2:3]
	global_load_dwordx4 v[4:7], v[4:5], off offset:512 nt
.LBB0_1067:
	s_or_b64 exec, exec, s[24:25]
	v_mov_b32_e32 v12, 0
	v_mov_b32_e32 v16, 0
	v_mov_b32_e32 v17, 0
	v_mov_b32_e32 v18, 0
	v_mov_b32_e32 v19, 0
	s_and_saveexec_b64 s[24:25], vcc
	s_cbranch_execz .LBB0_1069
	v_mov_b32_e32 v3, v0
	v_lshl_add_u64 v[14:15], v[74:75], 0, v[2:3]
	global_load_dwordx4 v[16:19], v[14:15], off offset:1024 nt
.LBB0_1069:
	s_or_b64 exec, exec, s[24:25]
	v_mov_b32_e32 v13, 0
	v_mov_b32_e32 v14, 0
	v_mov_b32_e32 v15, 0
	s_and_saveexec_b64 s[24:25], vcc
	s_cbranch_execz .LBB0_1071
	v_mov_b32_e32 v3, v0
	v_lshl_add_u64 v[12:13], v[74:75], 0, v[2:3]
	global_load_dwordx4 v[12:15], v[12:13], off offset:1536 nt
.LBB0_1071:
	s_or_b64 exec, exec, s[24:25]
	v_mov_b32_e32 v20, 0
	v_mov_b32_e32 v21, 0
	v_mov_b32_e32 v22, 0
	v_mov_b32_e32 v23, 0
	s_and_saveexec_b64 s[24:25], vcc
	s_cbranch_execz .LBB0_1073
	v_mov_b32_e32 v3, v0
	v_lshl_add_u64 v[2:3], v[74:75], 0, v[2:3]
	global_load_dwordx4 v[20:23], v[2:3], off offset:2048 nt
.LBB0_1073:
	s_or_b64 exec, exec, s[24:25]
	v_lshlrev_b32_e32 v1, 11, v93
	s_and_saveexec_b64 s[24:25], s[0:1]
	s_xor_b64 s[24:25], exec, s[24:25]
	v_lshlrev_b32_e32 v1, 11, v93
	s_or_saveexec_b64 s[24:25], s[24:25]
	v_mov_b32_e32 v28, 0
	v_mov_b32_e32 v24, 0
	v_mov_b32_e32 v25, 0
	v_mov_b32_e32 v26, 0
	v_mov_b32_e32 v27, 0
	s_xor_b64 exec, exec, s[24:25]
	s_cbranch_execz .LBB0_1077
	v_or_b32_e32 v2, v1, v104
	v_lshlrev_b32_e32 v2, 1, v2
	v_mov_b32_e32 v3, v0
	v_lshl_add_u64 v[2:3], v[74:75], 0, v[2:3]
	global_load_dwordx4 v[24:27], v[2:3], off offset:2560 nt
.LBB0_1077:
	s_or_b64 exec, exec, s[24:25]
	v_or_b32_e32 v2, v1, v104
	v_mov_b32_e32 v29, 0
	v_mov_b32_e32 v30, 0
	v_mov_b32_e32 v31, 0
	s_and_saveexec_b64 s[24:25], vcc
	s_cbranch_execz .LBB0_1079
	v_mov_b32_e32 v3, v0
	v_lshl_add_u64 v[28:29], v[2:3], 1, v[74:75]
	global_load_dwordx4 v[28:31], v[28:29], off offset:3072 nt
.LBB0_1079:
	s_or_b64 exec, exec, s[24:25]
	v_mov_b32_e32 v32, 0
	v_mov_b32_e32 v33, 0
	v_mov_b32_e32 v34, 0
	v_mov_b32_e32 v35, 0
	s_and_saveexec_b64 s[24:25], vcc
	s_cbranch_execz .LBB0_1081
	v_mov_b32_e32 v3, v0
	v_lshl_add_u64 v[2:3], v[2:3], 1, v[74:75]
	global_load_dwordx4 v[32:35], v[2:3], off offset:3584 nt
.LBB0_1081:
	s_or_b64 exec, exec, s[24:25]
	v_lshlrev_b32_e32 v2, 2, v72
	v_readlane_b32 s68, v248, 0
	v_lshl_or_b32 v2, v93, 6, v2
	v_readlane_b32 s69, v248, 1
	v_mov_b32_e32 v3, v0
	v_mov_b32_e32 v111, v93
	v_readlane_b32 s70, v248, 2
	v_readlane_b32 s71, v248, 3
	v_readlane_b32 s72, v248, 4
	global_load_dword v52, v2, s[68:69]
	v_or_b32_e32 v2, v1, v103
	v_lshl_or_b32 v1, v93, 9, v106
	v_lshl_add_u64 v[2:3], v[2:3], 1, v[76:77]
	global_load_dwordx2 v[88:89], v1, s[40:41]
	global_load_dwordx2 v[90:91], v1, s[46:47]
	global_load_dwordx4 v[36:39], v[2:3], off nt
	global_load_dwordx4 v[40:43], v[2:3], off offset:64 nt
	global_load_dwordx4 v[44:47], v[2:3], off offset:128 nt
	global_load_dwordx4 v[48:51], v[2:3], off offset:192 nt
	v_readlane_b32 s73, v248, 5
	v_readlane_b32 s74, v248, 6
	v_readlane_b32 s75, v248, 7
	s_waitcnt vmcnt(5)
	v_mov_b32_e32 v92, v89
	v_bfe_u32 v1, v52, 16, 1
	v_add3_u32 v1, v52, v1, s6
	v_alignbit_b32 v2, 0, v1, 16
	v_cndmask_b32_e64 v3, 0, v2, s[4:5]
	v_cndmask_b32_e64 v53, 0, v2, s[10:11]
	v_cndmask_b32_e64 v54, 0, v2, s[14:15]
	v_cndmask_b32_e64 v2, 0, v2, s[18:19]
	v_bfi_b32 v52, s7, v3, v1
	v_bfi_b32 v55, s7, v53, v1
	v_bfi_b32 v56, s7, v54, v1
	v_bfi_b32 v1, s7, v2, v1
	v_cndmask_b32_e64 v52, v3, v52, s[8:9]
	v_cndmask_b32_e64 v53, v53, v55, s[12:13]
	v_cndmask_b32_e64 v54, v54, v56, s[16:17]
	v_cndmask_b32_e64 v55, v2, v1, s[20:21]

; template <bool PASSB>
; __device__ __forceinline__ void s5_phase(LAS unsigned char* lds, const Params& p) {
;     ...
;         float hr = 0.f, hi = 0.f;
;         if (PASSB) {
;             for (int j0 = 0; j0 < c; j0 += 8) {
;                 f32x2 e[8];
; #pragma unroll
;                 for (int i = 0; i < 8; ++i) { const int jj = (j0 + i < c) ? j0 + i : c - 1; e[i] = *(const f32x2*)(AGG + ((size_t)((b * S5_NC + jj) * 64 + g) * 64 + lane) * 2); }
; #pragma unroll
;                 for (int i = 0; i < 8; ++i) if (j0 + i < c) { const float nr = alre * hr - alim * hi + e[i][0], ni = alre * hi + alim * hr + e[i][1]; hr = nr; hi = ni; }
;             }
;         }
;         const size_t row0 = (size_t)b * SEQ + (size_t)c * S5_LC;
;         const bf16_t* up = U + ((size_t)g * T + row0 + fr) * 16 + (fq & 1) * 8;
;         bf16x8 au_q0 = (fq < 2) ? *(const bf16x8*)up : zero8;
;         bf16x8 au_q1 = (fq < 2) ? *(const bf16x8*)(up + (size_t)1 * 16 * 16) : zero8;
;         bf16x8 au_q2 = (fq < 2) ? *(const bf16x8*)(up + (size_t)2 * 16 * 16) : zero8;
.LBB0_1086:
	s_or_b64 exec, exec, s[66:67]
	v_ashrrev_i32_e32 v57, 31, v56
	v_ashrrev_i32_e32 v3, 31, v2
	v_lshlrev_b64 v[64:65], 13, v[56:57]
	v_lshlrev_b64 v[66:67], 9, v[2:3]
	v_lshl_add_u64 v[96:97], v[66:67], 0, v[64:65]
	v_lshlrev_b32_e32 v2, 15, v93
	v_mov_b32_e32 v3, v0
	v_lshl_add_u64 v[2:3], v[96:97], 0, v[2:3]
	v_or_b32_e32 v2, v2, v72
	v_mov_b32_e32 v58, v0
	v_mov_b32_e32 v59, v0
	v_lshlrev_b64 v[2:3], 5, v[2:3]
	v_mov_b32_e32 v56, 0
	v_mov_b32_e32 v57, v0
	v_mov_b64_e32 v[70:71], v[58:59]
	v_lshl_add_u64 v[98:99], v[80:81], 0, v[2:3]
	v_mov_b64_e32 v[68:69], v[56:57]
	s_and_saveexec_b64 s[24:25], vcc
	s_cbranch_execz .LBB0_1088
	global_load_dwordx4 v[68:71], v[98:99], off nt
.LBB0_1088:
	s_or_b64 exec, exec, s[24:25]
	s_and_saveexec_b64 s[24:25], vcc
	s_cbranch_execz .LBB0_1090
	global_load_dwordx4 v[56:59], v[98:99], off offset:512 nt
.LBB0_1090:
	s_or_b64 exec, exec, s[24:25]
	v_mov_b32_e32 v2, v0
	v_mov_b32_e32 v3, v0
	v_mov_b32_e32 v1, v0
	s_waitcnt vmcnt(4)
	v_mov_b64_e32 v[62:63], v[2:3]
	v_mov_b64_e32 v[60:61], v[0:1]
	s_and_saveexec_b64 s[24:25], vcc
	s_cbranch_execz .LBB0_1092
	global_load_dwordx4 v[60:63], v[98:99], off offset:1024 nt

; template <bool PASSB>
; __device__ __forceinline__ void s5_phase(LAS unsigned char* lds, const Params& p) {
;     ...
;         for (int st = 0; st < NST; ++st) {
;             const size_t r0 = row0 + st * 16;
;             const bf16x8 au = au_q0; au_q0 = au_q1; au_q1 = au_q2;
;             if (st + 3 < NST) au_q2 = (fq < 2) ? *(const bf16x8*)(up + (size_t)(st + 3) * 16 * 16) : zero8;
.LBB0_1094:
	s_waitcnt vmcnt(0)
	v_mov_b64_e32 v[66:67], v[58:59]
	v_mov_b64_e32 v[64:65], v[56:57]
	v_mov_b64_e32 v[56:57], v[60:61]
	s_cmp_gt_u32 s23, 28
	v_mov_b64_e32 v[58:59], v[62:63]
	s_cselect_b64 s[24:25], -1, 0
	v_cndmask_b32_e64 v63, 0, v59, s[24:25]
	s_nor_b64 s[28:29], s[0:1], s[24:25]
	v_cndmask_b32_e64 v62, 0, v58, s[24:25]
	v_cndmask_b32_e64 v61, 0, v57, s[24:25]
	v_cndmask_b32_e64 v60, 0, v56, s[24:25]
	s_and_saveexec_b64 s[24:25], s[28:29]
	s_cbranch_execz .LBB0_1093
	global_load_dwordx4 v[60:63], v[98:99], off nt
	s_branch .LBB0_1093

; #define LAS __attribute__((address_space(3)))
; __device__ __forceinline__ float bflo(unsigned w) { return __uint_as_float(w << 16); }
; __device__ __forceinline__ float bfhi(unsigned w) { return __uint_as_float(w & 0xffff0000u); }
; __device__ __forceinline__ float sigmoidf_(float x) { return __builtin_amdgcn_rcpf(1.0f + __expf(-x)); }
;     __device__ __forceinline__ void operator()(f32x4 (&acc)[2][2][4][2], const Unit& u, int wr, int wc, int fr, int fq, LAS unsigned char* lds) const {
;         const int row0 = u.pm * BM + wr * 64 + fr, col0 = u.pn * BM + wc * 32 + 8 * fq;
;         f32x4 bv[2][2];
; #pragma unroll
;         for (int bj = 0; bj < 2; ++bj)
; #pragma unroll
;             for (int n = 0; n < 2; ++n) bv[bj][n] = *(const f32x4*)(bias + col0 + bj * HALF + 4 * n);
; #pragma unroll
;         for (int ai = 0; ai < 2; ++ai) {
;             u32x4 ywv[4][2], swv[4][2];
; #pragma unroll
;             for (int m = 0; m < 4; ++m) {
;                 const size_t off = (size_t)(row0 + ai * HALF + m * 16) * 1024 + col0;
; #pragma unroll
;                 for (int bj = 0; bj < 2; ++bj) { ywv[m][bj] = *(const u32x4*)(Y + off + bj * HALF); swv[m][bj] = *(const u32x4*)(SG + off + bj * HALF); }
;             }
; #pragma unroll
;             for (int m = 0; m < 4; ++m) {
;                 const size_t off = (size_t)(row0 + ai * HALF + m * 16) * 1024 + col0;
; #pragma unroll
;                 for (int bj = 0; bj < 2; ++bj) {
;                     const u32x4 yw = ywv[m][bj], sw = swv[m][bj];
;                     const f32x4 z0 = acc[ai][bj][m][0] + bv[bj][0], z1 = acc[ai][bj][m][1] + bv[bj][1];
;                     f32x4 v0, v1;
;                     v0[0] = bflo(yw.x) * bflo(sw.x) * sigmoidf_(z0[0]); v0[1] = bfhi(yw.x) * bfhi(sw.x) * sigmoidf_(z0[1]);
;                     v0[2] = bflo(yw.y) * bflo(sw.y) * sigmoidf_(z0[2]); v0[3] = bfhi(yw.y) * bfhi(sw.y) * sigmoidf_(z0[3]);
;                     v1[0] = bflo(yw.z) * bflo(sw.z) * sigmoidf_(z1[0]); v1[1] = bfhi(yw.z) * bfhi(sw.z) * sigmoidf_(z1[1]);
;                     v1[2] = bflo(yw.w) * bflo(sw.w) * sigmoidf_(z1[2]); v1[3] = bfhi(yw.w) * bfhi(sw.w) * sigmoidf_(z1[3]);
;                     store8(O + off + bj * HALF, v0, v1);
;                 }
;             }
.LBB0_1164:
	v_lshl_or_b32 v216, s22, 8, v229
	v_readlane_b32 s80, v248, 0
	v_ashrrev_i32_e32 v217, 31, v216
	v_readlane_b32 s84, v248, 4
	v_readlane_b32 s85, v248, 5
	v_lshl_add_u32 v218, s18, 8, v227
	v_ashrrev_i32_e32 v219, 31, v218
	v_lshl_add_u64 v[68:69], v[216:217], 2, s[84:85]
	global_load_dwordx4 v[76:79], v[68:69], off nt
	global_load_dwordx4 v[72:75], v[68:69], off offset:16 nt
	v_lshlrev_b64 v[64:65], 10, v[218:219]
	v_lshl_add_u64 v[64:65], v[64:65], 0, v[216:217]
	v_lshlrev_b64 v[64:65], 1, v[64:65]
	v_lshl_add_u64 v[136:137], s[44:45], 0, v[64:65]
	v_lshl_add_u64 v[138:139], s[42:43], 0, v[64:65]
	global_load_dwordx4 v[234:237], v[136:137], off nt
	global_load_dwordx4 v[238:241], v[138:139], off nt
	global_load_dwordx4 v[64:67], v[68:69], off offset:528 nt
	s_nop 0
	global_load_dwordx4 v[68:71], v[68:69], off offset:512 nt
	s_nop 0
	global_load_dwordx4 v[192:195], v[136:137], off offset:256 nt
	global_load_dwordx4 v[196:199], v[138:139], off offset:256 nt
	v_or_b32_e32 v224, 16, v218
	v_or_b32_e32 v222, 32, v218
	v_or_b32_e32 v220, 48, v218
	v_ashrrev_i32_e32 v225, 31, v224
	v_ashrrev_i32_e32 v223, 31, v222
	v_ashrrev_i32_e32 v221, 31, v220
	v_lshlrev_b64 v[140:141], 10, v[224:225]
	v_lshlrev_b64 v[142:143], 10, v[222:223]
	v_lshlrev_b64 v[152:153], 10, v[220:221]
	v_lshl_add_u64 v[140:141], v[140:141], 0, v[216:217]
	v_lshl_add_u64 v[142:143], v[142:143], 0, v[216:217]
	v_lshl_add_u64 v[152:153], v[152:153], 0, v[216:217]
	v_lshlrev_b64 v[140:141], 1, v[140:141]
	v_lshlrev_b64 v[142:143], 1, v[142:143]
	v_lshlrev_b64 v[152:153], 1, v[152:153]
	v_lshl_add_u64 v[136:137], s[44:45], 0, v[140:141]
	v_lshl_add_u64 v[138:139], s[42:43], 0, v[140:141]
	v_lshl_add_u64 v[140:141], s[44:45], 0, v[142:143]
	v_lshl_add_u64 v[142:143], s[42:43], 0, v[142:143]
	v_lshl_add_u64 v[156:157], s[44:45], 0, v[152:153]
	v_lshl_add_u64 v[244:245], s[42:43], 0, v[152:153]
	global_load_dwordx4 v[184:187], v[136:137], off nt
	global_load_dwordx4 v[176:179], v[136:137], off offset:256 nt
	global_load_dwordx4 v[188:191], v[138:139], off nt
	global_load_dwordx4 v[180:183], v[138:139], off offset:256 nt
	global_load_dwordx4 v[168:171], v[140:141], off nt
	global_load_dwordx4 v[160:163], v[140:141], off offset:256 nt
	global_load_dwordx4 v[172:175], v[142:143], off nt
	global_load_dwordx4 v[164:167], v[142:143], off offset:256 nt
	global_load_dwordx4 v[152:155], v[156:157], off nt
	global_load_dwordx4 v[136:139], v[156:157], off offset:256 nt
	s_nop 0
	global_load_dwordx4 v[156:159], v[244:245], off nt
	global_load_dwordx4 v[140:143], v[244:245], off offset:256 nt
	v_lshlrev_b64 v[242:243], 11, v[218:219]
	s_andn2_b64 vcc, exec, s[0:1]
	s_mov_b64 s[0:1], -1
	v_readlane_b32 s81, v248, 1
	v_readlane_b32 s82, v248, 2
	v_readlane_b32 s83, v248, 3
	v_readlane_b32 s86, v248, 6
	v_readlane_b32 s87, v248, 7
	s_waitcnt vmcnt(0)
	v_pk_add_f32 v[150:151], v[150:151], v[78:79]
	v_pk_add_f32 v[148:149], v[148:149], v[76:77]
	v_pk_add_f32 v[144:145], v[144:145], v[72:73]
	v_mul_f32_e32 v148, 0xbfb8aa3b, v148
	v_mul_f32_e32 v150, 0xbfb8aa3b, v150
	v_mul_f32_e32 v144, 0xbfb8aa3b, v144
	v_exp_f32_e32 v148, v148
	v_exp_f32_e32 v150, v150
	v_exp_f32_e32 v144, v144
	v_mul_f32_e32 v149, 0xbfb8aa3b, v149
	v_mul_f32_e32 v151, 0xbfb8aa3b, v151
	v_mul_f32_e32 v145, 0xbfb8aa3b, v145
	v_exp_f32_e32 v149, v149
	v_exp_f32_e32 v151, v151
	v_exp_f32_e32 v145, v145
	v_add_f32_e32 v148, 1.0, v148
	v_add_f32_e32 v150, 1.0, v150
	v_add_f32_e32 v144, 1.0, v144
	v_pk_add_f32 v[146:147], v[146:147], v[74:75]
	v_rcp_f32_e32 v148, v148
	v_rcp_f32_e32 v150, v150
	v_rcp_f32_e32 v144, v144
	v_add_f32_e32 v149, 1.0, v149
	v_add_f32_e32 v151, 1.0, v151
	v_add_f32_e32 v145, 1.0, v145
	v_mul_f32_e32 v146, 0xbfb8aa3b, v146
	v_lshlrev_b32_e32 v219, 16, v234
	v_lshlrev_b32_e32 v233, 16, v238
	v_and_b32_e32 v238, 0xffff0000, v238
	v_and_b32_e32 v234, 0xffff0000, v234
	v_lshlrev_b32_e32 v244, 16, v235
	v_lshlrev_b32_e32 v245, 16, v239
	v_lshlrev_b32_e32 v246, 16, v236
	v_lshlrev_b32_e32 v247, 16, v240
	v_rcp_f32_e32 v149, v149
	v_rcp_f32_e32 v151, v151
	v_rcp_f32_e32 v145, v145
	v_exp_f32_e32 v146, v146
	v_mul_f32_e32 v219, v233, v219
	v_mul_f32_e32 v233, v238, v234
	v_mul_f32_e32 v234, v245, v244
	v_mul_f32_e32 v238, v247, v246
	v_and_b32_e32 v239, 0xffff0000, v239
	v_and_b32_e32 v235, 0xffff0000, v235
	v_mul_f32_e32 v148, v148, v219
	v_mul_f32_e32 v219, v150, v234
	v_mul_f32_e32 v234, v144, v238
	v_and_b32_e32 v144, 0xffff0000, v240
	v_and_b32_e32 v150, 0xffff0000, v236
	v_mul_f32_e32 v235, v239, v235
	v_mul_f32_e32 v144, v144, v150
	v_mul_f32_e32 v149, v149, v233
	v_mul_f32_e32 v233, v151, v235
	v_mul_f32_e32 v235, v145, v144
	v_add_f32_e32 v145, 1.0, v146
	v_mul_f32_e32 v146, 0xbfb8aa3b, v147
	v_rcp_f32_e32 v145, v145
	v_exp_f32_e32 v146, v146
	v_lshlrev_b32_e32 v144, 16, v237
	v_lshlrev_b32_e32 v147, 16, v241
	v_pk_add_f32 v[132:133], v[132:133], v[68:69]
	v_mul_f32_e32 v144, v147, v144
	v_mul_f32_e32 v132, 0xbfb8aa3b, v132
	v_mul_f32_e32 v236, v145, v144
	v_add_f32_e32 v144, 1.0, v146
	v_exp_f32_e32 v132, v132
	v_rcp_f32_e32 v144, v144
	v_mul_f32_e32 v133, 0xbfb8aa3b, v133
	v_pk_add_f32 v[134:135], v[134:135], v[70:71]
	v_exp_f32_e32 v133, v133
	v_and_b32_e32 v145, 0xffff0000, v241
	v_and_b32_e32 v146, 0xffff0000, v237
	v_mul_f32_e32 v134, 0xbfb8aa3b, v134
	v_mul_f32_e32 v145, v145, v146
	v_add_f32_e32 v132, 1.0, v132
	v_exp_f32_e32 v134, v134
	v_mul_f32_e32 v237, v144, v145
	v_lshl_add_u64 v[146:147], s[26:27], 0, v[242:243]
	v_lshlrev_b64 v[144:145], 1, v[216:217]
	v_rcp_f32_e32 v132, v132
	v_mul_f32_e32 v135, 0xbfb8aa3b, v135
	v_lshl_add_u64 v[150:151], v[146:147], 0, v[144:145]
; __device__ __forceinline__ float bflo(unsigned w) { return __uint_as_float(w << 16); }
; __device__ __forceinline__ float bfhi(unsigned w) { return __uint_as_float(w & 0xffff0000u); }
; __device__ __forceinline__ float sigmoidf_(float x) { return __builtin_amdgcn_rcpf(1.0f + __expf(-x)); }
;     __device__ __forceinline__ void operator()(f32x4 (&acc)[2][2][4][2], const Unit& u, int wr, int wc, int fr, int fq, LAS unsigned char* lds) const {
;     ...
;             for (int m = 0; m < 4; ++m) {
;                 const size_t off = (size_t)(row0 + ai * HALF + m * 16) * 1024 + col0;
; #pragma unroll
;                 for (int bj = 0; bj < 2; ++bj) {
;                     const u32x4 yw = ywv[m][bj], sw = swv[m][bj];
;                     const f32x4 z0 = acc[ai][bj][m][0] + bv[bj][0], z1 = acc[ai][bj][m][1] + bv[bj][1];
;                     f32x4 v0, v1;
;                     v0[0] = bflo(yw.x) * bflo(sw.x) * sigmoidf_(z0[0]); v0[1] = bfhi(yw.x) * bfhi(sw.x) * sigmoidf_(z0[1]);
;                     v0[2] = bflo(yw.y) * bflo(sw.y) * sigmoidf_(z0[2]); v0[3] = bfhi(yw.y) * bfhi(sw.y) * sigmoidf_(z0[3]);
;                     v1[0] = bflo(yw.z) * bflo(sw.z) * sigmoidf_(z1[0]); v1[1] = bfhi(yw.z) * bfhi(sw.z) * sigmoidf_(z1[1]);
;                     v1[2] = bflo(yw.w) * bflo(sw.w) * sigmoidf_(z1[2]); v1[3] = bfhi(yw.w) * bfhi(sw.w) * sigmoidf_(z1[3]);
;                     store8(O + off + bj * HALF, v0, v1);
;                 }
;             }
	v_cvt_pk_bf16_f32 v146, v148, v149
	v_cvt_pk_bf16_f32 v147, v219, v233
	v_pk_add_f32 v[128:129], v[128:129], v[64:65]
	v_add_f32_e32 v133, 1.0, v133
	v_exp_f32_e32 v135, v135
	v_cvt_pk_bf16_f32 v148, v234, v235
	v_cvt_pk_bf16_f32 v149, v236, v237
	global_store_dwordx4 v[150:151], v[146:149], off
	v_rcp_f32_e32 v133, v133
	v_mul_f32_e32 v128, 0xbfb8aa3b, v128
	v_lshlrev_b32_e32 v146, 16, v192
	v_lshlrev_b32_e32 v147, 16, v196
	v_mul_f32_e32 v146, v147, v146
	v_add_f32_e32 v134, 1.0, v134
	v_exp_f32_e32 v128, v128
	v_mul_f32_e32 v132, v132, v146
	v_and_b32_e32 v146, 0xffff0000, v196
	v_and_b32_e32 v147, 0xffff0000, v192
	v_rcp_f32_e32 v134, v134
	v_mul_f32_e32 v129, 0xbfb8aa3b, v129
	v_mul_f32_e32 v146, v146, v147
	v_add_f32_e32 v135, 1.0, v135
	v_exp_f32_e32 v129, v129
	v_mul_f32_e32 v133, v133, v146
	v_lshlrev_b32_e32 v146, 16, v193
	v_lshlrev_b32_e32 v147, 16, v197
	v_rcp_f32_e32 v135, v135
	v_mul_f32_e32 v146, v147, v146
	v_add_f32_e32 v128, 1.0, v128
	v_pk_add_f32 v[130:131], v[130:131], v[66:67]
	v_mul_f32_e32 v134, v134, v146
	v_and_b32_e32 v146, 0xffff0000, v197
	v_and_b32_e32 v147, 0xffff0000, v193
	v_rcp_f32_e32 v128, v128
	v_mul_f32_e32 v146, v146, v147
	v_add_f32_e32 v129, 1.0, v129
	v_mul_f32_e32 v130, 0xbfb8aa3b, v130
	v_mul_f32_e32 v135, v135, v146
	v_lshlrev_b32_e32 v146, 16, v194
	v_lshlrev_b32_e32 v147, 16, v198
	v_rcp_f32_e32 v129, v129
	v_exp_f32_e32 v130, v130
	v_mul_f32_e32 v146, v147, v146
	v_mul_f32_e32 v146, v128, v146
	v_and_b32_e32 v128, 0xffff0000, v198
	v_and_b32_e32 v147, 0xffff0000, v194
	v_mul_f32_e32 v128, v128, v147
	v_mul_f32_e32 v147, v129, v128
	v_add_f32_e32 v129, 1.0, v130
	v_mul_f32_e32 v130, 0xbfb8aa3b, v131
	v_rcp_f32_e32 v129, v129
	v_exp_f32_e32 v130, v130
	v_pk_add_f32 v[124:125], v[124:125], v[76:77]
	v_lshlrev_b32_e32 v128, 16, v195
	v_lshlrev_b32_e32 v131, 16, v199
	v_mul_f32_e32 v124, 0xbfb8aa3b, v124
	v_mul_f32_e32 v128, v131, v128
	v_exp_f32_e32 v124, v124
	v_mul_f32_e32 v131, v129, v128
	v_add_f32_e32 v128, 1.0, v130
	v_mul_f32_e32 v125, 0xbfb8aa3b, v125
	v_rcp_f32_e32 v128, v128
	v_exp_f32_e32 v125, v125
	v_and_b32_e32 v129, 0xffff0000, v199
	v_and_b32_e32 v130, 0xffff0000, v195
	v_add_f32_e32 v124, 1.0, v124
	v_mul_f32_e32 v129, v129, v130
	v_rcp_f32_e32 v124, v124
	v_mul_f32_e32 v148, v128, v129
	v_cvt_pk_bf16_f32 v128, v132, v133
	v_cvt_pk_bf16_f32 v129, v134, v135
	v_cvt_pk_bf16_f32 v130, v146, v147
	v_cvt_pk_bf16_f32 v131, v131, v148
	v_add_f32_e32 v125, 1.0, v125
	global_store_dwordx4 v[150:151], v[128:131], off offset:256
	v_rcp_f32_e32 v125, v125
	v_pk_add_f32 v[126:127], v[126:127], v[78:79]
	v_lshlrev_b32_e32 v130, 16, v184
	v_lshlrev_b32_e32 v131, 16, v188
	v_mul_f32_e32 v130, v131, v130
	v_mul_f32_e32 v130, v124, v130
	v_and_b32_e32 v124, 0xffff0000, v188
	v_and_b32_e32 v131, 0xffff0000, v184
	v_mul_f32_e32 v124, v124, v131
	v_mul_f32_e32 v126, 0xbfb8aa3b, v126
	v_exp_f32_e32 v126, v126
	v_mul_f32_e32 v131, v125, v124
	v_lshlrev_b32_e32 v124, 16, v185
	v_lshlrev_b32_e32 v125, 16, v189
	v_mul_f32_e32 v124, v125, v124
	v_mul_f32_e32 v125, 0xbfb8aa3b, v127
	v_pk_add_f32 v[120:121], v[120:121], v[72:73]
	v_exp_f32_e32 v125, v125
	v_mul_f32_e32 v120, 0xbfb8aa3b, v120
	v_add_f32_e32 v126, 1.0, v126
	v_exp_f32_e32 v120, v120
	v_rcp_f32_e32 v126, v126
	v_mul_f32_e32 v121, 0xbfb8aa3b, v121
	v_add_f32_e32 v125, 1.0, v125
	v_exp_f32_e32 v121, v121
	v_rcp_f32_e32 v125, v125
	v_add_f32_e32 v120, 1.0, v120
	v_pk_add_f32 v[122:123], v[122:123], v[74:75]
	v_mul_f32_e32 v126, v126, v124
	v_and_b32_e32 v124, 0xffff0000, v189
	v_and_b32_e32 v127, 0xffff0000, v185
	v_rcp_f32_e32 v120, v120
	v_mul_f32_e32 v124, v124, v127
	v_add_f32_e32 v121, 1.0, v121
	v_mul_f32_e32 v122, 0xbfb8aa3b, v122
	v_mul_f32_e32 v127, v125, v124
	v_lshlrev_b32_e32 v124, 16, v186
	v_lshlrev_b32_e32 v125, 16, v190
	v_rcp_f32_e32 v121, v121
	v_exp_f32_e32 v122, v122
	v_mul_f32_e32 v124, v125, v124
	v_mul_f32_e32 v132, v120, v124
	v_and_b32_e32 v120, 0xffff0000, v190
	v_and_b32_e32 v124, 0xffff0000, v186
	v_mul_f32_e32 v120, v120, v124
	v_mul_f32_e32 v133, v121, v120
	v_add_f32_e32 v121, 1.0, v122
	v_mul_f32_e32 v122, 0xbfb8aa3b, v123
	v_rcp_f32_e32 v121, v121
	v_exp_f32_e32 v122, v122
	v_lshlrev_b32_e32 v120, 16, v187
	v_lshlrev_b32_e32 v123, 16, v191
	v_pk_add_f32 v[116:117], v[116:117], v[68:69]
	v_mul_f32_e32 v120, v123, v120
	v_mul_f32_e32 v116, 0xbfb8aa3b, v116
	v_mul_f32_e32 v123, v121, v120
	v_add_f32_e32 v120, 1.0, v122
	v_exp_f32_e32 v116, v116
	v_rcp_f32_e32 v120, v120
	v_mul_f32_e32 v117, 0xbfb8aa3b, v117
	v_pk_add_f32 v[118:119], v[118:119], v[70:71]
	v_exp_f32_e32 v117, v117
	v_and_b32_e32 v121, 0xffff0000, v191
	v_and_b32_e32 v122, 0xffff0000, v187
	v_mul_f32_e32 v118, 0xbfb8aa3b, v118
	v_lshlrev_b64 v[128:129], 11, v[224:225]
	v_mul_f32_e32 v121, v121, v122
	v_add_f32_e32 v116, 1.0, v116
	v_exp_f32_e32 v118, v118
	v_mul_f32_e32 v134, v120, v121
	v_lshl_add_u64 v[120:121], s[26:27], 0, v[128:129]
	v_rcp_f32_e32 v116, v116
	v_mul_f32_e32 v119, 0xbfb8aa3b, v119
	v_lshl_add_u64 v[124:125], v[120:121], 0, v[144:145]
	v_cvt_pk_bf16_f32 v120, v130, v131
	v_cvt_pk_bf16_f32 v121, v126, v127
	v_pk_add_f32 v[112:113], v[112:113], v[64:65]
	v_add_f32_e32 v117, 1.0, v117
	v_exp_f32_e32 v119, v119
	v_cvt_pk_bf16_f32 v122, v132, v133
	v_cvt_pk_bf16_f32 v123, v123, v134
	global_store_dwordx4 v[124:125], v[120:123], off
	v_rcp_f32_e32 v117, v117
	v_mul_f32_e32 v112, 0xbfb8aa3b, v112
	v_lshlrev_b32_e32 v120, 16, v176
	v_lshlrev_b32_e32 v121, 16, v180
	v_mul_f32_e32 v120, v121, v120
	v_add_f32_e32 v118, 1.0, v118
	v_exp_f32_e32 v112, v112
	v_mul_f32_e32 v116, v116, v120
	v_and_b32_e32 v120, 0xffff0000, v180
; __device__ __forceinline__ float bflo(unsigned w) { return __uint_as_float(w << 16); }
; __device__ __forceinline__ float bfhi(unsigned w) { return __uint_as_float(w & 0xffff0000u); }
; __device__ __forceinline__ float sigmoidf_(float x) { return __builtin_amdgcn_rcpf(1.0f + __expf(-x)); }
;     __device__ __forceinline__ void operator()(f32x4 (&acc)[2][2][4][2], const Unit& u, int wr, int wc, int fr, int fq, LAS unsigned char* lds) const {
;     ...
;             for (int m = 0; m < 4; ++m) {
;                 const size_t off = (size_t)(row0 + ai * HALF + m * 16) * 1024 + col0;
; #pragma unroll
;                 for (int bj = 0; bj < 2; ++bj) {
;                     const u32x4 yw = ywv[m][bj], sw = swv[m][bj];
;                     const f32x4 z0 = acc[ai][bj][m][0] + bv[bj][0], z1 = acc[ai][bj][m][1] + bv[bj][1];
;                     f32x4 v0, v1;
;                     v0[0] = bflo(yw.x) * bflo(sw.x) * sigmoidf_(z0[0]); v0[1] = bfhi(yw.x) * bfhi(sw.x) * sigmoidf_(z0[1]);
;                     v0[2] = bflo(yw.y) * bflo(sw.y) * sigmoidf_(z0[2]); v0[3] = bfhi(yw.y) * bfhi(sw.y) * sigmoidf_(z0[3]);
;                     v1[0] = bflo(yw.z) * bflo(sw.z) * sigmoidf_(z1[0]); v1[1] = bfhi(yw.z) * bfhi(sw.z) * sigmoidf_(z1[1]);
;                     v1[2] = bflo(yw.w) * bflo(sw.w) * sigmoidf_(z1[2]); v1[3] = bfhi(yw.w) * bfhi(sw.w) * sigmoidf_(z1[3]);
;                     store8(O + off + bj * HALF, v0, v1);
;                 }
;             }
	v_and_b32_e32 v121, 0xffff0000, v176
	v_rcp_f32_e32 v118, v118
	v_mul_f32_e32 v113, 0xbfb8aa3b, v113
	v_mul_f32_e32 v120, v120, v121
	v_add_f32_e32 v119, 1.0, v119
	v_exp_f32_e32 v113, v113
	v_mul_f32_e32 v117, v117, v120
	v_lshlrev_b32_e32 v120, 16, v177
	v_lshlrev_b32_e32 v121, 16, v181
	v_rcp_f32_e32 v119, v119
	v_mul_f32_e32 v120, v121, v120
	v_add_f32_e32 v112, 1.0, v112
	v_pk_add_f32 v[114:115], v[114:115], v[66:67]
	v_mul_f32_e32 v118, v118, v120
	v_and_b32_e32 v120, 0xffff0000, v181
	v_and_b32_e32 v121, 0xffff0000, v177
	v_rcp_f32_e32 v112, v112
	v_mul_f32_e32 v120, v120, v121
	v_add_f32_e32 v113, 1.0, v113
	v_mul_f32_e32 v114, 0xbfb8aa3b, v114
	v_mul_f32_e32 v119, v119, v120
	v_lshlrev_b32_e32 v120, 16, v178
	v_lshlrev_b32_e32 v121, 16, v182
	v_rcp_f32_e32 v113, v113
	v_exp_f32_e32 v114, v114
	v_mul_f32_e32 v120, v121, v120
	v_mul_f32_e32 v120, v112, v120
	v_and_b32_e32 v112, 0xffff0000, v182
	v_and_b32_e32 v121, 0xffff0000, v178
	v_mul_f32_e32 v112, v112, v121
	v_mul_f32_e32 v121, v113, v112
	v_add_f32_e32 v113, 1.0, v114
	v_mul_f32_e32 v114, 0xbfb8aa3b, v115
	v_rcp_f32_e32 v113, v113
	v_exp_f32_e32 v114, v114
	v_pk_add_f32 v[108:109], v[108:109], v[76:77]
	v_lshlrev_b32_e32 v112, 16, v179
	v_lshlrev_b32_e32 v115, 16, v183
	v_mul_f32_e32 v108, 0xbfb8aa3b, v108
	v_mul_f32_e32 v112, v115, v112
	v_exp_f32_e32 v108, v108
	v_mul_f32_e32 v115, v113, v112
	v_add_f32_e32 v112, 1.0, v114
	v_mul_f32_e32 v109, 0xbfb8aa3b, v109
	v_rcp_f32_e32 v112, v112
	v_exp_f32_e32 v109, v109
	v_and_b32_e32 v113, 0xffff0000, v183
	v_and_b32_e32 v114, 0xffff0000, v179
	v_add_f32_e32 v108, 1.0, v108
	v_mul_f32_e32 v113, v113, v114
	v_rcp_f32_e32 v108, v108
	v_mul_f32_e32 v122, v112, v113
	v_cvt_pk_bf16_f32 v112, v116, v117
	v_cvt_pk_bf16_f32 v113, v118, v119
	v_cvt_pk_bf16_f32 v114, v120, v121
	v_cvt_pk_bf16_f32 v115, v115, v122
	v_add_f32_e32 v109, 1.0, v109
	global_store_dwordx4 v[124:125], v[112:115], off offset:256
	v_rcp_f32_e32 v109, v109
	v_pk_add_f32 v[110:111], v[110:111], v[78:79]
	v_lshlrev_b32_e32 v114, 16, v168
	v_lshlrev_b32_e32 v115, 16, v172
	v_mul_f32_e32 v114, v115, v114
	v_mul_f32_e32 v114, v108, v114
	v_and_b32_e32 v108, 0xffff0000, v172
	v_and_b32_e32 v115, 0xffff0000, v168
	v_mul_f32_e32 v108, v108, v115
	v_mul_f32_e32 v110, 0xbfb8aa3b, v110
	v_exp_f32_e32 v110, v110
	v_mul_f32_e32 v115, v109, v108
	v_lshlrev_b32_e32 v108, 16, v169
	v_lshlrev_b32_e32 v109, 16, v173
	v_mul_f32_e32 v108, v109, v108
	v_mul_f32_e32 v109, 0xbfb8aa3b, v111
	v_pk_add_f32 v[104:105], v[104:105], v[72:73]
	v_exp_f32_e32 v109, v109
	v_mul_f32_e32 v104, 0xbfb8aa3b, v104
	v_add_f32_e32 v110, 1.0, v110
	v_exp_f32_e32 v104, v104
	v_rcp_f32_e32 v110, v110
	v_mul_f32_e32 v105, 0xbfb8aa3b, v105
	v_add_f32_e32 v109, 1.0, v109
	v_exp_f32_e32 v105, v105
	v_rcp_f32_e32 v109, v109
	v_add_f32_e32 v104, 1.0, v104
	v_pk_add_f32 v[106:107], v[106:107], v[74:75]
	v_mul_f32_e32 v110, v110, v108
	v_and_b32_e32 v108, 0xffff0000, v173
	v_and_b32_e32 v111, 0xffff0000, v169
	v_rcp_f32_e32 v104, v104
	v_mul_f32_e32 v108, v108, v111
	v_add_f32_e32 v105, 1.0, v105
	v_mul_f32_e32 v106, 0xbfb8aa3b, v106
	v_mul_f32_e32 v111, v109, v108
	v_lshlrev_b32_e32 v108, 16, v170
	v_lshlrev_b32_e32 v109, 16, v174
	v_rcp_f32_e32 v105, v105
	v_exp_f32_e32 v106, v106
	v_mul_f32_e32 v108, v109, v108
	v_mul_f32_e32 v116, v104, v108
	v_and_b32_e32 v104, 0xffff0000, v174
	v_and_b32_e32 v108, 0xffff0000, v170
	v_mul_f32_e32 v104, v104, v108
	v_mul_f32_e32 v117, v105, v104
	v_add_f32_e32 v105, 1.0, v106
	v_mul_f32_e32 v106, 0xbfb8aa3b, v107
	v_rcp_f32_e32 v105, v105
	v_exp_f32_e32 v106, v106
	v_lshlrev_b32_e32 v104, 16, v171
	v_lshlrev_b32_e32 v107, 16, v175
	v_pk_add_f32 v[100:101], v[100:101], v[68:69]
	v_mul_f32_e32 v104, v107, v104
	v_mul_f32_e32 v100, 0xbfb8aa3b, v100
	v_mul_f32_e32 v107, v105, v104
	v_add_f32_e32 v104, 1.0, v106
	v_exp_f32_e32 v100, v100
	v_rcp_f32_e32 v104, v104
	v_mul_f32_e32 v101, 0xbfb8aa3b, v101
	v_pk_add_f32 v[102:103], v[102:103], v[70:71]
	v_exp_f32_e32 v101, v101
	v_and_b32_e32 v105, 0xffff0000, v175
	v_and_b32_e32 v106, 0xffff0000, v171
	v_mul_f32_e32 v102, 0xbfb8aa3b, v102
	v_lshlrev_b64 v[112:113], 11, v[222:223]
	v_mul_f32_e32 v105, v105, v106
	v_add_f32_e32 v100, 1.0, v100
	v_exp_f32_e32 v102, v102
	v_mul_f32_e32 v118, v104, v105
	v_lshl_add_u64 v[104:105], s[26:27], 0, v[112:113]
	v_rcp_f32_e32 v100, v100
	v_mul_f32_e32 v103, 0xbfb8aa3b, v103
	v_lshl_add_u64 v[108:109], v[104:105], 0, v[144:145]
	v_cvt_pk_bf16_f32 v104, v114, v115
	v_cvt_pk_bf16_f32 v105, v110, v111
	v_pk_add_f32 v[96:97], v[96:97], v[64:65]
	v_add_f32_e32 v101, 1.0, v101
	v_exp_f32_e32 v103, v103
	v_cvt_pk_bf16_f32 v106, v116, v117
	v_cvt_pk_bf16_f32 v107, v107, v118
	global_store_dwordx4 v[108:109], v[104:107], off
	v_rcp_f32_e32 v101, v101
	v_mul_f32_e32 v96, 0xbfb8aa3b, v96
	v_lshlrev_b32_e32 v104, 16, v160
	v_lshlrev_b32_e32 v105, 16, v164
	v_mul_f32_e32 v104, v105, v104
	v_add_f32_e32 v102, 1.0, v102
	v_exp_f32_e32 v96, v96
	v_mul_f32_e32 v100, v100, v104
	v_and_b32_e32 v104, 0xffff0000, v164
	v_and_b32_e32 v105, 0xffff0000, v160
	v_rcp_f32_e32 v102, v102
	v_mul_f32_e32 v97, 0xbfb8aa3b, v97
	v_mul_f32_e32 v104, v104, v105
	v_add_f32_e32 v103, 1.0, v103
	v_exp_f32_e32 v97, v97
	v_mul_f32_e32 v101, v101, v104
	v_lshlrev_b32_e32 v104, 16, v161
	v_lshlrev_b32_e32 v105, 16, v165
	v_rcp_f32_e32 v103, v103
	v_mul_f32_e32 v104, v105, v104
	v_add_f32_e32 v96, 1.0, v96
	v_pk_add_f32 v[98:99], v[98:99], v[66:67]
	v_mul_f32_e32 v102, v102, v104
	v_and_b32_e32 v104, 0xffff0000, v165
	v_and_b32_e32 v105, 0xffff0000, v161
	v_rcp_f32_e32 v96, v96
	v_mul_f32_e32 v104, v104, v105
	v_add_f32_e32 v97, 1.0, v97
; __device__ __forceinline__ float bflo(unsigned w) { return __uint_as_float(w << 16); }
; __device__ __forceinline__ float bfhi(unsigned w) { return __uint_as_float(w & 0xffff0000u); }
; __device__ __forceinline__ float sigmoidf_(float x) { return __builtin_amdgcn_rcpf(1.0f + __expf(-x)); }
;     __device__ __forceinline__ void operator()(f32x4 (&acc)[2][2][4][2], const Unit& u, int wr, int wc, int fr, int fq, LAS unsigned char* lds) const {
;     ...
;             for (int m = 0; m < 4; ++m) {
;                 const size_t off = (size_t)(row0 + ai * HALF + m * 16) * 1024 + col0;
; #pragma unroll
;                 for (int bj = 0; bj < 2; ++bj) {
;                     const u32x4 yw = ywv[m][bj], sw = swv[m][bj];
;                     const f32x4 z0 = acc[ai][bj][m][0] + bv[bj][0], z1 = acc[ai][bj][m][1] + bv[bj][1];
;                     f32x4 v0, v1;
;                     v0[0] = bflo(yw.x) * bflo(sw.x) * sigmoidf_(z0[0]); v0[1] = bfhi(yw.x) * bfhi(sw.x) * sigmoidf_(z0[1]);
;                     v0[2] = bflo(yw.y) * bflo(sw.y) * sigmoidf_(z0[2]); v0[3] = bfhi(yw.y) * bfhi(sw.y) * sigmoidf_(z0[3]);
;                     v1[0] = bflo(yw.z) * bflo(sw.z) * sigmoidf_(z1[0]); v1[1] = bfhi(yw.z) * bfhi(sw.z) * sigmoidf_(z1[1]);
;                     v1[2] = bflo(yw.w) * bflo(sw.w) * sigmoidf_(z1[2]); v1[3] = bfhi(yw.w) * bfhi(sw.w) * sigmoidf_(z1[3]);
;                     store8(O + off + bj * HALF, v0, v1);
;                 }
;             }
	v_mul_f32_e32 v98, 0xbfb8aa3b, v98
	v_mul_f32_e32 v103, v103, v104
	v_lshlrev_b32_e32 v104, 16, v162
	v_lshlrev_b32_e32 v105, 16, v166
	v_rcp_f32_e32 v97, v97
	v_exp_f32_e32 v98, v98
	v_mul_f32_e32 v104, v105, v104
	v_mul_f32_e32 v104, v96, v104
	v_and_b32_e32 v96, 0xffff0000, v166
	v_and_b32_e32 v105, 0xffff0000, v162
	v_mul_f32_e32 v96, v96, v105
	v_mul_f32_e32 v105, v97, v96
	v_add_f32_e32 v97, 1.0, v98
	v_mul_f32_e32 v98, 0xbfb8aa3b, v99
	v_rcp_f32_e32 v97, v97
	v_exp_f32_e32 v98, v98
	v_pk_add_f32 v[92:93], v[92:93], v[76:77]
	v_lshlrev_b32_e32 v96, 16, v163
	v_lshlrev_b32_e32 v99, 16, v167
	v_mul_f32_e32 v92, 0xbfb8aa3b, v92
	v_mul_f32_e32 v96, v99, v96
	v_exp_f32_e32 v92, v92
	v_mul_f32_e32 v99, v97, v96
	v_add_f32_e32 v96, 1.0, v98
	v_mul_f32_e32 v93, 0xbfb8aa3b, v93
	v_rcp_f32_e32 v96, v96
	v_exp_f32_e32 v93, v93
	v_and_b32_e32 v97, 0xffff0000, v167
	v_and_b32_e32 v98, 0xffff0000, v163
	v_add_f32_e32 v92, 1.0, v92
	v_mul_f32_e32 v97, v97, v98
	v_rcp_f32_e32 v92, v92
	v_mul_f32_e32 v106, v96, v97
	v_cvt_pk_bf16_f32 v96, v100, v101
	v_cvt_pk_bf16_f32 v97, v102, v103
	v_cvt_pk_bf16_f32 v98, v104, v105
	v_cvt_pk_bf16_f32 v99, v99, v106
	v_add_f32_e32 v93, 1.0, v93
	global_store_dwordx4 v[108:109], v[96:99], off offset:256
	v_rcp_f32_e32 v93, v93
	v_pk_add_f32 v[94:95], v[94:95], v[78:79]
	v_lshlrev_b32_e32 v98, 16, v152
	v_lshlrev_b32_e32 v99, 16, v156
	v_mul_f32_e32 v98, v99, v98
	v_mul_f32_e32 v98, v92, v98
	v_and_b32_e32 v92, 0xffff0000, v156
	v_and_b32_e32 v99, 0xffff0000, v152
	v_mul_f32_e32 v92, v92, v99
	v_mul_f32_e32 v94, 0xbfb8aa3b, v94
	v_exp_f32_e32 v94, v94
	v_mul_f32_e32 v99, v93, v92
	v_lshlrev_b32_e32 v92, 16, v153
	v_lshlrev_b32_e32 v93, 16, v157
	v_mul_f32_e32 v92, v93, v92
	v_mul_f32_e32 v93, 0xbfb8aa3b, v95
	v_pk_add_f32 v[88:89], v[88:89], v[72:73]
	v_exp_f32_e32 v93, v93
	v_mul_f32_e32 v88, 0xbfb8aa3b, v88
	v_add_f32_e32 v94, 1.0, v94
	v_exp_f32_e32 v88, v88
	v_rcp_f32_e32 v94, v94
	v_mul_f32_e32 v89, 0xbfb8aa3b, v89
	v_add_f32_e32 v93, 1.0, v93
	v_exp_f32_e32 v89, v89
	v_rcp_f32_e32 v93, v93
	v_add_f32_e32 v88, 1.0, v88
	v_pk_add_f32 v[90:91], v[90:91], v[74:75]
	v_mul_f32_e32 v94, v94, v92
	v_and_b32_e32 v92, 0xffff0000, v157
	v_and_b32_e32 v95, 0xffff0000, v153
	v_rcp_f32_e32 v88, v88
	v_mul_f32_e32 v92, v92, v95
	v_add_f32_e32 v89, 1.0, v89
	v_mul_f32_e32 v90, 0xbfb8aa3b, v90
	v_mul_f32_e32 v95, v93, v92
	v_lshlrev_b32_e32 v92, 16, v154
	v_lshlrev_b32_e32 v93, 16, v158
	v_rcp_f32_e32 v89, v89
	v_exp_f32_e32 v90, v90
	v_mul_f32_e32 v92, v93, v92
	v_mul_f32_e32 v100, v88, v92
	v_and_b32_e32 v88, 0xffff0000, v158
	v_and_b32_e32 v92, 0xffff0000, v154
	v_mul_f32_e32 v88, v88, v92
	v_mul_f32_e32 v101, v89, v88
	v_add_f32_e32 v89, 1.0, v90
	v_mul_f32_e32 v90, 0xbfb8aa3b, v91
	v_rcp_f32_e32 v89, v89
	v_exp_f32_e32 v90, v90
	v_lshlrev_b32_e32 v88, 16, v155
	v_lshlrev_b32_e32 v91, 16, v159
	v_pk_add_f32 v[84:85], v[84:85], v[68:69]
	v_mul_f32_e32 v88, v91, v88
	v_mul_f32_e32 v84, 0xbfb8aa3b, v84
	v_mul_f32_e32 v91, v89, v88
	v_add_f32_e32 v88, 1.0, v90
	v_exp_f32_e32 v84, v84
	v_rcp_f32_e32 v88, v88
	v_mul_f32_e32 v85, 0xbfb8aa3b, v85
	v_pk_add_f32 v[86:87], v[86:87], v[70:71]
	v_exp_f32_e32 v85, v85
	v_and_b32_e32 v89, 0xffff0000, v159
	v_and_b32_e32 v90, 0xffff0000, v155
	v_mul_f32_e32 v86, 0xbfb8aa3b, v86
	v_lshlrev_b64 v[96:97], 11, v[220:221]
	v_mul_f32_e32 v89, v89, v90
	v_add_f32_e32 v84, 1.0, v84
	v_exp_f32_e32 v86, v86
	v_mul_f32_e32 v102, v88, v89
	v_lshl_add_u64 v[88:89], s[26:27], 0, v[96:97]
	v_rcp_f32_e32 v84, v84
	v_mul_f32_e32 v87, 0xbfb8aa3b, v87
	v_lshl_add_u64 v[92:93], v[88:89], 0, v[144:145]
	v_cvt_pk_bf16_f32 v88, v98, v99
	v_cvt_pk_bf16_f32 v89, v94, v95
	v_pk_add_f32 v[80:81], v[80:81], v[64:65]
	v_add_f32_e32 v85, 1.0, v85
	v_exp_f32_e32 v87, v87
	v_cvt_pk_bf16_f32 v90, v100, v101
	v_cvt_pk_bf16_f32 v91, v91, v102
	global_store_dwordx4 v[92:93], v[88:91], off
	v_rcp_f32_e32 v85, v85
	v_mul_f32_e32 v80, 0xbfb8aa3b, v80
	v_lshlrev_b32_e32 v88, 16, v136
	v_lshlrev_b32_e32 v89, 16, v140
	v_mul_f32_e32 v88, v89, v88
	v_add_f32_e32 v86, 1.0, v86
	v_exp_f32_e32 v80, v80
	v_mul_f32_e32 v84, v84, v88
	v_and_b32_e32 v88, 0xffff0000, v140
	v_and_b32_e32 v89, 0xffff0000, v136
	v_rcp_f32_e32 v86, v86
	v_mul_f32_e32 v81, 0xbfb8aa3b, v81
	v_mul_f32_e32 v88, v88, v89
	v_add_f32_e32 v87, 1.0, v87
	v_exp_f32_e32 v81, v81
	v_mul_f32_e32 v85, v85, v88
	v_lshlrev_b32_e32 v88, 16, v137
	v_lshlrev_b32_e32 v89, 16, v141
	v_rcp_f32_e32 v87, v87
	v_mul_f32_e32 v88, v89, v88
	v_add_f32_e32 v80, 1.0, v80
	v_pk_add_f32 v[82:83], v[82:83], v[66:67]
	v_mul_f32_e32 v86, v86, v88
	v_and_b32_e32 v88, 0xffff0000, v141
	v_and_b32_e32 v89, 0xffff0000, v137
	v_rcp_f32_e32 v80, v80
	v_mul_f32_e32 v88, v88, v89
	v_add_f32_e32 v81, 1.0, v81
	v_mul_f32_e32 v82, 0xbfb8aa3b, v82
	v_mul_f32_e32 v87, v87, v88
	v_lshlrev_b32_e32 v88, 16, v138
	v_lshlrev_b32_e32 v89, 16, v142
	v_rcp_f32_e32 v81, v81
	v_exp_f32_e32 v82, v82
	v_mul_f32_e32 v88, v89, v88
	v_mul_f32_e32 v88, v80, v88
	v_and_b32_e32 v80, 0xffff0000, v142
	v_and_b32_e32 v89, 0xffff0000, v138
	v_mul_f32_e32 v80, v80, v89
	v_mul_f32_e32 v89, v81, v80
	v_add_f32_e32 v81, 1.0, v82
	v_mul_f32_e32 v82, 0xbfb8aa3b, v83
	v_rcp_f32_e32 v81, v81
	v_exp_f32_e32 v82, v82
	v_lshlrev_b32_e32 v80, 16, v139
	v_lshlrev_b32_e32 v83, 16, v143
	v_mul_f32_e32 v80, v83, v80
	v_mul_f32_e32 v83, v81, v80
	v_add_f32_e32 v80, 1.0, v82
	v_rcp_f32_e32 v80, v80
	v_and_b32_e32 v81, 0xffff0000, v143
	v_and_b32_e32 v82, 0xffff0000, v139
	v_mul_f32_e32 v81, v81, v82
	v_add_u32_e32 v142, 0x80, v218
	v_mul_f32_e32 v90, v80, v81
	v_cvt_pk_bf16_f32 v80, v84, v85
	v_cvt_pk_bf16_f32 v81, v86, v87
; __device__ __forceinline__ float bflo(unsigned w) { return __uint_as_float(w << 16); }
; __device__ __forceinline__ float bfhi(unsigned w) { return __uint_as_float(w & 0xffff0000u); }
; __device__ __forceinline__ float sigmoidf_(float x) { return __builtin_amdgcn_rcpf(1.0f + __expf(-x)); }
;     __device__ __forceinline__ void operator()(f32x4 (&acc)[2][2][4][2], const Unit& u, int wr, int wc, int fr, int fq, LAS unsigned char* lds) const {
;     ...
;         for (int ai = 0; ai < 2; ++ai) {
;             u32x4 ywv[4][2], swv[4][2];
; #pragma unroll
;             for (int m = 0; m < 4; ++m) {
;                 const size_t off = (size_t)(row0 + ai * HALF + m * 16) * 1024 + col0;
; #pragma unroll
;                 for (int bj = 0; bj < 2; ++bj) { ywv[m][bj] = *(const u32x4*)(Y + off + bj * HALF); swv[m][bj] = *(const u32x4*)(SG + off + bj * HALF); }
;             }
; #pragma unroll
;             for (int m = 0; m < 4; ++m) {
;                 const size_t off = (size_t)(row0 + ai * HALF + m * 16) * 1024 + col0;
; #pragma unroll
;                 for (int bj = 0; bj < 2; ++bj) {
;                     const u32x4 yw = ywv[m][bj], sw = swv[m][bj];
;                     const f32x4 z0 = acc[ai][bj][m][0] + bv[bj][0], z1 = acc[ai][bj][m][1] + bv[bj][1];
;                     f32x4 v0, v1;
;                     v0[0] = bflo(yw.x) * bflo(sw.x) * sigmoidf_(z0[0]); v0[1] = bfhi(yw.x) * bfhi(sw.x) * sigmoidf_(z0[1]);
;                     v0[2] = bflo(yw.y) * bflo(sw.y) * sigmoidf_(z0[2]); v0[3] = bfhi(yw.y) * bfhi(sw.y) * sigmoidf_(z0[3]);
;                     v1[0] = bflo(yw.z) * bflo(sw.z) * sigmoidf_(z1[0]); v1[1] = bfhi(yw.z) * bfhi(sw.z) * sigmoidf_(z1[1]);
;                     v1[2] = bflo(yw.w) * bflo(sw.w) * sigmoidf_(z1[2]); v1[3] = bfhi(yw.w) * bfhi(sw.w) * sigmoidf_(z1[3]);
;                     store8(O + off + bj * HALF, v0, v1);
;                 }
;             }
	v_ashrrev_i32_e32 v143, 31, v142
	v_cvt_pk_bf16_f32 v82, v88, v89
	v_cvt_pk_bf16_f32 v83, v83, v90
	global_store_dwordx4 v[92:93], v[80:83], off offset:256
	v_add_u32_e32 v140, 0x90, v218
	v_ashrrev_i32_e32 v141, 31, v140
	v_lshlrev_b64 v[80:81], 10, v[142:143]
	v_lshl_add_u64 v[80:81], v[80:81], 0, v[216:217]
	v_lshlrev_b64 v[80:81], 1, v[80:81]
	v_lshl_add_u64 v[82:83], s[44:45], 0, v[80:81]
	v_lshl_add_u64 v[80:81], s[42:43], 0, v[80:81]
	global_load_dwordx4 v[146:149], v[82:83], off nt
	global_load_dwordx4 v[150:153], v[80:81], off nt
	global_load_dwordx4 v[128:131], v[82:83], off offset:256 nt
	global_load_dwordx4 v[132:135], v[80:81], off offset:256 nt
	v_lshlrev_b64 v[80:81], 10, v[140:141]
	v_lshl_add_u64 v[80:81], v[80:81], 0, v[216:217]
	v_lshlrev_b64 v[80:81], 1, v[80:81]
	v_lshl_add_u64 v[82:83], s[44:45], 0, v[80:81]
	v_lshl_add_u64 v[80:81], s[42:43], 0, v[80:81]
	global_load_dwordx4 v[120:123], v[82:83], off nt
	global_load_dwordx4 v[112:115], v[82:83], off offset:256 nt
	global_load_dwordx4 v[124:127], v[80:81], off nt
	global_load_dwordx4 v[116:119], v[80:81], off offset:256 nt
	v_pk_add_f32 v[60:61], v[60:61], v[76:77]
	v_pk_add_f32 v[62:63], v[62:63], v[78:79]
	v_mul_f32_e32 v60, 0xbfb8aa3b, v60
	v_exp_f32_e32 v60, v60
	v_mul_f32_e32 v61, 0xbfb8aa3b, v61
	v_exp_f32_e32 v61, v61
	v_mul_f32_e32 v62, 0xbfb8aa3b, v62
	v_add_f32_e32 v60, 1.0, v60
	v_rcp_f32_e32 v60, v60
	v_add_f32_e32 v61, 1.0, v61
	v_rcp_f32_e32 v61, v61
	v_exp_f32_e32 v62, v62
	v_pk_add_f32 v[56:57], v[56:57], v[72:73]
	v_pk_add_f32 v[58:59], v[58:59], v[74:75]
	v_mul_f32_e32 v56, 0xbfb8aa3b, v56
	v_add_f32_e32 v62, 1.0, v62
	v_exp_f32_e32 v56, v56
	v_rcp_f32_e32 v62, v62
	v_mul_f32_e32 v57, 0xbfb8aa3b, v57
	v_exp_f32_e32 v57, v57
	v_add_f32_e32 v56, 1.0, v56
	v_rcp_f32_e32 v56, v56
	v_mul_f32_e32 v58, 0xbfb8aa3b, v58
	v_add_f32_e32 v57, 1.0, v57
	v_rcp_f32_e32 v57, v57
	v_exp_f32_e32 v58, v58
	v_add_u32_e32 v138, 0xa0, v218
	v_ashrrev_i32_e32 v139, 31, v138
	v_lshlrev_b64 v[80:81], 10, v[138:139]
	v_pk_add_f32 v[52:53], v[52:53], v[68:69]
	v_lshl_add_u64 v[80:81], v[80:81], 0, v[216:217]
	v_mul_f32_e32 v52, 0xbfb8aa3b, v52
	v_lshlrev_b64 v[80:81], 1, v[80:81]
	v_add_u32_e32 v136, 0xb0, v218
	v_exp_f32_e32 v52, v52
	v_lshl_add_u64 v[82:83], s[44:45], 0, v[80:81]
	v_lshl_add_u64 v[80:81], s[42:43], 0, v[80:81]
	v_ashrrev_i32_e32 v137, 31, v136
	v_mul_f32_e32 v53, 0xbfb8aa3b, v53
	global_load_dwordx4 v[104:107], v[82:83], off nt
	global_load_dwordx4 v[96:99], v[82:83], off offset:256 nt
	global_load_dwordx4 v[108:111], v[80:81], off nt
	global_load_dwordx4 v[100:103], v[80:81], off offset:256 nt
	v_lshlrev_b64 v[80:81], 10, v[136:137]
	v_pk_add_f32 v[54:55], v[54:55], v[70:71]
	v_exp_f32_e32 v53, v53
	v_lshl_add_u64 v[80:81], v[80:81], 0, v[216:217]
	v_mul_f32_e32 v54, 0xbfb8aa3b, v54
	v_lshlrev_b64 v[80:81], 1, v[80:81]
	v_lshlrev_b64 v[142:143], 11, v[142:143]
	v_add_f32_e32 v52, 1.0, v52
	v_exp_f32_e32 v54, v54
	v_lshl_add_u64 v[82:83], s[44:45], 0, v[80:81]
	v_lshl_add_u64 v[84:85], s[42:43], 0, v[80:81]
	v_rcp_f32_e32 v52, v52
	v_mul_f32_e32 v55, 0xbfb8aa3b, v55
	global_load_dwordx4 v[88:91], v[82:83], off nt
	s_nop 0
	global_load_dwordx4 v[80:83], v[82:83], off offset:256 nt
	s_nop 0
	global_load_dwordx4 v[92:95], v[84:85], off nt
	s_nop 0
	global_load_dwordx4 v[84:87], v[84:85], off offset:256 nt
	v_pk_add_f32 v[48:49], v[48:49], v[64:65]
	v_add_f32_e32 v53, 1.0, v53
	v_exp_f32_e32 v55, v55
	v_rcp_f32_e32 v53, v53
	v_mul_f32_e32 v48, 0xbfb8aa3b, v48
	v_add_f32_e32 v54, 1.0, v54
	v_exp_f32_e32 v48, v48
	v_rcp_f32_e32 v54, v54
	v_mul_f32_e32 v49, 0xbfb8aa3b, v49
	v_add_f32_e32 v55, 1.0, v55
	v_exp_f32_e32 v49, v49
	v_rcp_f32_e32 v55, v55
	v_add_f32_e32 v48, 1.0, v48
	v_pk_add_f32 v[50:51], v[50:51], v[66:67]
	v_rcp_f32_e32 v48, v48
	v_add_f32_e32 v49, 1.0, v49
	s_waitcnt vmcnt(15)
	v_lshlrev_b32_e32 v154, 16, v146
	s_waitcnt vmcnt(14)
	v_lshlrev_b32_e32 v155, 16, v150
	v_mul_f32_e32 v154, v155, v154
	v_mul_f32_e32 v154, v60, v154
	v_and_b32_e32 v60, 0xffff0000, v150
	v_and_b32_e32 v146, 0xffff0000, v146
	v_mul_f32_e32 v60, v60, v146
	v_mul_f32_e32 v146, v61, v60
	v_lshlrev_b32_e32 v60, 16, v147
	v_lshlrev_b32_e32 v61, 16, v151
	v_mul_f32_e32 v60, v61, v60
	v_mul_f32_e32 v61, 0xbfb8aa3b, v63
	v_exp_f32_e32 v61, v61
	v_mul_f32_e32 v62, v62, v60
	v_and_b32_e32 v60, 0xffff0000, v151
	v_and_b32_e32 v63, 0xffff0000, v147
	v_add_f32_e32 v61, 1.0, v61
	v_rcp_f32_e32 v61, v61
	v_mul_f32_e32 v60, v60, v63
	v_mul_f32_e32 v50, 0xbfb8aa3b, v50
	v_rcp_f32_e32 v49, v49
	v_mul_f32_e32 v63, v61, v60
	v_lshlrev_b32_e32 v60, 16, v148
	v_lshlrev_b32_e32 v61, 16, v152
	v_mul_f32_e32 v60, v61, v60
	v_mul_f32_e32 v147, v56, v60
	v_and_b32_e32 v56, 0xffff0000, v152
	v_and_b32_e32 v60, 0xffff0000, v148
	v_mul_f32_e32 v56, v56, v60
	v_mul_f32_e32 v148, v57, v56
	v_add_f32_e32 v57, 1.0, v58
	v_mul_f32_e32 v58, 0xbfb8aa3b, v59
	v_rcp_f32_e32 v57, v57
	v_exp_f32_e32 v58, v58
	v_lshlrev_b32_e32 v56, 16, v149
	v_lshlrev_b32_e32 v59, 16, v153
	v_mul_f32_e32 v56, v59, v56
	v_mul_f32_e32 v59, v57, v56
	v_add_f32_e32 v56, 1.0, v58
	v_rcp_f32_e32 v56, v56
	v_and_b32_e32 v57, 0xffff0000, v153
	v_and_b32_e32 v58, 0xffff0000, v149
	v_mul_f32_e32 v57, v57, v58
	v_mul_f32_e32 v149, v56, v57
	v_lshl_add_u64 v[56:57], s[26:27], 0, v[142:143]
	v_lshl_add_u64 v[60:61], v[56:57], 0, v[144:145]
	v_cvt_pk_bf16_f32 v56, v154, v146
	v_cvt_pk_bf16_f32 v57, v62, v63
	v_cvt_pk_bf16_f32 v58, v147, v148
	v_cvt_pk_bf16_f32 v59, v59, v149
	global_store_dwordx4 v[60:61], v[56:59], off
	v_exp_f32_e32 v50, v50
	v_pk_add_f32 v[44:45], v[44:45], v[76:77]
	s_waitcnt vmcnt(14)
	v_lshlrev_b32_e32 v56, 16, v128
	s_waitcnt vmcnt(13)
; __device__ __forceinline__ float bflo(unsigned w) { return __uint_as_float(w << 16); }
; __device__ __forceinline__ float bfhi(unsigned w) { return __uint_as_float(w & 0xffff0000u); }
; __device__ __forceinline__ float sigmoidf_(float x) { return __builtin_amdgcn_rcpf(1.0f + __expf(-x)); }
;     __device__ __forceinline__ void operator()(f32x4 (&acc)[2][2][4][2], const Unit& u, int wr, int wc, int fr, int fq, LAS unsigned char* lds) const {
;     ...
;             for (int m = 0; m < 4; ++m) {
;                 const size_t off = (size_t)(row0 + ai * HALF + m * 16) * 1024 + col0;
; #pragma unroll
;                 for (int bj = 0; bj < 2; ++bj) {
;                     const u32x4 yw = ywv[m][bj], sw = swv[m][bj];
;                     const f32x4 z0 = acc[ai][bj][m][0] + bv[bj][0], z1 = acc[ai][bj][m][1] + bv[bj][1];
;                     f32x4 v0, v1;
;                     v0[0] = bflo(yw.x) * bflo(sw.x) * sigmoidf_(z0[0]); v0[1] = bfhi(yw.x) * bfhi(sw.x) * sigmoidf_(z0[1]);
;                     v0[2] = bflo(yw.y) * bflo(sw.y) * sigmoidf_(z0[2]); v0[3] = bfhi(yw.y) * bfhi(sw.y) * sigmoidf_(z0[3]);
;                     v1[0] = bflo(yw.z) * bflo(sw.z) * sigmoidf_(z1[0]); v1[1] = bfhi(yw.z) * bfhi(sw.z) * sigmoidf_(z1[1]);
;                     v1[2] = bflo(yw.w) * bflo(sw.w) * sigmoidf_(z1[2]); v1[3] = bfhi(yw.w) * bfhi(sw.w) * sigmoidf_(z1[3]);
;                     store8(O + off + bj * HALF, v0, v1);
;                 }
;             }
	v_lshlrev_b32_e32 v57, 16, v132
	v_mul_f32_e32 v56, v57, v56
	v_mul_f32_e32 v52, v52, v56
	v_and_b32_e32 v56, 0xffff0000, v132
	v_and_b32_e32 v57, 0xffff0000, v128
	v_mul_f32_e32 v56, v56, v57
	v_mul_f32_e32 v53, v53, v56
	v_lshlrev_b32_e32 v56, 16, v129
	v_lshlrev_b32_e32 v57, 16, v133
	v_mul_f32_e32 v56, v57, v56
	v_mul_f32_e32 v54, v54, v56
	v_and_b32_e32 v56, 0xffff0000, v133
	v_and_b32_e32 v57, 0xffff0000, v129
	v_mul_f32_e32 v56, v56, v57
	v_mul_f32_e32 v55, v55, v56
	v_lshlrev_b32_e32 v56, 16, v130
	v_lshlrev_b32_e32 v57, 16, v134
	v_mul_f32_e32 v56, v57, v56
	v_mul_f32_e32 v56, v48, v56
	v_and_b32_e32 v48, 0xffff0000, v134
	v_and_b32_e32 v57, 0xffff0000, v130
	v_mul_f32_e32 v48, v48, v57
	v_mul_f32_e32 v57, v49, v48
	v_add_f32_e32 v49, 1.0, v50
	v_mul_f32_e32 v50, 0xbfb8aa3b, v51
	v_rcp_f32_e32 v49, v49
	v_exp_f32_e32 v50, v50
	v_lshlrev_b32_e32 v48, 16, v131
	v_lshlrev_b32_e32 v51, 16, v135
	v_mul_f32_e32 v44, 0xbfb8aa3b, v44
	v_mul_f32_e32 v48, v51, v48
	v_exp_f32_e32 v44, v44
	v_mul_f32_e32 v51, v49, v48
	v_add_f32_e32 v48, 1.0, v50
	v_mul_f32_e32 v45, 0xbfb8aa3b, v45
	v_rcp_f32_e32 v48, v48
	v_exp_f32_e32 v45, v45
	v_and_b32_e32 v49, 0xffff0000, v135
	v_and_b32_e32 v50, 0xffff0000, v131
	v_add_f32_e32 v44, 1.0, v44
	v_mul_f32_e32 v49, v49, v50
	v_rcp_f32_e32 v44, v44
	v_mul_f32_e32 v58, v48, v49
	v_cvt_pk_bf16_f32 v48, v52, v53
	v_cvt_pk_bf16_f32 v49, v54, v55
	v_cvt_pk_bf16_f32 v50, v56, v57
	v_cvt_pk_bf16_f32 v51, v51, v58
	v_add_f32_e32 v45, 1.0, v45
	global_store_dwordx4 v[60:61], v[48:51], off offset:256
	v_rcp_f32_e32 v45, v45
	v_pk_add_f32 v[46:47], v[46:47], v[78:79]
	s_waitcnt vmcnt(13)
	v_lshlrev_b32_e32 v50, 16, v120
	s_waitcnt vmcnt(11)
	v_lshlrev_b32_e32 v51, 16, v124
	v_mul_f32_e32 v50, v51, v50
	v_mul_f32_e32 v50, v44, v50
	v_and_b32_e32 v44, 0xffff0000, v124
	v_and_b32_e32 v51, 0xffff0000, v120
	v_mul_f32_e32 v44, v44, v51
	v_mul_f32_e32 v46, 0xbfb8aa3b, v46
	v_exp_f32_e32 v46, v46
	v_mul_f32_e32 v51, v45, v44
	v_lshlrev_b32_e32 v44, 16, v121
	v_lshlrev_b32_e32 v45, 16, v125
	v_mul_f32_e32 v44, v45, v44
	v_mul_f32_e32 v45, 0xbfb8aa3b, v47
	v_pk_add_f32 v[40:41], v[40:41], v[72:73]
	v_exp_f32_e32 v45, v45
	v_mul_f32_e32 v40, 0xbfb8aa3b, v40
	v_add_f32_e32 v46, 1.0, v46
	v_exp_f32_e32 v40, v40
	v_rcp_f32_e32 v46, v46
	v_mul_f32_e32 v41, 0xbfb8aa3b, v41
	v_add_f32_e32 v45, 1.0, v45
	v_exp_f32_e32 v41, v41
	v_rcp_f32_e32 v45, v45
	v_add_f32_e32 v40, 1.0, v40
	v_pk_add_f32 v[42:43], v[42:43], v[74:75]
	v_mul_f32_e32 v46, v46, v44
	v_and_b32_e32 v44, 0xffff0000, v125
	v_and_b32_e32 v47, 0xffff0000, v121
	v_rcp_f32_e32 v40, v40
	v_mul_f32_e32 v44, v44, v47
	v_add_f32_e32 v41, 1.0, v41
	v_mul_f32_e32 v42, 0xbfb8aa3b, v42
	v_mul_f32_e32 v47, v45, v44
	v_lshlrev_b32_e32 v44, 16, v122
	v_lshlrev_b32_e32 v45, 16, v126
	v_rcp_f32_e32 v41, v41
	v_exp_f32_e32 v42, v42
	v_mul_f32_e32 v44, v45, v44
	v_mul_f32_e32 v52, v40, v44
	v_and_b32_e32 v40, 0xffff0000, v126
	v_and_b32_e32 v44, 0xffff0000, v122
	v_mul_f32_e32 v40, v40, v44
	v_mul_f32_e32 v53, v41, v40
	v_add_f32_e32 v41, 1.0, v42
	v_mul_f32_e32 v42, 0xbfb8aa3b, v43
	v_rcp_f32_e32 v41, v41
	v_exp_f32_e32 v42, v42
	v_lshlrev_b32_e32 v40, 16, v123
	v_lshlrev_b32_e32 v43, 16, v127
	v_pk_add_f32 v[36:37], v[36:37], v[68:69]
	v_mul_f32_e32 v40, v43, v40
	v_mul_f32_e32 v36, 0xbfb8aa3b, v36
	v_mul_f32_e32 v43, v41, v40
	v_add_f32_e32 v40, 1.0, v42
	v_exp_f32_e32 v36, v36
	v_rcp_f32_e32 v40, v40
	v_mul_f32_e32 v37, 0xbfb8aa3b, v37
	v_pk_add_f32 v[38:39], v[38:39], v[70:71]
	v_exp_f32_e32 v37, v37
	v_and_b32_e32 v41, 0xffff0000, v127
	v_and_b32_e32 v42, 0xffff0000, v123
	v_mul_f32_e32 v38, 0xbfb8aa3b, v38
	v_lshlrev_b64 v[48:49], 11, v[140:141]
	v_mul_f32_e32 v41, v41, v42
	v_add_f32_e32 v36, 1.0, v36
	v_exp_f32_e32 v38, v38
	v_mul_f32_e32 v54, v40, v41
	v_lshl_add_u64 v[40:41], s[26:27], 0, v[48:49]
	v_rcp_f32_e32 v36, v36
	v_mul_f32_e32 v39, 0xbfb8aa3b, v39
	v_lshl_add_u64 v[44:45], v[40:41], 0, v[144:145]
	v_cvt_pk_bf16_f32 v40, v50, v51
	v_cvt_pk_bf16_f32 v41, v46, v47
	v_pk_add_f32 v[32:33], v[32:33], v[64:65]
	v_add_f32_e32 v37, 1.0, v37
	v_exp_f32_e32 v39, v39
	v_cvt_pk_bf16_f32 v42, v52, v53
	v_cvt_pk_bf16_f32 v43, v43, v54
	global_store_dwordx4 v[44:45], v[40:43], off
	v_rcp_f32_e32 v37, v37
	v_mul_f32_e32 v32, 0xbfb8aa3b, v32
	v_lshlrev_b32_e32 v40, 16, v112
	s_waitcnt vmcnt(11)
	v_lshlrev_b32_e32 v41, 16, v116
	v_mul_f32_e32 v40, v41, v40
	v_add_f32_e32 v38, 1.0, v38
	v_exp_f32_e32 v32, v32
	v_mul_f32_e32 v36, v36, v40
	v_and_b32_e32 v40, 0xffff0000, v116
	v_and_b32_e32 v41, 0xffff0000, v112
	v_rcp_f32_e32 v38, v38
	v_mul_f32_e32 v33, 0xbfb8aa3b, v33
	v_mul_f32_e32 v40, v40, v41
	v_add_f32_e32 v39, 1.0, v39
	v_exp_f32_e32 v33, v33
	v_mul_f32_e32 v37, v37, v40
	v_lshlrev_b32_e32 v40, 16, v113
	v_lshlrev_b32_e32 v41, 16, v117
	v_rcp_f32_e32 v39, v39
	v_mul_f32_e32 v40, v41, v40
	v_add_f32_e32 v32, 1.0, v32
	v_pk_add_f32 v[34:35], v[34:35], v[66:67]
	v_mul_f32_e32 v38, v38, v40
	v_and_b32_e32 v40, 0xffff0000, v117
	v_and_b32_e32 v41, 0xffff0000, v113
	v_rcp_f32_e32 v32, v32
	v_mul_f32_e32 v40, v40, v41
	v_add_f32_e32 v33, 1.0, v33
	v_mul_f32_e32 v34, 0xbfb8aa3b, v34
	v_mul_f32_e32 v39, v39, v40
	v_lshlrev_b32_e32 v40, 16, v114
	v_lshlrev_b32_e32 v41, 16, v118
	v_rcp_f32_e32 v33, v33
	v_exp_f32_e32 v34, v34
	v_mul_f32_e32 v40, v41, v40
	v_mul_f32_e32 v40, v32, v40
	v_and_b32_e32 v32, 0xffff0000, v118
	v_and_b32_e32 v41, 0xffff0000, v114
	v_mul_f32_e32 v32, v32, v41
	v_mul_f32_e32 v41, v33, v32
	v_add_f32_e32 v33, 1.0, v34
	v_mul_f32_e32 v34, 0xbfb8aa3b, v35
	v_rcp_f32_e32 v33, v33
	v_exp_f32_e32 v34, v34
	v_pk_add_f32 v[28:29], v[28:29], v[76:77]
	v_lshlrev_b32_e32 v32, 16, v115
	v_lshlrev_b32_e32 v35, 16, v119
	v_mul_f32_e32 v28, 0xbfb8aa3b, v28
	v_mul_f32_e32 v32, v35, v32
	v_exp_f32_e32 v28, v28
	v_mul_f32_e32 v35, v33, v32
	v_add_f32_e32 v32, 1.0, v34
	v_mul_f32_e32 v29, 0xbfb8aa3b, v29
	v_rcp_f32_e32 v32, v32
	v_exp_f32_e32 v29, v29
	v_and_b32_e32 v33, 0xffff0000, v119
	v_and_b32_e32 v34, 0xffff0000, v115
	v_add_f32_e32 v28, 1.0, v28
	v_mul_f32_e32 v33, v33, v34
	v_rcp_f32_e32 v28, v28
	v_mul_f32_e32 v42, v32, v33
	v_cvt_pk_bf16_f32 v32, v36, v37
	v_cvt_pk_bf16_f32 v33, v38, v39
	v_cvt_pk_bf16_f32 v34, v40, v41
	v_cvt_pk_bf16_f32 v35, v35, v42
	v_add_f32_e32 v29, 1.0, v29
	global_store_dwordx4 v[44:45], v[32:35], off offset:256
	v_rcp_f32_e32 v29, v29
	v_pk_add_f32 v[30:31], v[30:31], v[78:79]
	s_waitcnt vmcnt(11)
; __device__ __forceinline__ float bflo(unsigned w) { return __uint_as_float(w << 16); }
; __device__ __forceinline__ float bfhi(unsigned w) { return __uint_as_float(w & 0xffff0000u); }
; __device__ __forceinline__ float sigmoidf_(float x) { return __builtin_amdgcn_rcpf(1.0f + __expf(-x)); }
;     __device__ __forceinline__ void operator()(f32x4 (&acc)[2][2][4][2], const Unit& u, int wr, int wc, int fr, int fq, LAS unsigned char* lds) const {
;     ...
;             for (int m = 0; m < 4; ++m) {
;                 const size_t off = (size_t)(row0 + ai * HALF + m * 16) * 1024 + col0;
; #pragma unroll
;                 for (int bj = 0; bj < 2; ++bj) {
;                     const u32x4 yw = ywv[m][bj], sw = swv[m][bj];
;                     const f32x4 z0 = acc[ai][bj][m][0] + bv[bj][0], z1 = acc[ai][bj][m][1] + bv[bj][1];
;                     f32x4 v0, v1;
;                     v0[0] = bflo(yw.x) * bflo(sw.x) * sigmoidf_(z0[0]); v0[1] = bfhi(yw.x) * bfhi(sw.x) * sigmoidf_(z0[1]);
;                     v0[2] = bflo(yw.y) * bflo(sw.y) * sigmoidf_(z0[2]); v0[3] = bfhi(yw.y) * bfhi(sw.y) * sigmoidf_(z0[3]);
;                     v1[0] = bflo(yw.z) * bflo(sw.z) * sigmoidf_(z1[0]); v1[1] = bfhi(yw.z) * bfhi(sw.z) * sigmoidf_(z1[1]);
;                     v1[2] = bflo(yw.w) * bflo(sw.w) * sigmoidf_(z1[2]); v1[3] = bfhi(yw.w) * bfhi(sw.w) * sigmoidf_(z1[3]);
;                     store8(O + off + bj * HALF, v0, v1);
;                 }
;             }
	v_lshlrev_b32_e32 v34, 16, v104
	s_waitcnt vmcnt(9)
	v_lshlrev_b32_e32 v35, 16, v108
	v_mul_f32_e32 v34, v35, v34
	v_mul_f32_e32 v34, v28, v34
	v_and_b32_e32 v28, 0xffff0000, v108
	v_and_b32_e32 v35, 0xffff0000, v104
	v_mul_f32_e32 v28, v28, v35
	v_mul_f32_e32 v30, 0xbfb8aa3b, v30
	v_exp_f32_e32 v30, v30
	v_mul_f32_e32 v35, v29, v28
	v_lshlrev_b32_e32 v28, 16, v105
	v_lshlrev_b32_e32 v29, 16, v109
	v_mul_f32_e32 v28, v29, v28
	v_mul_f32_e32 v29, 0xbfb8aa3b, v31
	v_pk_add_f32 v[24:25], v[24:25], v[72:73]
	v_exp_f32_e32 v29, v29
	v_mul_f32_e32 v24, 0xbfb8aa3b, v24
	v_add_f32_e32 v30, 1.0, v30
	v_exp_f32_e32 v24, v24
	v_rcp_f32_e32 v30, v30
	v_mul_f32_e32 v25, 0xbfb8aa3b, v25
	v_add_f32_e32 v29, 1.0, v29
	v_exp_f32_e32 v25, v25
	v_rcp_f32_e32 v29, v29
	v_add_f32_e32 v24, 1.0, v24
	v_pk_add_f32 v[26:27], v[26:27], v[74:75]
	v_mul_f32_e32 v30, v30, v28
	v_and_b32_e32 v28, 0xffff0000, v109
	v_and_b32_e32 v31, 0xffff0000, v105
	v_rcp_f32_e32 v24, v24
	v_mul_f32_e32 v28, v28, v31
	v_add_f32_e32 v25, 1.0, v25
	v_mul_f32_e32 v26, 0xbfb8aa3b, v26
	v_mul_f32_e32 v31, v29, v28
	v_lshlrev_b32_e32 v28, 16, v106
	v_lshlrev_b32_e32 v29, 16, v110
	v_rcp_f32_e32 v25, v25
	v_exp_f32_e32 v26, v26
	v_mul_f32_e32 v28, v29, v28
	v_mul_f32_e32 v36, v24, v28
	v_and_b32_e32 v24, 0xffff0000, v110
	v_and_b32_e32 v28, 0xffff0000, v106
	v_mul_f32_e32 v24, v24, v28
	v_mul_f32_e32 v37, v25, v24
	v_add_f32_e32 v25, 1.0, v26
	v_mul_f32_e32 v26, 0xbfb8aa3b, v27
	v_rcp_f32_e32 v25, v25
	v_exp_f32_e32 v26, v26
	v_lshlrev_b32_e32 v24, 16, v107
	v_lshlrev_b32_e32 v27, 16, v111
	v_pk_add_f32 v[20:21], v[20:21], v[68:69]
	v_mul_f32_e32 v24, v27, v24
	v_mul_f32_e32 v20, 0xbfb8aa3b, v20
	v_mul_f32_e32 v27, v25, v24
	v_add_f32_e32 v24, 1.0, v26
	v_exp_f32_e32 v20, v20
	v_rcp_f32_e32 v24, v24
	v_mul_f32_e32 v21, 0xbfb8aa3b, v21
	v_pk_add_f32 v[22:23], v[22:23], v[70:71]
	v_exp_f32_e32 v21, v21
	v_and_b32_e32 v25, 0xffff0000, v111
	v_and_b32_e32 v26, 0xffff0000, v107
	v_mul_f32_e32 v22, 0xbfb8aa3b, v22
	v_lshlrev_b64 v[32:33], 11, v[138:139]
	v_mul_f32_e32 v25, v25, v26
	v_add_f32_e32 v20, 1.0, v20
	v_exp_f32_e32 v22, v22
	v_mul_f32_e32 v38, v24, v25
	v_lshl_add_u64 v[24:25], s[26:27], 0, v[32:33]
	v_rcp_f32_e32 v20, v20
	v_mul_f32_e32 v23, 0xbfb8aa3b, v23
	v_lshl_add_u64 v[28:29], v[24:25], 0, v[144:145]
	v_cvt_pk_bf16_f32 v24, v34, v35
	v_cvt_pk_bf16_f32 v25, v30, v31
	v_pk_add_f32 v[16:17], v[16:17], v[64:65]
	v_add_f32_e32 v21, 1.0, v21
	v_exp_f32_e32 v23, v23
	v_cvt_pk_bf16_f32 v26, v36, v37
	v_cvt_pk_bf16_f32 v27, v27, v38
	global_store_dwordx4 v[28:29], v[24:27], off
	v_rcp_f32_e32 v21, v21
	v_mul_f32_e32 v16, 0xbfb8aa3b, v16
	v_lshlrev_b32_e32 v24, 16, v96
	s_waitcnt vmcnt(9)
	v_lshlrev_b32_e32 v25, 16, v100
	v_mul_f32_e32 v24, v25, v24
	v_add_f32_e32 v22, 1.0, v22
	v_exp_f32_e32 v16, v16
	v_mul_f32_e32 v20, v20, v24
	v_and_b32_e32 v24, 0xffff0000, v100
	v_and_b32_e32 v25, 0xffff0000, v96
	v_rcp_f32_e32 v22, v22
	v_mul_f32_e32 v17, 0xbfb8aa3b, v17
	v_mul_f32_e32 v24, v24, v25
	v_add_f32_e32 v23, 1.0, v23
	v_exp_f32_e32 v17, v17
	v_mul_f32_e32 v21, v21, v24
	v_lshlrev_b32_e32 v24, 16, v97
	v_lshlrev_b32_e32 v25, 16, v101
	v_rcp_f32_e32 v23, v23
	v_mul_f32_e32 v24, v25, v24
	v_add_f32_e32 v16, 1.0, v16
	v_pk_add_f32 v[18:19], v[18:19], v[66:67]
	v_mul_f32_e32 v22, v22, v24
	v_and_b32_e32 v24, 0xffff0000, v101
	v_and_b32_e32 v25, 0xffff0000, v97
	v_rcp_f32_e32 v16, v16
	v_mul_f32_e32 v24, v24, v25
	v_add_f32_e32 v17, 1.0, v17
	v_mul_f32_e32 v18, 0xbfb8aa3b, v18
	v_mul_f32_e32 v23, v23, v24
	v_lshlrev_b32_e32 v24, 16, v98
	v_lshlrev_b32_e32 v25, 16, v102
	v_rcp_f32_e32 v17, v17
	v_exp_f32_e32 v18, v18
	v_mul_f32_e32 v24, v25, v24
	v_mul_f32_e32 v24, v16, v24
	v_and_b32_e32 v16, 0xffff0000, v102
	v_and_b32_e32 v25, 0xffff0000, v98
	v_mul_f32_e32 v16, v16, v25
	v_mul_f32_e32 v25, v17, v16
	v_add_f32_e32 v17, 1.0, v18
	v_mul_f32_e32 v18, 0xbfb8aa3b, v19
	v_rcp_f32_e32 v17, v17
	v_exp_f32_e32 v18, v18
	v_pk_add_f32 v[12:13], v[12:13], v[76:77]
	v_lshlrev_b32_e32 v16, 16, v99
	v_lshlrev_b32_e32 v19, 16, v103
	v_mul_f32_e32 v12, 0xbfb8aa3b, v12
	v_mul_f32_e32 v16, v19, v16
	v_exp_f32_e32 v12, v12
	v_mul_f32_e32 v19, v17, v16
	v_add_f32_e32 v16, 1.0, v18
	v_mul_f32_e32 v13, 0xbfb8aa3b, v13
	v_rcp_f32_e32 v16, v16
	v_exp_f32_e32 v13, v13
	v_and_b32_e32 v17, 0xffff0000, v103
	v_and_b32_e32 v18, 0xffff0000, v99
	v_add_f32_e32 v12, 1.0, v12
	v_mul_f32_e32 v17, v17, v18
	v_rcp_f32_e32 v12, v12
	v_mul_f32_e32 v26, v16, v17
	v_cvt_pk_bf16_f32 v16, v20, v21
	v_cvt_pk_bf16_f32 v17, v22, v23
	v_cvt_pk_bf16_f32 v18, v24, v25
	v_cvt_pk_bf16_f32 v19, v19, v26
	v_add_f32_e32 v13, 1.0, v13
	global_store_dwordx4 v[28:29], v[16:19], off offset:256
	v_rcp_f32_e32 v13, v13
	v_pk_add_f32 v[14:15], v[14:15], v[78:79]
	s_waitcnt vmcnt(9)
; __device__ __forceinline__ float bflo(unsigned w) { return __uint_as_float(w << 16); }
; __device__ __forceinline__ float bfhi(unsigned w) { return __uint_as_float(w & 0xffff0000u); }
; __device__ __forceinline__ float sigmoidf_(float x) { return __builtin_amdgcn_rcpf(1.0f + __expf(-x)); }
; #define PG8_BAR __builtin_amdgcn_s_barrier()
; template <class Epi, bool ALIGN_EPI = true, bool SP2 = true>
; __device__ __forceinline__ void gemm_phase(LAS unsigned char* lds, const Gemm g, const StaticOrder& S, const Epi& E) {
;     ...
;         cur = nxt; cB = nB; ++ui;
;         if constexpr (ALIGN_EPI) { if (wr == 1) PG8_BAR; }
;     __device__ __forceinline__ void operator()(f32x4 (&acc)[2][2][4][2], const Unit& u, int wr, int wc, int fr, int fq, LAS unsigned char* lds) const {
;     ...
;             for (int m = 0; m < 4; ++m) {
;                 const size_t off = (size_t)(row0 + ai * HALF + m * 16) * 1024 + col0;
; #pragma unroll
;                 for (int bj = 0; bj < 2; ++bj) {
;                     const u32x4 yw = ywv[m][bj], sw = swv[m][bj];
;                     const f32x4 z0 = acc[ai][bj][m][0] + bv[bj][0], z1 = acc[ai][bj][m][1] + bv[bj][1];
;                     f32x4 v0, v1;
;                     v0[0] = bflo(yw.x) * bflo(sw.x) * sigmoidf_(z0[0]); v0[1] = bfhi(yw.x) * bfhi(sw.x) * sigmoidf_(z0[1]);
;                     v0[2] = bflo(yw.y) * bflo(sw.y) * sigmoidf_(z0[2]); v0[3] = bfhi(yw.y) * bfhi(sw.y) * sigmoidf_(z0[3]);
;                     v1[0] = bflo(yw.z) * bflo(sw.z) * sigmoidf_(z1[0]); v1[1] = bfhi(yw.z) * bfhi(sw.z) * sigmoidf_(z1[1]);
;                     v1[2] = bflo(yw.w) * bflo(sw.w) * sigmoidf_(z1[2]); v1[3] = bfhi(yw.w) * bfhi(sw.w) * sigmoidf_(z1[3]);
;                     store8(O + off + bj * HALF, v0, v1);
;                 }
;             }
	v_lshlrev_b32_e32 v18, 16, v88
	s_waitcnt vmcnt(7)
	v_lshlrev_b32_e32 v19, 16, v92
	v_mul_f32_e32 v18, v19, v18
	v_mul_f32_e32 v18, v12, v18
	v_and_b32_e32 v12, 0xffff0000, v92
	v_and_b32_e32 v19, 0xffff0000, v88
	v_mul_f32_e32 v12, v12, v19
	v_mul_f32_e32 v14, 0xbfb8aa3b, v14
	v_exp_f32_e32 v14, v14
	v_mul_f32_e32 v19, v13, v12
	v_lshlrev_b32_e32 v12, 16, v89
	v_lshlrev_b32_e32 v13, 16, v93
	v_mul_f32_e32 v12, v13, v12
	v_mul_f32_e32 v13, 0xbfb8aa3b, v15
	v_pk_add_f32 v[8:9], v[8:9], v[72:73]
	v_exp_f32_e32 v13, v13
	v_mul_f32_e32 v8, 0xbfb8aa3b, v8
	v_add_f32_e32 v14, 1.0, v14
	v_exp_f32_e32 v8, v8
	v_rcp_f32_e32 v14, v14
	v_mul_f32_e32 v9, 0xbfb8aa3b, v9
	v_add_f32_e32 v13, 1.0, v13
	v_exp_f32_e32 v9, v9
	v_rcp_f32_e32 v13, v13
	v_add_f32_e32 v8, 1.0, v8
	v_pk_add_f32 v[10:11], v[10:11], v[74:75]
	v_mul_f32_e32 v14, v14, v12
	v_and_b32_e32 v12, 0xffff0000, v93
	v_and_b32_e32 v15, 0xffff0000, v89
	v_rcp_f32_e32 v8, v8
	v_mul_f32_e32 v12, v12, v15
	v_add_f32_e32 v9, 1.0, v9
	v_mul_f32_e32 v10, 0xbfb8aa3b, v10
	v_mul_f32_e32 v15, v13, v12
	v_lshlrev_b32_e32 v12, 16, v90
	v_lshlrev_b32_e32 v13, 16, v94
	v_rcp_f32_e32 v9, v9
	v_exp_f32_e32 v10, v10
	v_mul_f32_e32 v12, v13, v12
	v_mul_f32_e32 v20, v8, v12
	v_and_b32_e32 v8, 0xffff0000, v94
	v_and_b32_e32 v12, 0xffff0000, v90
	v_mul_f32_e32 v8, v8, v12
	v_mul_f32_e32 v21, v9, v8
	v_add_f32_e32 v9, 1.0, v10
	v_mul_f32_e32 v10, 0xbfb8aa3b, v11
	v_rcp_f32_e32 v9, v9
	v_exp_f32_e32 v10, v10
	v_lshlrev_b32_e32 v8, 16, v91
	v_lshlrev_b32_e32 v11, 16, v95
	v_pk_add_f32 v[4:5], v[4:5], v[68:69]
	v_mul_f32_e32 v8, v11, v8
	v_mul_f32_e32 v4, 0xbfb8aa3b, v4
	v_mul_f32_e32 v11, v9, v8
	v_add_f32_e32 v8, 1.0, v10
	v_exp_f32_e32 v4, v4
	v_rcp_f32_e32 v8, v8
	v_mul_f32_e32 v5, 0xbfb8aa3b, v5
	v_pk_add_f32 v[6:7], v[6:7], v[70:71]
	v_exp_f32_e32 v5, v5
	v_and_b32_e32 v9, 0xffff0000, v95
	v_and_b32_e32 v10, 0xffff0000, v91
	v_mul_f32_e32 v6, 0xbfb8aa3b, v6
	v_lshlrev_b64 v[16:17], 11, v[136:137]
	v_mul_f32_e32 v9, v9, v10
	v_add_f32_e32 v4, 1.0, v4
	v_exp_f32_e32 v6, v6
	v_mul_f32_e32 v22, v8, v9
	v_lshl_add_u64 v[8:9], s[26:27], 0, v[16:17]
	v_rcp_f32_e32 v4, v4
	v_mul_f32_e32 v7, 0xbfb8aa3b, v7
	v_lshl_add_u64 v[12:13], v[8:9], 0, v[144:145]
	v_cvt_pk_bf16_f32 v8, v18, v19
	v_cvt_pk_bf16_f32 v9, v14, v15
	v_pk_add_f32 v[0:1], v[0:1], v[64:65]
	v_add_f32_e32 v5, 1.0, v5
	v_exp_f32_e32 v7, v7
	v_cvt_pk_bf16_f32 v10, v20, v21
	v_cvt_pk_bf16_f32 v11, v11, v22
	global_store_dwordx4 v[12:13], v[8:11], off
	v_rcp_f32_e32 v5, v5
	v_mul_f32_e32 v0, 0xbfb8aa3b, v0
	v_lshlrev_b32_e32 v8, 16, v80
	s_waitcnt vmcnt(7)
	v_lshlrev_b32_e32 v9, 16, v84
	v_mul_f32_e32 v8, v9, v8
	v_add_f32_e32 v6, 1.0, v6
	v_exp_f32_e32 v0, v0
	v_mul_f32_e32 v4, v4, v8
	v_and_b32_e32 v8, 0xffff0000, v84
	v_and_b32_e32 v9, 0xffff0000, v80
	v_rcp_f32_e32 v6, v6
	v_mul_f32_e32 v1, 0xbfb8aa3b, v1
	v_mul_f32_e32 v8, v8, v9
	v_add_f32_e32 v7, 1.0, v7
	v_exp_f32_e32 v1, v1
	v_mul_f32_e32 v5, v5, v8
	v_lshlrev_b32_e32 v8, 16, v81
	v_lshlrev_b32_e32 v9, 16, v85
	v_rcp_f32_e32 v7, v7
	v_mul_f32_e32 v8, v9, v8
	v_add_f32_e32 v0, 1.0, v0
	v_pk_add_f32 v[2:3], v[2:3], v[66:67]
	v_mul_f32_e32 v6, v6, v8
	v_and_b32_e32 v8, 0xffff0000, v85
	v_and_b32_e32 v9, 0xffff0000, v81
	v_rcp_f32_e32 v0, v0
	v_mul_f32_e32 v8, v8, v9
	v_add_f32_e32 v1, 1.0, v1
	v_mul_f32_e32 v2, 0xbfb8aa3b, v2
	v_mul_f32_e32 v7, v7, v8
	v_lshlrev_b32_e32 v8, 16, v82
	v_lshlrev_b32_e32 v9, 16, v86
	v_rcp_f32_e32 v1, v1
	v_exp_f32_e32 v2, v2
	v_mul_f32_e32 v8, v9, v8
	v_mul_f32_e32 v8, v0, v8
	v_and_b32_e32 v0, 0xffff0000, v86
	v_and_b32_e32 v9, 0xffff0000, v82
	v_mul_f32_e32 v0, v0, v9
	v_mul_f32_e32 v9, v1, v0
	v_add_f32_e32 v1, 1.0, v2
	v_mul_f32_e32 v2, 0xbfb8aa3b, v3
	v_rcp_f32_e32 v1, v1
	v_exp_f32_e32 v2, v2
	v_lshlrev_b32_e32 v0, 16, v83
	v_lshlrev_b32_e32 v3, 16, v87
	v_mul_f32_e32 v0, v3, v0
	v_mul_f32_e32 v3, v1, v0
	v_add_f32_e32 v0, 1.0, v2
	v_rcp_f32_e32 v0, v0
	v_and_b32_e32 v1, 0xffff0000, v87
	v_and_b32_e32 v2, 0xffff0000, v83
	v_mul_f32_e32 v1, v1, v2
	v_mul_f32_e32 v10, v0, v1
	v_cvt_pk_bf16_f32 v0, v4, v5
	v_cvt_pk_bf16_f32 v1, v6, v7
	v_cvt_pk_bf16_f32 v2, v8, v9
	v_cvt_pk_bf16_f32 v3, v3, v10
	global_store_dwordx4 v[12:13], v[0:3], off offset:256
	s_cbranch_vccnz .LBB0_1153
	s_andn2_b64 vcc, exec, s[8:9]
	s_cbranch_vccnz .LBB0_1152
	s_barrier
	s_branch .LBB0_1152

; #define LAS __attribute__((address_space(3)))
; __device__ __forceinline__ float bflo(unsigned w) { return __uint_as_float(w << 16); }
; __device__ __forceinline__ float bfhi(unsigned w) { return __uint_as_float(w & 0xffff0000u); }
;     __device__ __forceinline__ void operator()(f32x4 (&acc)[2][2][4][2], const Unit& u, int wr, int wc, int fr, int fq, LAS unsigned char* lds) const {
;         const int b = (u.pm * BM) / SEQ;
;         const int row0 = u.pm * BM + wr * 64 + fr, col0 = u.pn * BM + wc * 32 + 8 * fq;
;         f32x4 gv[2][2];
; #pragma unroll
;         for (int bj = 0; bj < 2; ++bj)
; #pragma unroll
;             for (int n = 0; n < 2; ++n) gv[bj][n] = *(const f32x4*)(gate + b * 3072 + col0 + bj * HALF + 4 * n);
; #pragma unroll
;         for (int ai = 0; ai < 2; ++ai) {
;             u32x4 xw[4][2];
; #pragma unroll
;             for (int m = 0; m < 4; ++m) {
;                 const size_t off = (size_t)(row0 + ai * HALF + m * 16) * 1024 + col0;
; #pragma unroll
;                 for (int bj = 0; bj < 2; ++bj) xw[m][bj] = *(const u32x4*)(base + off + bj * HALF);
;             }
; #pragma unroll
;             for (int m = 0; m < 4; ++m) {
;                 const size_t off = (size_t)(row0 + ai * HALF + m * 16) * 1024 + col0;
; #pragma unroll
;                 for (int bj = 0; bj < 2; ++bj) {
;                     const u32x4 w = xw[m][bj];
;                     const f32x4 x0 = (f32x4){bflo(w.x), bfhi(w.x), bflo(w.y), bfhi(w.y)}, x1 = (f32x4){bflo(w.z), bfhi(w.z), bflo(w.w), bfhi(w.w)};
;                     *(f32x4*)(out + off + bj * HALF) = x0 + gv[bj][0] * acc[ai][bj][m][0];
;                     *(f32x4*)(out + off + bj * HALF + 4) = x1 + gv[bj][1] * acc[ai][bj][m][1];
;                 }
;             }
;             asm volatile("" ::: "memory");
;         }
;     }
.LBB0_1237:
	s_lshr_b32 s4, s17, 27
	s_add_i32 s4, s16, s4
	s_lshr_b32 s4, s4, 5
	v_lshl_or_b32 v128, s52, 8, v170
	v_lshl_add_u32 v164, s16, 8, v168
	s_mul_i32 s16, s4, 0xc00
	v_ashrrev_i32_e32 v129, 31, v128
	v_ashrrev_i32_e32 v165, 31, v164
	s_ashr_i32 s17, s16, 31
	v_lshl_add_u64 v[162:163], v[128:129], 1, s[30:31]
	v_lshlrev_b64 v[130:131], 11, v[164:165]
	v_or_b32_e32 v194, 16, v164
	s_lshl_b64 s[16:17], s[16:17], 2
	v_lshl_add_u64 v[130:131], v[162:163], 0, v[130:131]
	v_ashrrev_i32_e32 v195, 31, v194
	s_add_u32 s16, s44, s16
	global_load_dwordx4 v[174:177], v[130:131], off nt
	global_load_dwordx4 v[178:181], v[130:131], off offset:256 nt
	v_lshlrev_b64 v[130:131], 11, v[194:195]
	v_lshlrev_b64 v[160:161], 2, v[128:129]
	s_addc_u32 s17, s45, s17
	v_lshl_add_u64 v[130:131], v[162:163], 0, v[130:131]
	v_lshl_add_u64 v[128:129], s[16:17], 0, v[160:161]
	v_or_b32_e32 v206, 32, v164
	global_load_dwordx4 v[182:185], v[130:131], off nt
	global_load_dwordx4 v[186:189], v[130:131], off offset:256 nt
	global_load_dwordx4 v[140:143], v[128:129], off nt
	global_load_dwordx4 v[136:139], v[128:129], off offset:16 nt
	global_load_dwordx4 v[132:135], v[128:129], off offset:512 nt
	s_nop 0
	global_load_dwordx4 v[128:131], v[128:129], off offset:528 nt
	v_ashrrev_i32_e32 v207, 31, v206
	v_lshlrev_b64 v[166:167], 11, v[206:207]
	v_lshl_add_u64 v[196:197], v[162:163], 0, v[166:167]
	global_load_dwordx4 v[190:193], v[196:197], off nt
	v_or_b32_e32 v166, 48, v164
	v_ashrrev_i32_e32 v167, 31, v166
	v_lshlrev_b64 v[202:203], 12, v[194:195]
	global_load_dwordx4 v[194:197], v[196:197], off offset:256 nt
	v_lshlrev_b64 v[198:199], 12, v[164:165]
	v_lshlrev_b64 v[200:201], 11, v[166:167]
	v_lshl_add_u64 v[198:199], s[76:77], 0, v[198:199]
	v_lshl_add_u64 v[204:205], v[162:163], 0, v[200:201]
	v_lshl_add_u64 v[208:209], v[198:199], 0, v[160:161]
	v_lshl_add_u64 v[210:211], s[76:77], 0, v[202:203]
	global_load_dwordx4 v[198:201], v[204:205], off nt
	s_nop 0
	global_load_dwordx4 v[202:205], v[204:205], off offset:256 nt
	v_lshl_add_u64 v[210:211], v[210:211], 0, v[160:161]
	s_andn2_b64 vcc, exec, s[0:1]
	s_mov_b64 s[0:1], -1
	s_waitcnt vmcnt(0)
	v_lshlrev_b32_e32 v212, 16, v174
	v_and_b32_e32 v213, 0xffff0000, v174
	v_lshlrev_b32_e32 v174, 16, v175
	v_and_b32_e32 v175, 0xffff0000, v175
	v_lshlrev_b32_e32 v216, 16, v178
	v_and_b32_e32 v217, 0xffff0000, v178
	v_lshlrev_b32_e32 v218, 16, v180
	v_and_b32_e32 v219, 0xffff0000, v180
	v_lshlrev_b32_e32 v180, 16, v181
	v_and_b32_e32 v181, 0xffff0000, v181
	v_lshlrev_b32_e32 v214, 16, v176
	v_and_b32_e32 v215, 0xffff0000, v176
	v_lshlrev_b32_e32 v176, 16, v177
	v_and_b32_e32 v177, 0xffff0000, v177
	v_lshlrev_b32_e32 v178, 16, v179
	v_and_b32_e32 v179, 0xffff0000, v179
	v_lshlrev_b32_e32 v220, 16, v182
	v_and_b32_e32 v221, 0xffff0000, v182
	v_lshlrev_b32_e32 v182, 16, v183
	v_and_b32_e32 v183, 0xffff0000, v183
	v_lshlrev_b32_e32 v222, 16, v184
	v_and_b32_e32 v223, 0xffff0000, v184
	v_lshlrev_b32_e32 v184, 16, v185
	v_and_b32_e32 v185, 0xffff0000, v185
	v_pk_fma_f32 v[124:125], v[124:125], v[140:141], v[212:213]
	v_pk_fma_f32 v[126:127], v[126:127], v[142:143], v[174:175]
	v_pk_fma_f32 v[108:109], v[108:109], v[132:133], v[216:217]
	v_pk_fma_f32 v[106:107], v[106:107], v[130:131], v[180:181]
	v_pk_fma_f32 v[120:121], v[120:121], v[136:137], v[214:215]
	v_pk_fma_f32 v[122:123], v[122:123], v[138:139], v[176:177]
	v_pk_fma_f32 v[110:111], v[110:111], v[134:135], v[178:179]
	v_pk_fma_f32 v[104:105], v[104:105], v[128:129], v[218:219]
	v_pk_fma_f32 v[116:117], v[116:117], v[140:141], v[220:221]
	v_pk_fma_f32 v[118:119], v[118:119], v[142:143], v[182:183]
	v_pk_fma_f32 v[112:113], v[112:113], v[136:137], v[222:223]
	v_pk_fma_f32 v[114:115], v[114:115], v[138:139], v[184:185]
	global_store_dwordx4 v[208:209], v[124:127], off
	global_store_dwordx4 v[208:209], v[120:123], off offset:16
	global_store_dwordx4 v[208:209], v[108:111], off offset:512
	global_store_dwordx4 v[208:209], v[104:107], off offset:528
	global_store_dwordx4 v[210:211], v[116:119], off
	global_store_dwordx4 v[210:211], v[112:115], off offset:16
	v_lshlrev_b32_e32 v106, 16, v188
	v_and_b32_e32 v107, 0xffff0000, v188
	v_lshlrev_b32_e32 v108, 16, v189
	v_and_b32_e32 v109, 0xffff0000, v189
	v_pk_fma_f32 v[92:93], v[92:93], v[128:129], v[106:107]
	v_pk_fma_f32 v[94:95], v[94:95], v[130:131], v[108:109]
	global_store_dwordx4 v[210:211], v[92:95], off offset:528
	v_lshlrev_b32_e32 v224, 16, v186
	v_and_b32_e32 v225, 0xffff0000, v186
	v_lshlrev_b32_e32 v92, 16, v190
	v_and_b32_e32 v93, 0xffff0000, v190
	v_pk_fma_f32 v[92:93], v[96:97], v[140:141], v[92:93]
	v_lshlrev_b64 v[96:97], 12, v[206:207]
	v_lshlrev_b32_e32 v104, 16, v187
	v_and_b32_e32 v105, 0xffff0000, v187
	v_lshlrev_b32_e32 v94, 16, v191
	v_and_b32_e32 v95, 0xffff0000, v191
	v_lshl_add_u64 v[96:97], s[76:77], 0, v[96:97]
	v_pk_fma_f32 v[100:101], v[100:101], v[132:133], v[224:225]
	v_pk_fma_f32 v[102:103], v[102:103], v[134:135], v[104:105]
	v_pk_fma_f32 v[94:95], v[98:99], v[142:143], v[94:95]
	v_lshl_add_u64 v[96:97], v[96:97], 0, v[160:161]
	global_store_dwordx4 v[210:211], v[100:103], off offset:512
	global_store_dwordx4 v[96:97], v[92:95], off
	v_add_u32_e32 v98, 0x90, v164
	v_lshlrev_b32_e32 v100, 16, v192
	v_and_b32_e32 v101, 0xffff0000, v192
	v_lshlrev_b32_e32 v102, 16, v193
	v_and_b32_e32 v103, 0xffff0000, v193
	v_lshlrev_b32_e32 v92, 16, v196
	v_and_b32_e32 v93, 0xffff0000, v196
	v_lshlrev_b32_e32 v94, 16, v197
	v_and_b32_e32 v95, 0xffff0000, v197
	v_pk_fma_f32 v[88:89], v[88:89], v[136:137], v[100:101]
	v_pk_fma_f32 v[90:91], v[90:91], v[138:139], v[102:103]
	v_pk_fma_f32 v[76:77], v[76:77], v[128:129], v[92:93]
; __device__ __forceinline__ float bflo(unsigned w) { return __uint_as_float(w << 16); }
; __device__ __forceinline__ float bfhi(unsigned w) { return __uint_as_float(w & 0xffff0000u); }
;     __device__ __forceinline__ void operator()(f32x4 (&acc)[2][2][4][2], const Unit& u, int wr, int wc, int fr, int fq, LAS unsigned char* lds) const {
;     ...
;         for (int ai = 0; ai < 2; ++ai) {
;             u32x4 xw[4][2];
; #pragma unroll
;             for (int m = 0; m < 4; ++m) {
;                 const size_t off = (size_t)(row0 + ai * HALF + m * 16) * 1024 + col0;
; #pragma unroll
;                 for (int bj = 0; bj < 2; ++bj) xw[m][bj] = *(const u32x4*)(base + off + bj * HALF);
;             }
; #pragma unroll
;             for (int m = 0; m < 4; ++m) {
;                 const size_t off = (size_t)(row0 + ai * HALF + m * 16) * 1024 + col0;
; #pragma unroll
;                 for (int bj = 0; bj < 2; ++bj) {
;                     const u32x4 w = xw[m][bj];
;                     const f32x4 x0 = (f32x4){bflo(w.x), bfhi(w.x), bflo(w.y), bfhi(w.y)}, x1 = (f32x4){bflo(w.z), bfhi(w.z), bflo(w.w), bfhi(w.w)};
;                     *(f32x4*)(out + off + bj * HALF) = x0 + gv[bj][0] * acc[ai][bj][m][0];
;                     *(f32x4*)(out + off + bj * HALF + 4) = x1 + gv[bj][1] * acc[ai][bj][m][1];
;                 }
;             }
;             asm volatile("" ::: "memory");
	v_pk_fma_f32 v[78:79], v[78:79], v[130:131], v[94:95]
	global_store_dwordx4 v[96:97], v[88:91], off offset:16
	global_store_dwordx4 v[96:97], v[76:79], off offset:528
	v_ashrrev_i32_e32 v99, 31, v98
	v_lshlrev_b32_e32 v88, 16, v194
	v_and_b32_e32 v89, 0xffff0000, v194
	v_lshlrev_b32_e32 v90, 16, v195
	v_and_b32_e32 v91, 0xffff0000, v195
	v_lshlrev_b32_e32 v76, 16, v198
	v_and_b32_e32 v77, 0xffff0000, v198
	v_pk_fma_f32 v[84:85], v[84:85], v[132:133], v[88:89]
	v_pk_fma_f32 v[86:87], v[86:87], v[134:135], v[90:91]
	v_pk_fma_f32 v[76:77], v[80:81], v[140:141], v[76:77]
	v_lshlrev_b64 v[80:81], 12, v[166:167]
	global_store_dwordx4 v[96:97], v[84:87], off offset:512
	v_lshlrev_b32_e32 v78, 16, v199
	v_and_b32_e32 v79, 0xffff0000, v199
	v_lshlrev_b32_e32 v84, 16, v200
	v_and_b32_e32 v85, 0xffff0000, v200
	v_lshlrev_b32_e32 v86, 16, v201
	v_and_b32_e32 v87, 0xffff0000, v201
	v_lshl_add_u64 v[80:81], s[76:77], 0, v[80:81]
	v_pk_fma_f32 v[78:79], v[82:83], v[142:143], v[78:79]
	v_lshl_add_u64 v[80:81], v[80:81], 0, v[160:161]
	v_pk_fma_f32 v[72:73], v[72:73], v[136:137], v[84:85]
	v_pk_fma_f32 v[74:75], v[74:75], v[138:139], v[86:87]
	global_store_dwordx4 v[80:81], v[76:79], off
	global_store_dwordx4 v[80:81], v[72:75], off offset:16
	v_add_u32_e32 v96, 0x80, v164
	v_lshlrev_b32_e32 v76, 16, v204
	v_lshlrev_b32_e32 v72, 16, v202
	v_and_b32_e32 v73, 0xffff0000, v202
	v_lshlrev_b32_e32 v74, 16, v203
	v_and_b32_e32 v75, 0xffff0000, v203
	v_and_b32_e32 v77, 0xffff0000, v204
	v_lshlrev_b32_e32 v78, 16, v205
	v_and_b32_e32 v79, 0xffff0000, v205
	v_pk_fma_f32 v[68:69], v[68:69], v[132:133], v[72:73]
	v_pk_fma_f32 v[70:71], v[70:71], v[134:135], v[74:75]
	v_pk_fma_f32 v[64:65], v[64:65], v[128:129], v[76:77]
	v_pk_fma_f32 v[66:67], v[66:67], v[130:131], v[78:79]
	v_ashrrev_i32_e32 v97, 31, v96
	global_store_dwordx4 v[80:81], v[68:71], off offset:512
	global_store_dwordx4 v[80:81], v[64:67], off offset:528
	v_add_u32_e32 v100, 0xa0, v164
	v_ashrrev_i32_e32 v101, 31, v100
	v_lshlrev_b64 v[64:65], 11, v[96:97]
	v_lshl_add_u64 v[64:65], v[162:163], 0, v[64:65]
	global_load_dwordx4 v[68:71], v[64:65], off nt
	global_load_dwordx4 v[72:75], v[64:65], off offset:256 nt
	v_lshlrev_b64 v[64:65], 11, v[98:99]
	v_lshl_add_u64 v[64:65], v[162:163], 0, v[64:65]
	global_load_dwordx4 v[76:79], v[64:65], off nt
	global_load_dwordx4 v[80:83], v[64:65], off offset:256 nt
	v_lshlrev_b64 v[64:65], 11, v[100:101]
	v_lshl_add_u64 v[64:65], v[162:163], 0, v[64:65]
	global_load_dwordx4 v[84:87], v[64:65], off nt
	global_load_dwordx4 v[88:91], v[64:65], off offset:256 nt
	v_add_u32_e32 v102, 0xb0, v164
	v_ashrrev_i32_e32 v103, 31, v102
	v_lshlrev_b64 v[64:65], 11, v[102:103]
	v_lshl_add_u64 v[64:65], v[162:163], 0, v[64:65]
	global_load_dwordx4 v[92:95], v[64:65], off nt
	s_nop 0
	global_load_dwordx4 v[64:67], v[64:65], off offset:256 nt
	s_waitcnt vmcnt(7)
	v_lshlrev_b32_e32 v104, 16, v68
	v_and_b32_e32 v105, 0xffff0000, v68
	v_lshlrev_b32_e32 v68, 16, v69
	v_and_b32_e32 v69, 0xffff0000, v69
	v_pk_fma_f32 v[62:63], v[62:63], v[142:143], v[68:69]
	v_lshlrev_b64 v[68:69], 12, v[96:97]
	v_lshl_add_u64 v[68:69], s[76:77], 0, v[68:69]
	v_pk_fma_f32 v[60:61], v[60:61], v[140:141], v[104:105]
	v_lshl_add_u64 v[68:69], v[68:69], 0, v[160:161]
	global_store_dwordx4 v[68:69], v[60:63], off
	v_lshlrev_b32_e32 v106, 16, v70
	v_and_b32_e32 v107, 0xffff0000, v70
	s_waitcnt vmcnt(7)
	v_lshlrev_b32_e32 v60, 16, v74
	v_and_b32_e32 v61, 0xffff0000, v74
	v_lshlrev_b32_e32 v62, 16, v75
	v_and_b32_e32 v63, 0xffff0000, v75
	v_pk_fma_f32 v[46:47], v[46:47], v[130:131], v[62:63]
	v_pk_fma_f32 v[44:45], v[44:45], v[128:129], v[60:61]
	global_store_dwordx4 v[68:69], v[44:47], off offset:528
	v_lshlrev_b32_e32 v70, 16, v71
	v_and_b32_e32 v71, 0xffff0000, v71
	s_waitcnt vmcnt(7)
	v_lshlrev_b32_e32 v44, 16, v76
	v_and_b32_e32 v45, 0xffff0000, v76
	v_pk_fma_f32 v[44:45], v[48:49], v[140:141], v[44:45]
	v_lshlrev_b64 v[48:49], 12, v[98:99]
	v_lshlrev_b32_e32 v46, 16, v77
	v_and_b32_e32 v47, 0xffff0000, v77
	v_lshl_add_u64 v[48:49], s[76:77], 0, v[48:49]
	v_pk_fma_f32 v[58:59], v[58:59], v[138:139], v[70:71]
	v_pk_fma_f32 v[56:57], v[56:57], v[136:137], v[106:107]
	v_pk_fma_f32 v[46:47], v[50:51], v[142:143], v[46:47]
	v_lshl_add_u64 v[48:49], v[48:49], 0, v[160:161]
	global_store_dwordx4 v[68:69], v[56:59], off offset:16
	global_store_dwordx4 v[48:49], v[44:47], off
	s_nop 0
	v_lshlrev_b32_e32 v56, 16, v72
	v_and_b32_e32 v57, 0xffff0000, v72
	v_lshlrev_b32_e32 v58, 16, v73
	v_and_b32_e32 v59, 0xffff0000, v73
	s_waitcnt vmcnt(8)
; __device__ __forceinline__ float bflo(unsigned w) { return __uint_as_float(w << 16); }
; __device__ __forceinline__ float bfhi(unsigned w) { return __uint_as_float(w & 0xffff0000u); }
; #define PG8_BAR __builtin_amdgcn_s_barrier()
; template <class Epi, bool ALIGN_EPI = true, bool SP2 = true>
; __device__ __forceinline__ void gemm_phase(LAS unsigned char* lds, const Gemm g, const StaticOrder& S, const Epi& E) {
;     ...
;         cur = nxt; cB = nB; ++ui;
;         if constexpr (ALIGN_EPI) { if (wr == 1) PG8_BAR; }
;     __device__ __forceinline__ void operator()(f32x4 (&acc)[2][2][4][2], const Unit& u, int wr, int wc, int fr, int fq, LAS unsigned char* lds) const {
;     ...
;             for (int m = 0; m < 4; ++m) {
;                 const size_t off = (size_t)(row0 + ai * HALF + m * 16) * 1024 + col0;
; #pragma unroll
;                 for (int bj = 0; bj < 2; ++bj) {
;                     const u32x4 w = xw[m][bj];
;                     const f32x4 x0 = (f32x4){bflo(w.x), bfhi(w.x), bflo(w.y), bfhi(w.y)}, x1 = (f32x4){bflo(w.z), bfhi(w.z), bflo(w.w), bfhi(w.w)};
;                     *(f32x4*)(out + off + bj * HALF) = x0 + gv[bj][0] * acc[ai][bj][m][0];
;                     *(f32x4*)(out + off + bj * HALF + 4) = x1 + gv[bj][1] * acc[ai][bj][m][1];
;                 }
;             }
;             asm volatile("" ::: "memory");
	v_lshlrev_b32_e32 v44, 16, v82
	v_and_b32_e32 v45, 0xffff0000, v82
	v_lshlrev_b32_e32 v46, 16, v83
	v_and_b32_e32 v47, 0xffff0000, v83
	v_pk_fma_f32 v[54:55], v[54:55], v[134:135], v[58:59]
	v_pk_fma_f32 v[52:53], v[52:53], v[132:133], v[56:57]
	v_pk_fma_f32 v[30:31], v[30:31], v[130:131], v[46:47]
	v_pk_fma_f32 v[28:29], v[28:29], v[128:129], v[44:45]
	global_store_dwordx4 v[68:69], v[52:55], off offset:512
	global_store_dwordx4 v[48:49], v[28:31], off offset:528
	s_nop 0
	v_lshlrev_b32_e32 v52, 16, v78
	v_and_b32_e32 v53, 0xffff0000, v78
	v_lshlrev_b32_e32 v54, 16, v79
	v_and_b32_e32 v55, 0xffff0000, v79
	s_waitcnt vmcnt(9)
	v_lshlrev_b32_e32 v28, 16, v84
	v_and_b32_e32 v29, 0xffff0000, v84
	v_pk_fma_f32 v[42:43], v[42:43], v[138:139], v[54:55]
	v_pk_fma_f32 v[40:41], v[40:41], v[136:137], v[52:53]
	v_pk_fma_f32 v[28:29], v[32:33], v[140:141], v[28:29]
	v_lshlrev_b64 v[32:33], 12, v[100:101]
	global_store_dwordx4 v[48:49], v[40:43], off offset:16
	v_lshlrev_b32_e32 v30, 16, v85
	v_and_b32_e32 v31, 0xffff0000, v85
	v_lshlrev_b32_e32 v40, 16, v80
	v_and_b32_e32 v41, 0xffff0000, v80
	v_lshlrev_b32_e32 v42, 16, v81
	v_and_b32_e32 v43, 0xffff0000, v81
	v_lshl_add_u64 v[32:33], s[76:77], 0, v[32:33]
	v_pk_fma_f32 v[38:39], v[38:39], v[134:135], v[42:43]
	v_pk_fma_f32 v[36:37], v[36:37], v[132:133], v[40:41]
	v_pk_fma_f32 v[30:31], v[34:35], v[142:143], v[30:31]
	v_lshl_add_u64 v[32:33], v[32:33], 0, v[160:161]
	global_store_dwordx4 v[48:49], v[36:39], off offset:512
	global_store_dwordx4 v[32:33], v[28:31], off
	s_nop 0
	v_lshlrev_b32_e32 v36, 16, v86
	v_and_b32_e32 v37, 0xffff0000, v86
	v_lshlrev_b32_e32 v38, 16, v87
	v_and_b32_e32 v39, 0xffff0000, v87
	s_waitcnt vmcnt(11)
	v_lshlrev_b32_e32 v28, 16, v90
	v_and_b32_e32 v29, 0xffff0000, v90
	v_lshlrev_b32_e32 v30, 16, v91
	v_and_b32_e32 v31, 0xffff0000, v91
	v_pk_fma_f32 v[26:27], v[26:27], v[138:139], v[38:39]
	v_pk_fma_f32 v[24:25], v[24:25], v[136:137], v[36:37]
	v_pk_fma_f32 v[14:15], v[14:15], v[130:131], v[30:31]
	v_pk_fma_f32 v[12:13], v[12:13], v[128:129], v[28:29]
	global_store_dwordx4 v[32:33], v[24:27], off offset:16
	global_store_dwordx4 v[32:33], v[12:15], off offset:528
	s_nop 0
	v_lshlrev_b32_e32 v24, 16, v88
	v_and_b32_e32 v25, 0xffff0000, v88
	v_lshlrev_b32_e32 v26, 16, v89
	v_and_b32_e32 v27, 0xffff0000, v89
	s_waitcnt vmcnt(12)
	v_lshlrev_b32_e32 v12, 16, v92
	v_and_b32_e32 v13, 0xffff0000, v92
	v_pk_fma_f32 v[22:23], v[22:23], v[134:135], v[26:27]
	v_pk_fma_f32 v[20:21], v[20:21], v[132:133], v[24:25]
	v_pk_fma_f32 v[12:13], v[16:17], v[140:141], v[12:13]
	v_lshlrev_b64 v[16:17], 12, v[102:103]
	global_store_dwordx4 v[32:33], v[20:23], off offset:512
	v_lshlrev_b32_e32 v14, 16, v93
	v_and_b32_e32 v15, 0xffff0000, v93
	v_lshlrev_b32_e32 v20, 16, v94
	v_and_b32_e32 v21, 0xffff0000, v94
	v_lshlrev_b32_e32 v22, 16, v95
	v_and_b32_e32 v23, 0xffff0000, v95
	v_lshl_add_u64 v[16:17], s[76:77], 0, v[16:17]
	v_pk_fma_f32 v[14:15], v[18:19], v[142:143], v[14:15]
	v_lshl_add_u64 v[16:17], v[16:17], 0, v[160:161]
	v_pk_fma_f32 v[10:11], v[10:11], v[138:139], v[22:23]
	v_pk_fma_f32 v[8:9], v[8:9], v[136:137], v[20:21]
	global_store_dwordx4 v[16:17], v[12:15], off
	global_store_dwordx4 v[16:17], v[8:11], off offset:16
	s_waitcnt vmcnt(14)
	v_lshlrev_b32_e32 v12, 16, v66
	v_lshlrev_b32_e32 v8, 16, v64
	v_and_b32_e32 v9, 0xffff0000, v64
	v_lshlrev_b32_e32 v10, 16, v65
	v_and_b32_e32 v11, 0xffff0000, v65
	v_and_b32_e32 v13, 0xffff0000, v66
	v_lshlrev_b32_e32 v14, 16, v67
	v_and_b32_e32 v15, 0xffff0000, v67
	v_pk_fma_f32 v[6:7], v[6:7], v[134:135], v[10:11]
	v_pk_fma_f32 v[4:5], v[4:5], v[132:133], v[8:9]
	v_pk_fma_f32 v[2:3], v[2:3], v[130:131], v[14:15]
	v_pk_fma_f32 v[0:1], v[0:1], v[128:129], v[12:13]
	global_store_dwordx4 v[16:17], v[4:7], off offset:512
	global_store_dwordx4 v[16:17], v[0:3], off offset:528
	s_cbranch_vccnz .LBB0_1226
	s_andn2_b64 vcc, exec, s[6:7]
	s_cbranch_vccnz .LBB0_1225
	s_barrier
	s_branch .LBB0_1225
